# loader role: no VALU (saddr DMA, precomputed LDS bases), counted lgkmcnt between fragment read groups; FFN2-up conversion fully beside w_in GEMM
# speedup vs baseline: 1.0121x; 1.0040x over previous
; #define LAS __attribute__((address_space(3)))
;     LAS float* scr = (LAS float*)(F.lds + RING_OFF + F.wave * 16384);
;     const int nblk = nbn ? nbn : N / 32, nall = (K / 64) * nblk, nitems = (int)((long)nall * f1 / 16);
;     int it = (int)((long)nall * f0 / 16) + w0; if (it >= nitems) return;
;     f32x4 va[8], vb[8], vc[8];
;     __builtin_amdgcn_s_waitcnt(0x0F70);
;     const int last = nitems - 1, ntri = ((nitems - it + nw - 1) / nw + 2) / 3;
;     int i1 = min(it + nw, last);
;     p0_item_load(W, N, nblk, nb0, it, F.lane, va);
;     p0_item_load(W, N, nblk, nb0, i1, F.lane, vb); __builtin_amdgcn_sched_barrier(0);
; __device__ __forceinline__ void p0_prologue(Frame& F, const Args& A) {
;     ...
;     p0_transpose(F, A.in[26], D, DFF, (bf16*)(F.ws + WS_WGU2), 2, F.gw, F.ngw, UP2_SPLIT, 16);
.LBB0_26:
	s_cmpk_gt_i32 s88, 0x157f
	s_branch .LBB0_30
	s_add_i32 s17, s88, 0x4080
	s_load_dwordx8 s[20:27], s[0:1], 0xc0
	s_add_i32 s2, s17, s90
	s_min_i32 s3, s2, 0x55ff
	s_mul_hi_i32 s2, s17, 0x2fa0be83
	s_lshr_b32 s4, s2, 31
	s_ashr_i32 s2, s2, 6
	s_add_i32 s2, s2, s4
	s_mul_i32 s4, s2, 0x158
	s_waitcnt vmcnt(15)
	v_lshl_or_b32 v4, s2, 6, v1
	s_mov_b32 s6, 0xac00
	s_waitcnt lgkmcnt(0)
	v_mov_b64_e32 v[2:3], s[24:25]
	s_sub_i32 s7, s17, s4
	v_mad_i64_i32 v[4:5], s[4:5], v4, s6, v[2:3]
	s_lshl_b32 s4, s7, 5
	s_ashr_i32 s5, s4, 31
	s_mul_hi_i32 s2, s3, 0x2fa0be83
	v_lshl_add_u64 v[4:5], s[4:5], 2, v[4:5]
	s_lshr_b32 s4, s2, 31
	s_ashr_i32 s2, s2, 6
	v_mov_b32_e32 v99, 0
	s_add_i32 s2, s2, s4
	s_waitcnt vmcnt(8)
	v_lshl_add_u64 v[18:19], v[4:5], 0, v[98:99]
	s_mul_i32 s4, s2, 0x158
	v_lshl_or_b32 v4, s2, 6, v1
	s_sub_i32 s7, s3, s4
	v_mad_i64_i32 v[2:3], s[4:5], v4, s6, v[2:3]
	s_lshl_b32 s4, s7, 5
	s_ashr_i32 s5, s4, 31
	v_lshl_add_u64 v[2:3], s[4:5], 2, v[2:3]
	s_mov_b32 s7, 0x56000
	s_waitcnt vmcnt(1)
	v_lshl_add_u64 v[58:59], v[2:3], 0, v[98:99]
	v_add_co_u32_e32 v2, vcc, s7, v18
	s_mov_b32 s8, 0xac000
	s_nop 0
	v_addc_co_u32_e32 v3, vcc, 0, v19, vcc
	v_add_co_u32_e32 v6, vcc, s8, v18
	s_mov_b32 s9, 0x102000
	s_nop 0
	v_addc_co_u32_e32 v7, vcc, 0, v19, vcc
	v_add_co_u32_e32 v10, vcc, s9, v18
	s_mov_b32 s10, 0x158000
	s_nop 0
	v_addc_co_u32_e32 v11, vcc, 0, v19, vcc
	v_add_co_u32_e32 v14, vcc, s10, v18
	s_mov_b32 s11, 0x1ae000
	s_nop 0
	v_addc_co_u32_e32 v15, vcc, 0, v19, vcc
	v_add_co_u32_e32 v20, vcc, s11, v18
	s_mov_b32 s13, 0x204000
	s_nop 0
	v_addc_co_u32_e32 v21, vcc, 0, v19, vcc
	v_add_co_u32_e32 v22, vcc, s13, v18
	s_mov_b32 s14, 0x25a000
	s_nop 0
	v_addc_co_u32_e32 v23, vcc, 0, v19, vcc
	s_waitcnt vmcnt(0)
	global_load_dwordx4 v[2:5], v[2:3], off nt
	s_nop 0
	global_load_dwordx4 v[6:9], v[6:7], off nt
	s_nop 0
	global_load_dwordx4 v[10:13], v[10:11], off nt
	s_nop 0
	global_load_dwordx4 v[14:17], v[14:15], off nt
	s_nop 0
	global_load_dwordx4 v[26:29], v[20:21], off nt
	global_load_dwordx4 v[34:37], v[22:23], off nt
	v_add_co_u32_e32 v22, vcc, s14, v18
	s_abs_i32 s2, s90
	s_nop 0
	v_addc_co_u32_e32 v23, vcc, 0, v19, vcc
	v_add_co_u32_e32 v24, vcc, s7, v58
	global_load_dwordx4 v[30:33], v[18:19], off nt
	s_nop 0
	global_load_dwordx4 v[18:21], v[58:59], off nt
	v_addc_co_u32_e32 v25, vcc, 0, v59, vcc
	v_add_co_u32_e32 v38, vcc, s8, v58
	global_load_dwordx4 v[42:45], v[22:23], off nt
	s_nop 0
	global_load_dwordx4 v[22:25], v[24:25], off nt
	v_addc_co_u32_e32 v39, vcc, 0, v59, vcc
	v_add_co_u32_e32 v46, vcc, s9, v58
	v_cvt_f32_u32_e32 v66, s2
	s_nop 0
	v_addc_co_u32_e32 v47, vcc, 0, v59, vcc
	v_add_co_u32_e32 v50, vcc, s10, v58
	global_load_dwordx4 v[38:41], v[38:39], off nt
	s_nop 0
	global_load_dwordx4 v[46:49], v[46:47], off nt
	v_addc_co_u32_e32 v51, vcc, 0, v59, vcc
	v_add_co_u32_e32 v54, vcc, s11, v58
	v_rcp_iflag_f32_e32 v66, v66
	s_nop 0
	v_addc_co_u32_e32 v55, vcc, 0, v59, vcc
	v_add_co_u32_e32 v60, vcc, 0x204000, v58
	global_load_dwordx4 v[50:53], v[50:51], off nt
	s_nop 0
	global_load_dwordx4 v[54:57], v[54:55], off nt
	v_addc_co_u32_e32 v61, vcc, 0, v59, vcc
	v_add_co_u32_e32 v62, vcc, 0x25a000, v58
	v_mul_f32_e32 v66, 0x4f7ffffe, v66
	s_nop 0
	v_addc_co_u32_e32 v63, vcc, 0, v59, vcc
	global_load_dwordx4 v[58:61], v[60:61], off nt
	s_nop 0
	global_load_dwordx4 v[62:65], v[62:63], off nt
	v_cvt_u32_f32_e32 v66, v66
	s_add_i32 s4, s12, 0x157f
	s_sub_i32 s12, 0xffffea81, s12
	s_xor_b32 s5, s4, s90
	s_max_i32 s4, s4, s12
	s_sub_i32 s12, 0, s2
	v_readfirstlane_b32 s15, v66
	s_mul_i32 s12, s12, s15
	s_mul_hi_u32 s12, s15, s12
	s_add_i32 s15, s15, s12
	s_mul_hi_u32 s12, s4, s15
	s_mul_i32 s15, s12, s2
	s_sub_i32 s4, s4, s15
	s_ashr_i32 s5, s5, 31
	s_add_i32 s15, s12, 1
	s_sub_i32 s16, s4, s2
	s_cmp_ge_u32 s4, s2
	s_cselect_b32 s12, s15, s12
	s_cselect_b32 s4, s16, s4
	s_add_i32 s15, s12, 1
	s_cmp_ge_u32 s4, s2
	s_cselect_b32 s2, s15, s12
	s_xor_b32 s2, s2, s5
	s_sub_i32 s2, s2, s5
	s_cmp_lt_i32 s2, 1
	s_cbranch_scc1 .LBB0_30
	s_load_dwordx8 s[20:27], s[0:1], 0xc0
	v_lshlrev_b32_e32 v66, 1, v114
	v_mov_b32_e32 v67, v99
	s_add_i32 s2, s2, 2
	v_lshl_add_u64 v[66:67], s[96:97], 0, v[66:67]
	s_mov_b64 s[4:5], 0x1ce00000
	s_mul_hi_u32 s2, s2, 0xaaaaaaab
	v_lshl_add_u64 v[100:101], v[66:67], 0, s[4:5]
	s_lshr_b32 s12, s2, 1

; #define PG8_STAGE(bufoff, gbase, voff) do { _Pragma("unroll") for (int _i = 0; _i < 2; ++_i) \
;         __builtin_amdgcn_global_load_lds((const unsigned*)((const char*)(gbase) + (voff)[_i]), (PG8_LAS unsigned*)(lds + (bufoff) + ldsw + _i * 8192), 16, 0, 0); } while (0)
; #define PG8_WAIT_V(n) asm volatile("s_waitcnt vmcnt(" #n ")" ::: "memory")
; #define PG8_BAR __builtin_amdgcn_s_barrier()
; template <class Epi, class Sched, bool ALIGN_EPI = false, bool SP2 = true>
; __device__ __forceinline__ void gemm_phase(PG8_LAS unsigned char* lds, const Gemm g, const Sched& S, const Epi& E) {
;     ...
;     const unsigned ldsw = (unsigned)wid * 1024u;
;     const int aoff = lds_byte(wr * 64 + fr, fq * 8), boff = lds_byte(wc * 32 + fr, fq * 8);
;     ...
;         PG8_STAGE(PG8_SB(0, 0), cB, voffB); PG8_STAGE(PG8_SB(0, 1), cB + hstep, voffB); PG8_STAGE(PG8_SA(0, 0), cA, voffA); PG8_STAGE(PG8_SA(0, 1), cA + hstep, voffA);
;         if (wr == 1) PG8_BAR;
;         PG8_WAIT_V(2); PG8_BAR;
;         PG8_STAGE(PG8_SB(1, 0), cB + kstep, voffB); PG8_STAGE(PG8_SA(1, 0), cA + kstep, voffA); PG8_STAGE(PG8_SB(1, 1), cB + hstep + kstep, voffB);
;         PG8_WAIT_V(6); PG8_BAR;
.LBB0_135:
	s_lshl_b32 s4, s4, 5
	s_and_b32 s10, s4, 0x60
	s_lshl_b32 s3, s1, 13
	s_lshl_b32 s18, s10, 7
	s_cmp_gt_i32 s6, 63
	s_cselect_b64 s[4:5], -1, 0
	s_cmp_lt_i32 s6, 64
	s_cselect_b32 s53, 13, 12
	s_add_i32 s54, s44, 0x18000
	s_mov_b64 s[14:15], 0x80
	v_lshl_add_u64 v[10:11], v[10:11], 0, s[14:15]
	s_mov_b32 m0, s54
	s_add_i32 s55, s44, 0x1a000
	s_waitcnt vmcnt(2)
	s_barrier
	global_load_lds_dwordx4 v[10:11], off
	v_lshl_add_u64 v[8:9], v[8:9], 0, s[14:15]
	s_mov_b32 m0, s55
	s_add_i32 s56, s44, 0x8000
	s_add_i32 s57, s44, 0xa000
	global_load_lds_dwordx4 v[8:9], off
	v_lshl_add_u64 v[4:5], v[4:5], 0, s[14:15]
	s_mov_b32 m0, s56
	s_add_u32 s16, s34, 0x100080
	global_load_lds_dwordx4 v[4:5], off
	v_lshl_add_u64 v[4:5], v[6:7], 0, s[14:15]
	s_mov_b32 m0, s57
	s_addc_u32 s17, s35, 0
	s_add_i32 s58, s44, 0x1c000
	global_load_lds_dwordx4 v[4:5], off
	v_lshl_add_u64 v[4:5], s[16:17], 0, v[202:203]
	s_mov_b32 m0, s58
	s_add_i32 s59, s44, 0x1e000
	global_load_lds_dwordx4 v[4:5], off
	v_lshl_add_u64 v[4:5], s[16:17], 0, v[206:207]
	s_mov_b32 m0, s59
	s_movk_i32 s16, 0x3c0
	global_load_lds_dwordx4 v[4:5], off
	v_lshlrev_b32_e32 v4, 1, v3
	v_lshlrev_b32_e32 v5, 6, v0
	v_and_b32_e32 v7, 15, v0
	v_and_or_b32 v5, v5, s16, v4
	v_and_b32_e32 v6, 32, v1
	v_lshl_or_b32 v4, v7, 6, v4
	s_waitcnt vmcnt(6)
	v_bitop3_b32 v4, v4, s3, v6 bitop3:0xde
	v_bitop3_b32 v5, s18, v5, v6 bitop3:0xf6
	s_cmpk_lt_u32 s0, 0x100
	v_or_b32_e32 v216, s10, v3
	v_cndmask_b32_e64 v3, 0, 1, s[4:5]
	v_lshl_or_b32 v1, s1, 6, v7
	s_cselect_b64 s[16:17], -1, 0
	s_add_i32 s60, s6, 0xfffff8e0
	v_cmp_ne_u32_e64 s[0:1], 1, v3
	s_movk_i32 s61, 0x5600
	v_mov_b64_e32 v[208:209], 0xabf
	v_add_u32_e32 v217, 0, v5
	v_add_u32_e32 v237, 0x10000, v217
	v_add_u32_e32 v238, 0x14000, v217
	v_add_u32_e32 v218, 0, v4
	s_mov_b32 s10, 0
	s_mov_b32 s21, 0
	s_barrier
	s_branch .LBB0_138

; #define PG8_STAGE(bufoff, gbase, voff) do { _Pragma("unroll") for (int _i = 0; _i < 2; ++_i) \
;         __builtin_amdgcn_global_load_lds((const unsigned*)((const char*)(gbase) + (voff)[_i]), (PG8_LAS unsigned*)(lds + (bufoff) + ldsw + _i * 8192), 16, 0, 0); } while (0)
; #define PG8_LDA(dst, b, h) do { _Pragma("unroll") for (int m = 0; m < 4; ++m) _Pragma("unroll") for (int k = 0; k < 2; ++k) dst[m][k] = *(const PG8_LAS bf16x8*)(lds + PG8_SA(b, h) + aoff + m * 2048 + k * 1024); } while (0)
; #define PG8_LDB(dst, b, h) do { _Pragma("unroll") for (int n = 0; n < 2; ++n) _Pragma("unroll") for (int k = 0; k < 2; ++k) dst[n][k] = *(const PG8_LAS bf16x8*)(lds + PG8_SB(b, h) + boff + n * 2048 + k * 1024); } while (0)
; #define PG8_MMA(ai, bj, At, Bt) do { __builtin_amdgcn_s_setprio(1); _Pragma("unroll") for (int m = 0; m < 4; ++m) _Pragma("unroll") for (int n = 0; n < 2; ++n) _Pragma("unroll") for (int k = 0; k < 2; ++k) \
;         acc[ai][bj][m][n] = __builtin_amdgcn_mfma_f32_16x16x32_bf16(Bt[n][k], At[m][k], acc[ai][bj][m][n], 0, 0, 0); __builtin_amdgcn_s_setprio(0); } while (0)
; #define PG8_WAIT_V(n) asm volatile("s_waitcnt vmcnt(" #n ")" ::: "memory")
; #define PG8_WAIT_L(n) asm volatile("s_waitcnt lgkmcnt(" #n ")" ::: "memory")
; #define PG8_BAR __builtin_amdgcn_s_barrier()
; #define PG8_SCHED __builtin_amdgcn_sched_barrier(0)
; template <class Epi, class Sched, bool ALIGN_EPI = false, bool SP2 = true>
; __device__ __forceinline__ void gemm_phase(PG8_LAS unsigned char* lds, const Gemm g, const Sched& S, const Epi& E) {
;     ...
;             PG8_LDB(B0, 0, 0); PG8_LDB(B1, 0, 1); PG8_SCHED; PG8_LDA(At, 0, 0); PG8_STAGE(PG8_SA(1, 1), a1 + hstep, voffA);
;             PG8_WAIT_V(8); PG8_WAIT_L(0); PG8_BAR; PG8_MMA(0, 0, At, B0); PG8_MMA(0, 1, At, B1); PG8_BAR; PG8_SCHED;
;             if (full) { PG8_LDA(At, 0, 1); } PG8_STAGE(PG8_SB(0, 0), b2, voffB); PG8_STAGE(PG8_SB(0, 1), b2 + hstep, voffB); PG8_STAGE(PG8_SA(0, 0), a2, voffA);
;             PG8_WAIT_V(8); PG8_WAIT_L(0); PG8_BAR; if (full) { PG8_MMA(1, 0, At, B0); PG8_MMA(1, 1, At, B1); } PG8_BAR; PG8_SCHED;
.LBB0_152:
	ds_read_b128 v[150:153], v237
	ds_read_b128 v[154:157], v237 offset:1024
	ds_read_b128 v[158:161], v237 offset:2048
	ds_read_b128 v[162:165], v237 offset:3072
	ds_read_b128 v[134:137], v238
	ds_read_b128 v[138:141], v238 offset:1024
	ds_read_b128 v[142:145], v238 offset:2048
	ds_read_b128 v[146:149], v238 offset:3072
	s_or_b32 s10, s66, 1
	s_lshl_b64 s[4:5], s[10:11], 7
	s_add_u32 s4, s30, s4
	s_addc_u32 s5, s31, s5
	s_add_u32 s4, s4, 0x100000
	s_addc_u32 s5, s5, 0
	s_add_i32 m0, s44, 0xc000
	s_waitcnt lgkmcnt(7)
	ds_read_b128 v[178:181], v218
	ds_read_b128 v[194:197], v218 offset:1024
	ds_read_b128 v[174:177], v218 offset:2048
	ds_read_b128 v[190:193], v218 offset:3072
	ds_read_b128 v[170:173], v218 offset:4096
	ds_read_b128 v[186:189], v218 offset:5120
	ds_read_b128 v[166:169], v218 offset:6144
	ds_read_b128 v[182:185], v218 offset:7168
	global_load_lds_dwordx4 v200, s[4:5]
	s_add_i32 m0, s44, 0xe000
	s_nop 0
	global_load_lds_dwordx4 v204, s[4:5]
	s_waitcnt vmcnt(8)
	s_waitcnt lgkmcnt(0)
	s_setprio 1
	s_barrier
	v_mfma_f32_16x16x32_bf16 v[130:133], v[150:153], v[178:181], v[130:133]
	v_mfma_f32_16x16x32_bf16 v[122:125], v[158:161], v[178:181], v[122:125]
	v_mfma_f32_16x16x32_bf16 v[114:117], v[150:153], v[174:177], v[114:117]
	v_mfma_f32_16x16x32_bf16 v[106:109], v[158:161], v[174:177], v[106:109]
	v_mfma_f32_16x16x32_bf16 v[98:101], v[150:153], v[170:173], v[98:101]
	v_mfma_f32_16x16x32_bf16 v[90:93], v[158:161], v[170:173], v[90:93]
	v_mfma_f32_16x16x32_bf16 v[82:85], v[150:153], v[166:169], v[82:85]
	v_mfma_f32_16x16x32_bf16 v[74:77], v[158:161], v[166:169], v[74:77]
	v_mfma_f32_16x16x32_bf16 v[130:133], v[154:157], v[194:197], v[130:133]
	v_mfma_f32_16x16x32_bf16 v[122:125], v[162:165], v[194:197], v[122:125]
	v_mfma_f32_16x16x32_bf16 v[114:117], v[154:157], v[190:193], v[114:117]
	v_mfma_f32_16x16x32_bf16 v[106:109], v[162:165], v[190:193], v[106:109]
	v_mfma_f32_16x16x32_bf16 v[98:101], v[154:157], v[186:189], v[98:101]
	v_mfma_f32_16x16x32_bf16 v[90:93], v[162:165], v[186:189], v[90:93]
	v_mfma_f32_16x16x32_bf16 v[82:85], v[154:157], v[182:185], v[82:85]
	v_mfma_f32_16x16x32_bf16 v[74:77], v[162:165], v[182:185], v[74:77]
	v_mfma_f32_16x16x32_bf16 v[126:129], v[134:137], v[178:181], v[126:129]
	v_mfma_f32_16x16x32_bf16 v[118:121], v[142:145], v[178:181], v[118:121]
	v_mfma_f32_16x16x32_bf16 v[110:113], v[134:137], v[174:177], v[110:113]
	v_mfma_f32_16x16x32_bf16 v[102:105], v[142:145], v[174:177], v[102:105]
	v_mfma_f32_16x16x32_bf16 v[94:97], v[134:137], v[170:173], v[94:97]
	v_mfma_f32_16x16x32_bf16 v[86:89], v[142:145], v[170:173], v[86:89]
	v_mfma_f32_16x16x32_bf16 v[78:81], v[134:137], v[166:169], v[78:81]
	v_mfma_f32_16x16x32_bf16 v[70:73], v[142:145], v[166:169], v[70:73]
	v_mfma_f32_16x16x32_bf16 v[126:129], v[138:141], v[194:197], v[126:129]
	v_mfma_f32_16x16x32_bf16 v[118:121], v[146:149], v[194:197], v[118:121]
	v_mfma_f32_16x16x32_bf16 v[110:113], v[138:141], v[190:193], v[110:113]
	v_mfma_f32_16x16x32_bf16 v[102:105], v[146:149], v[190:193], v[102:105]
	v_mfma_f32_16x16x32_bf16 v[94:97], v[138:141], v[186:189], v[94:97]
	v_mfma_f32_16x16x32_bf16 v[86:89], v[146:149], v[186:189], v[86:89]
	v_mfma_f32_16x16x32_bf16 v[78:81], v[138:141], v[182:185], v[78:81]
	v_mfma_f32_16x16x32_bf16 v[70:73], v[146:149], v[182:185], v[70:73]
	s_barrier
	s_setprio 0
	s_andn2_b64 s[4:5], exec, s[36:37]
	s_andn2_b64 vcc, exec, s[36:37]
	s_cbranch_vccnz .LBB0_154
	ds_read_b128 v[178:181], v218 offset:16384
	ds_read_b128 v[194:197], v218 offset:17408
	ds_read_b128 v[174:177], v218 offset:18432
	ds_read_b128 v[190:193], v218 offset:19456
	ds_read_b128 v[170:173], v218 offset:20480
	ds_read_b128 v[186:189], v218 offset:21504
	ds_read_b128 v[166:169], v218 offset:22528
	ds_read_b128 v[182:185], v218 offset:23552

; #define PG8_STAGE(bufoff, gbase, voff) do { _Pragma("unroll") for (int _i = 0; _i < 2; ++_i) \
;         __builtin_amdgcn_global_load_lds((const unsigned*)((const char*)(gbase) + (voff)[_i]), (PG8_LAS unsigned*)(lds + (bufoff) + ldsw + _i * 8192), 16, 0, 0); } while (0)
; #define PG8_LDA(dst, b, h) do { _Pragma("unroll") for (int m = 0; m < 4; ++m) _Pragma("unroll") for (int k = 0; k < 2; ++k) dst[m][k] = *(const PG8_LAS bf16x8*)(lds + PG8_SA(b, h) + aoff + m * 2048 + k * 1024); } while (0)
; #define PG8_LDB(dst, b, h) do { _Pragma("unroll") for (int n = 0; n < 2; ++n) _Pragma("unroll") for (int k = 0; k < 2; ++k) dst[n][k] = *(const PG8_LAS bf16x8*)(lds + PG8_SB(b, h) + boff + n * 2048 + k * 1024); } while (0)
; #define PG8_MMA(ai, bj, At, Bt) do { __builtin_amdgcn_s_setprio(1); _Pragma("unroll") for (int m = 0; m < 4; ++m) _Pragma("unroll") for (int n = 0; n < 2; ++n) _Pragma("unroll") for (int k = 0; k < 2; ++k) \
;         acc[ai][bj][m][n] = __builtin_amdgcn_mfma_f32_16x16x32_bf16(Bt[n][k], At[m][k], acc[ai][bj][m][n], 0, 0, 0); __builtin_amdgcn_s_setprio(0); } while (0)
; #define PG8_WAIT_V(n) asm volatile("s_waitcnt vmcnt(" #n ")" ::: "memory")
; #define PG8_WAIT_L(n) asm volatile("s_waitcnt lgkmcnt(" #n ")" ::: "memory")
; #define PG8_BAR __builtin_amdgcn_s_barrier()
; #define PG8_SCHED __builtin_amdgcn_sched_barrier(0)
; template <class Epi, class Sched, bool ALIGN_EPI = false, bool SP2 = true>
; __device__ __forceinline__ void gemm_phase(PG8_LAS unsigned char* lds, const Gemm g, const Sched& S, const Epi& E) {
;     ...
;             PG8_LDB(B0, 1, 0); PG8_LDB(B1, 1, 1); PG8_SCHED; PG8_LDA(At, 1, 0); PG8_STAGE(PG8_SA(0, 1), a2 + hstep, voffA);
;             PG8_WAIT_V(8); PG8_WAIT_L(0); PG8_BAR; PG8_MMA(0, 0, At, B0); PG8_MMA(0, 1, At, B1); PG8_BAR; PG8_SCHED;
;             if (full) { PG8_LDA(At, 1, 1); } PG8_STAGE(PG8_SB(1, 0), b3, voffB); PG8_STAGE(PG8_SB(1, 1), b3 + hstep, voffB); PG8_STAGE(PG8_SA(1, 0), a3, voffA);
;             PG8_WAIT_V(8); PG8_WAIT_L(0); PG8_BAR; if (full) { PG8_MMA(1, 0, At, B0); PG8_MMA(1, 1, At, B1); } PG8_BAR; PG8_SCHED;
.LBB0_156:
	s_barrier
	s_setprio 0
	ds_read_b128 v[150:153], v237 offset:32768
	ds_read_b128 v[154:157], v237 offset:33792
	ds_read_b128 v[158:161], v237 offset:34816
	ds_read_b128 v[162:165], v237 offset:35840
	ds_read_b128 v[134:137], v238 offset:32768
	ds_read_b128 v[138:141], v238 offset:33792
	ds_read_b128 v[142:145], v238 offset:34816
	ds_read_b128 v[146:149], v238 offset:35840
	s_add_u32 s40, s40, 0x100000
	s_addc_u32 s41, s41, 0
	s_mov_b32 m0, s51
	s_waitcnt lgkmcnt(7)
	ds_read_b128 v[178:181], v218 offset:32768
	ds_read_b128 v[194:197], v218 offset:33792
	ds_read_b128 v[174:177], v218 offset:34816
	ds_read_b128 v[190:193], v218 offset:35840
	ds_read_b128 v[170:173], v218 offset:36864
	ds_read_b128 v[186:189], v218 offset:37888
	ds_read_b128 v[166:169], v218 offset:38912
	ds_read_b128 v[182:185], v218 offset:39936
	global_load_lds_dwordx4 v200, s[40:41]
	s_mov_b32 m0, s52
	s_nop 0
	global_load_lds_dwordx4 v204, s[40:41]
	s_waitcnt vmcnt(8)
	s_waitcnt lgkmcnt(0)
	s_setprio 1
	s_barrier
	v_mfma_f32_16x16x32_bf16 v[130:133], v[150:153], v[178:181], v[130:133]
	v_mfma_f32_16x16x32_bf16 v[122:125], v[158:161], v[178:181], v[122:125]
	v_mfma_f32_16x16x32_bf16 v[114:117], v[150:153], v[174:177], v[114:117]
	v_mfma_f32_16x16x32_bf16 v[106:109], v[158:161], v[174:177], v[106:109]
	v_mfma_f32_16x16x32_bf16 v[98:101], v[150:153], v[170:173], v[98:101]
	v_mfma_f32_16x16x32_bf16 v[90:93], v[158:161], v[170:173], v[90:93]
	v_mfma_f32_16x16x32_bf16 v[82:85], v[150:153], v[166:169], v[82:85]
	v_mfma_f32_16x16x32_bf16 v[74:77], v[158:161], v[166:169], v[74:77]
	v_mfma_f32_16x16x32_bf16 v[130:133], v[154:157], v[194:197], v[130:133]
	v_mfma_f32_16x16x32_bf16 v[122:125], v[162:165], v[194:197], v[122:125]
	v_mfma_f32_16x16x32_bf16 v[114:117], v[154:157], v[190:193], v[114:117]
	v_mfma_f32_16x16x32_bf16 v[106:109], v[162:165], v[190:193], v[106:109]
	v_mfma_f32_16x16x32_bf16 v[98:101], v[154:157], v[186:189], v[98:101]
	v_mfma_f32_16x16x32_bf16 v[90:93], v[162:165], v[186:189], v[90:93]
	v_mfma_f32_16x16x32_bf16 v[82:85], v[154:157], v[182:185], v[82:85]
	v_mfma_f32_16x16x32_bf16 v[74:77], v[162:165], v[182:185], v[74:77]
	v_mfma_f32_16x16x32_bf16 v[126:129], v[134:137], v[178:181], v[126:129]
	v_mfma_f32_16x16x32_bf16 v[118:121], v[142:145], v[178:181], v[118:121]
	v_mfma_f32_16x16x32_bf16 v[110:113], v[134:137], v[174:177], v[110:113]
	v_mfma_f32_16x16x32_bf16 v[102:105], v[142:145], v[174:177], v[102:105]
	v_mfma_f32_16x16x32_bf16 v[94:97], v[134:137], v[170:173], v[94:97]
	v_mfma_f32_16x16x32_bf16 v[86:89], v[142:145], v[170:173], v[86:89]
	v_mfma_f32_16x16x32_bf16 v[78:81], v[134:137], v[166:169], v[78:81]
	v_mfma_f32_16x16x32_bf16 v[70:73], v[142:145], v[166:169], v[70:73]
	v_mfma_f32_16x16x32_bf16 v[126:129], v[138:141], v[194:197], v[126:129]
	v_mfma_f32_16x16x32_bf16 v[118:121], v[146:149], v[194:197], v[118:121]
	v_mfma_f32_16x16x32_bf16 v[110:113], v[138:141], v[190:193], v[110:113]
	v_mfma_f32_16x16x32_bf16 v[102:105], v[146:149], v[190:193], v[102:105]
	v_mfma_f32_16x16x32_bf16 v[94:97], v[138:141], v[186:189], v[94:97]
	v_mfma_f32_16x16x32_bf16 v[86:89], v[146:149], v[186:189], v[86:89]
	v_mfma_f32_16x16x32_bf16 v[78:81], v[138:141], v[182:185], v[78:81]
	v_mfma_f32_16x16x32_bf16 v[70:73], v[146:149], v[182:185], v[70:73]
	s_barrier
	s_setprio 0
	s_and_b64 vcc, exec, s[4:5]
	s_cbranch_vccnz .LBB0_158
	ds_read_b128 v[178:181], v218 offset:49152
	ds_read_b128 v[194:197], v218 offset:50176
	ds_read_b128 v[174:177], v218 offset:51200
	ds_read_b128 v[190:193], v218 offset:52224
	ds_read_b128 v[170:173], v218 offset:53248
	ds_read_b128 v[186:189], v218 offset:54272
	ds_read_b128 v[166:169], v218 offset:55296
	ds_read_b128 v[182:185], v218 offset:56320

; #define PG8_STAGE(bufoff, gbase, voff) do { _Pragma("unroll") for (int _i = 0; _i < 2; ++_i) \
;         __builtin_amdgcn_global_load_lds((const unsigned*)((const char*)(gbase) + (voff)[_i]), (PG8_LAS unsigned*)(lds + (bufoff) + ldsw + _i * 8192), 16, 0, 0); } while (0)
; #define PG8_LDA(dst, b, h) do { _Pragma("unroll") for (int m = 0; m < 4; ++m) _Pragma("unroll") for (int k = 0; k < 2; ++k) dst[m][k] = *(const PG8_LAS bf16x8*)(lds + PG8_SA(b, h) + aoff + m * 2048 + k * 1024); } while (0)
; #define PG8_LDB(dst, b, h) do { _Pragma("unroll") for (int n = 0; n < 2; ++n) _Pragma("unroll") for (int k = 0; k < 2; ++k) dst[n][k] = *(const PG8_LAS bf16x8*)(lds + PG8_SB(b, h) + boff + n * 2048 + k * 1024); } while (0)
; #define PG8_MMA(ai, bj, At, Bt) do { __builtin_amdgcn_s_setprio(1); _Pragma("unroll") for (int m = 0; m < 4; ++m) _Pragma("unroll") for (int n = 0; n < 2; ++n) _Pragma("unroll") for (int k = 0; k < 2; ++k) \
;         acc[ai][bj][m][n] = __builtin_amdgcn_mfma_f32_16x16x32_bf16(Bt[n][k], At[m][k], acc[ai][bj][m][n], 0, 0, 0); __builtin_amdgcn_s_setprio(0); } while (0)
; #define PG8_WAIT_V(n) asm volatile("s_waitcnt vmcnt(" #n ")" ::: "memory")
; #define PG8_WAIT_L(n) asm volatile("s_waitcnt lgkmcnt(" #n ")" ::: "memory")
; #define PG8_BAR __builtin_amdgcn_s_barrier()
; #define PG8_SCHED __builtin_amdgcn_sched_barrier(0)
; template <class Epi, class Sched, bool ALIGN_EPI = false, bool SP2 = true>
; __device__ __forceinline__ void gemm_phase(PG8_LAS unsigned char* lds, const Gemm g, const Sched& S, const Epi& E) {
;     ...
;             PG8_LDB(B0, 0, 0); PG8_LDB(B1, 0, 1); PG8_SCHED; PG8_LDA(At, 0, 0); PG8_STAGE(PG8_SA(1, 1), a1 + hstep, voffA);
;             PG8_WAIT_V(8); PG8_WAIT_L(0); PG8_BAR; PG8_MMA(0, 0, At, B0); PG8_MMA(0, 1, At, B1); PG8_BAR; PG8_SCHED;
;             if (full) { PG8_LDA(At, 0, 1); } PG8_STAGE(PG8_SB(0, 0), b2, voffB); PG8_STAGE(PG8_SB(0, 1), b2 + hstep, voffB); PG8_STAGE(PG8_SA(0, 0), a2, voffA);
;             PG8_WAIT_V(8); PG8_WAIT_L(0); PG8_BAR; if (full) { PG8_MMA(1, 0, At, B0); PG8_MMA(1, 1, At, B1); } PG8_BAR; PG8_SCHED;
.LBB0_260:
	ds_read_b128 v[150:153], v209
	ds_read_b128 v[154:157], v209 offset:1024
	ds_read_b128 v[158:161], v209 offset:2048
	ds_read_b128 v[162:165], v209 offset:3072
	ds_read_b128 v[134:137], v226
	ds_read_b128 v[138:141], v226 offset:1024
	ds_read_b128 v[142:145], v226 offset:2048
	ds_read_b128 v[146:149], v226 offset:3072
	s_add_i32 m0, s38, 0xc000
	s_waitcnt lgkmcnt(7)
	ds_read_b128 v[178:181], v227
	ds_read_b128 v[194:197], v227 offset:1024
	ds_read_b128 v[174:177], v227 offset:2048
	ds_read_b128 v[190:193], v227 offset:3072
	ds_read_b128 v[170:173], v227 offset:4096
	ds_read_b128 v[186:189], v227 offset:5120
	ds_read_b128 v[166:169], v227 offset:6144
	ds_read_b128 v[182:185], v227 offset:7168
	global_load_lds_dwordx4 v212, s[24:25]
	s_add_i32 m0, s38, 0xe000
	s_nop 0
	global_load_lds_dwordx4 v214, s[24:25]
	s_waitcnt vmcnt(8)
	s_waitcnt lgkmcnt(0)
	s_setprio 1
	s_barrier
	v_mfma_f32_16x16x32_bf16 v[66:69], v[150:153], v[178:181], v[66:69]
	v_mfma_f32_16x16x32_bf16 v[62:65], v[158:161], v[178:181], v[62:65]
	v_mfma_f32_16x16x32_bf16 v[50:53], v[150:153], v[174:177], v[50:53]
	v_mfma_f32_16x16x32_bf16 v[46:49], v[158:161], v[174:177], v[46:49]
	v_mfma_f32_16x16x32_bf16 v[34:37], v[150:153], v[170:173], v[34:37]
	v_mfma_f32_16x16x32_bf16 v[30:33], v[158:161], v[170:173], v[30:33]
	v_mfma_f32_16x16x32_bf16 v[18:21], v[150:153], v[166:169], v[18:21]
	v_mfma_f32_16x16x32_bf16 v[14:17], v[158:161], v[166:169], v[14:17]
	v_mfma_f32_16x16x32_bf16 v[66:69], v[154:157], v[194:197], v[66:69]
	v_mfma_f32_16x16x32_bf16 v[62:65], v[162:165], v[194:197], v[62:65]
	v_mfma_f32_16x16x32_bf16 v[50:53], v[154:157], v[190:193], v[50:53]
	v_mfma_f32_16x16x32_bf16 v[46:49], v[162:165], v[190:193], v[46:49]
	v_mfma_f32_16x16x32_bf16 v[34:37], v[154:157], v[186:189], v[34:37]
	v_mfma_f32_16x16x32_bf16 v[30:33], v[162:165], v[186:189], v[30:33]
	v_mfma_f32_16x16x32_bf16 v[18:21], v[154:157], v[182:185], v[18:21]
	v_mfma_f32_16x16x32_bf16 v[14:17], v[162:165], v[182:185], v[14:17]
	v_mfma_f32_16x16x32_bf16 v[58:61], v[134:137], v[178:181], v[58:61]
	v_mfma_f32_16x16x32_bf16 v[54:57], v[142:145], v[178:181], v[54:57]
	v_mfma_f32_16x16x32_bf16 v[42:45], v[134:137], v[174:177], v[42:45]
	v_mfma_f32_16x16x32_bf16 v[38:41], v[142:145], v[174:177], v[38:41]
	v_mfma_f32_16x16x32_bf16 v[26:29], v[134:137], v[170:173], v[26:29]
	v_mfma_f32_16x16x32_bf16 v[22:25], v[142:145], v[170:173], v[22:25]
	v_mfma_f32_16x16x32_bf16 v[10:13], v[134:137], v[166:169], v[10:13]
	v_mfma_f32_16x16x32_bf16 v[4:7], v[142:145], v[166:169], v[6:9]
	v_mfma_f32_16x16x32_bf16 v[58:61], v[138:141], v[194:197], v[58:61]
	v_mfma_f32_16x16x32_bf16 v[54:57], v[146:149], v[194:197], v[54:57]
	v_mfma_f32_16x16x32_bf16 v[42:45], v[138:141], v[190:193], v[42:45]
	v_mfma_f32_16x16x32_bf16 v[38:41], v[146:149], v[190:193], v[38:41]
	v_mfma_f32_16x16x32_bf16 v[26:29], v[138:141], v[186:189], v[26:29]
	v_mfma_f32_16x16x32_bf16 v[22:25], v[146:149], v[186:189], v[22:25]
	v_mfma_f32_16x16x32_bf16 v[10:13], v[138:141], v[182:185], v[10:13]
	v_mfma_f32_16x16x32_bf16 v[4:7], v[146:149], v[182:185], v[4:7]
	s_barrier
	s_setprio 0
	v_cmp_ne_u32_e64 s[8:9], 1, v228
	s_andn2_b64 vcc, exec, s[2:3]
	s_cbranch_vccnz .LBB0_262
	ds_read_b128 v[178:181], v227 offset:16384
	ds_read_b128 v[194:197], v227 offset:17408
	ds_read_b128 v[174:177], v227 offset:18432
	ds_read_b128 v[190:193], v227 offset:19456
	ds_read_b128 v[170:173], v227 offset:20480
	ds_read_b128 v[186:189], v227 offset:21504
	ds_read_b128 v[166:169], v227 offset:22528
	ds_read_b128 v[182:185], v227 offset:23552

; #define PG8_STAGE(bufoff, gbase, voff) do { _Pragma("unroll") for (int _i = 0; _i < 2; ++_i) \
;         __builtin_amdgcn_global_load_lds((const unsigned*)((const char*)(gbase) + (voff)[_i]), (PG8_LAS unsigned*)(lds + (bufoff) + ldsw + _i * 8192), 16, 0, 0); } while (0)
; #define PG8_LDA(dst, b, h) do { _Pragma("unroll") for (int m = 0; m < 4; ++m) _Pragma("unroll") for (int k = 0; k < 2; ++k) dst[m][k] = *(const PG8_LAS bf16x8*)(lds + PG8_SA(b, h) + aoff + m * 2048 + k * 1024); } while (0)
; #define PG8_LDB(dst, b, h) do { _Pragma("unroll") for (int n = 0; n < 2; ++n) _Pragma("unroll") for (int k = 0; k < 2; ++k) dst[n][k] = *(const PG8_LAS bf16x8*)(lds + PG8_SB(b, h) + boff + n * 2048 + k * 1024); } while (0)
; #define PG8_MMA(ai, bj, At, Bt) do { __builtin_amdgcn_s_setprio(1); _Pragma("unroll") for (int m = 0; m < 4; ++m) _Pragma("unroll") for (int n = 0; n < 2; ++n) _Pragma("unroll") for (int k = 0; k < 2; ++k) \
;         acc[ai][bj][m][n] = __builtin_amdgcn_mfma_f32_16x16x32_bf16(Bt[n][k], At[m][k], acc[ai][bj][m][n], 0, 0, 0); __builtin_amdgcn_s_setprio(0); } while (0)
; #define PG8_WAIT_V(n) asm volatile("s_waitcnt vmcnt(" #n ")" ::: "memory")
; #define PG8_WAIT_L(n) asm volatile("s_waitcnt lgkmcnt(" #n ")" ::: "memory")
; #define PG8_BAR __builtin_amdgcn_s_barrier()
; #define PG8_SCHED __builtin_amdgcn_sched_barrier(0)
; template <class Epi, class Sched, bool ALIGN_EPI = false, bool SP2 = true>
; __device__ __forceinline__ void gemm_phase(PG8_LAS unsigned char* lds, const Gemm g, const Sched& S, const Epi& E) {
;     ...
;             PG8_LDB(B0, 1, 0); PG8_LDB(B1, 1, 1); PG8_SCHED; PG8_LDA(At, 1, 0); PG8_STAGE(PG8_SA(0, 1), a2 + hstep, voffA);
;             PG8_WAIT_V(8); PG8_WAIT_L(0); PG8_BAR; PG8_MMA(0, 0, At, B0); PG8_MMA(0, 1, At, B1); PG8_BAR; PG8_SCHED;
;             if (full) { PG8_LDA(At, 1, 1); } PG8_STAGE(PG8_SB(1, 0), b3, voffB); PG8_STAGE(PG8_SB(1, 1), b3 + hstep, voffB); PG8_STAGE(PG8_SA(1, 0), a3, voffA);
;             PG8_WAIT_V(8); PG8_WAIT_L(0); PG8_BAR; if (full) { PG8_MMA(1, 0, At, B0); PG8_MMA(1, 1, At, B1); } PG8_BAR; PG8_SCHED;
.LBB0_264:
	s_barrier
	s_setprio 0
	ds_read_b128 v[150:153], v209 offset:32768
	ds_read_b128 v[154:157], v209 offset:33792
	ds_read_b128 v[158:161], v209 offset:34816
	ds_read_b128 v[162:165], v209 offset:35840
	ds_read_b128 v[134:137], v226 offset:32768
	ds_read_b128 v[138:141], v226 offset:33792
	ds_read_b128 v[142:145], v226 offset:34816
	ds_read_b128 v[146:149], v226 offset:35840
	s_add_u32 s28, s28, 0x2b0000
	s_addc_u32 s29, s29, 0
	s_mov_b32 m0, s44
	s_waitcnt lgkmcnt(7)
	ds_read_b128 v[178:181], v227 offset:32768
	ds_read_b128 v[194:197], v227 offset:33792
	ds_read_b128 v[174:177], v227 offset:34816
	ds_read_b128 v[190:193], v227 offset:35840
	ds_read_b128 v[170:173], v227 offset:36864
	ds_read_b128 v[186:189], v227 offset:37888
	ds_read_b128 v[166:169], v227 offset:38912
	ds_read_b128 v[182:185], v227 offset:39936
	global_load_lds_dwordx4 v200, s[28:29]
	s_mov_b32 m0, s45
	s_nop 0
	global_load_lds_dwordx4 v204, s[28:29]
	s_waitcnt vmcnt(8)
	s_waitcnt lgkmcnt(0)
	s_setprio 1
	s_barrier
	v_mfma_f32_16x16x32_bf16 v[66:69], v[150:153], v[178:181], v[66:69]
	v_mfma_f32_16x16x32_bf16 v[62:65], v[158:161], v[178:181], v[62:65]
	v_mfma_f32_16x16x32_bf16 v[50:53], v[150:153], v[174:177], v[50:53]
	v_mfma_f32_16x16x32_bf16 v[46:49], v[158:161], v[174:177], v[46:49]
	v_mfma_f32_16x16x32_bf16 v[34:37], v[150:153], v[170:173], v[34:37]
	v_mfma_f32_16x16x32_bf16 v[30:33], v[158:161], v[170:173], v[30:33]
	v_mfma_f32_16x16x32_bf16 v[18:21], v[150:153], v[166:169], v[18:21]
	v_mfma_f32_16x16x32_bf16 v[14:17], v[158:161], v[166:169], v[14:17]
	v_mfma_f32_16x16x32_bf16 v[66:69], v[154:157], v[194:197], v[66:69]
	v_mfma_f32_16x16x32_bf16 v[62:65], v[162:165], v[194:197], v[62:65]
	v_mfma_f32_16x16x32_bf16 v[50:53], v[154:157], v[190:193], v[50:53]
	v_mfma_f32_16x16x32_bf16 v[46:49], v[162:165], v[190:193], v[46:49]
	v_mfma_f32_16x16x32_bf16 v[34:37], v[154:157], v[186:189], v[34:37]
	v_mfma_f32_16x16x32_bf16 v[30:33], v[162:165], v[186:189], v[30:33]
	v_mfma_f32_16x16x32_bf16 v[18:21], v[154:157], v[182:185], v[18:21]
	v_mfma_f32_16x16x32_bf16 v[14:17], v[162:165], v[182:185], v[14:17]
	v_mfma_f32_16x16x32_bf16 v[58:61], v[134:137], v[178:181], v[58:61]
	v_mfma_f32_16x16x32_bf16 v[54:57], v[142:145], v[178:181], v[54:57]
	v_mfma_f32_16x16x32_bf16 v[42:45], v[134:137], v[174:177], v[42:45]
	v_mfma_f32_16x16x32_bf16 v[38:41], v[142:145], v[174:177], v[38:41]
	v_mfma_f32_16x16x32_bf16 v[26:29], v[134:137], v[170:173], v[26:29]
	v_mfma_f32_16x16x32_bf16 v[22:25], v[142:145], v[170:173], v[22:25]
	v_mfma_f32_16x16x32_bf16 v[8:11], v[134:137], v[166:169], v[10:13]
	v_mfma_f32_16x16x32_bf16 v[4:7], v[142:145], v[166:169], v[4:7]
	v_mfma_f32_16x16x32_bf16 v[58:61], v[138:141], v[194:197], v[58:61]
	v_mfma_f32_16x16x32_bf16 v[54:57], v[146:149], v[194:197], v[54:57]
	v_mfma_f32_16x16x32_bf16 v[42:45], v[138:141], v[190:193], v[42:45]
	v_mfma_f32_16x16x32_bf16 v[38:41], v[146:149], v[190:193], v[38:41]
	v_mfma_f32_16x16x32_bf16 v[26:29], v[138:141], v[186:189], v[26:29]
	v_mfma_f32_16x16x32_bf16 v[22:25], v[146:149], v[186:189], v[22:25]
	v_mfma_f32_16x16x32_bf16 v[10:13], v[138:141], v[182:185], v[8:11]
	v_mfma_f32_16x16x32_bf16 v[6:9], v[146:149], v[182:185], v[4:7]
	s_barrier
	s_setprio 0
	s_and_b64 vcc, exec, s[8:9]
	s_cbranch_vccnz .LBB0_266
	ds_read_b128 v[178:181], v227 offset:49152
	ds_read_b128 v[194:197], v227 offset:50176
	ds_read_b128 v[174:177], v227 offset:51200
	ds_read_b128 v[190:193], v227 offset:52224
	ds_read_b128 v[170:173], v227 offset:53248
	ds_read_b128 v[186:189], v227 offset:54272
	ds_read_b128 v[166:169], v227 offset:55296
	ds_read_b128 v[182:185], v227 offset:56320

; #define LAS __attribute__((address_space(3)))
;     LAS float* scr = (LAS float*)(F.lds + RING_OFF + F.wave * 16384);
;     const int nblk = nbn ? nbn : N / 32, nall = (K / 64) * nblk, nitems = (int)((long)nall * f1 / 16);
;     int it = (int)((long)nall * f0 / 16) + w0; if (it >= nitems) return;
;     f32x4 va[8], vb[8], vc[8];
;     __builtin_amdgcn_s_waitcnt(0x0F70);
;     const int last = nitems - 1, ntri = ((nitems - it + nw - 1) / nw + 2) / 3;
;     int i1 = min(it + nw, last);
;     p0_item_load(W, N, nblk, nb0, it, F.lane, va);
;     p0_item_load(W, N, nblk, nb0, i1, F.lane, vb); __builtin_amdgcn_sched_barrier(0);
; __device__ __forceinline__ void convert_beside_win(Frame& F, const Args& A, int w0, int nw) {
;     ...
;     p0_transpose(F, A.in[26], D, DFF, (bf16*)(F.ws + WS_WGU2), 2, w0, nw, 0, UP2_SPLIT);
.LBB0_474:
	s_cmpk_gt_i32 s9, 0x55ff
	s_cbranch_scc1 .LBB0_478
	v_readlane_b32 s20, v236, 3
	v_readlane_b32 s21, v236, 4
	v_readlane_b32 s22, v236, 5
	v_readlane_b32 s23, v236, 6
	v_readlane_b32 s24, v236, 7
	v_readlane_b32 s25, v236, 8
	v_readlane_b32 s26, v236, 9
	v_readlane_b32 s27, v236, 10
	s_mov_b64 s[20:21], s[24:25]
	s_min_i32 s19, s11, 0x55ff
	s_waitcnt vmcnt(0)
	v_lshl_add_u64 v[2:3], s[20:21], 0, v[104:105]
	v_lshl_add_u64 v[2:3], s[0:1], 2, v[2:3]
	s_mul_hi_i32 s0, s19, 0x2fa0be83
	s_lshr_b32 s1, s0, 31
	s_ashr_i32 s0, s0, 6
	v_mov_b32_e32 v99, 0
	s_add_i32 s0, s0, s1
	v_lshl_add_u64 v[18:19], v[2:3], 0, v[98:99]
	s_mul_i32 s1, s0, 0x158
	v_lshl_or_b32 v4, s0, 6, v108
	s_mov_b32 s4, 0xac00
	v_mov_b64_e32 v[2:3], s[20:21]
	s_sub_i32 s2, s19, s1
	v_mad_i64_i32 v[2:3], s[0:1], v4, s4, v[2:3]
	s_lshl_b32 s0, s2, 5
	s_ashr_i32 s1, s0, 31
	v_lshl_add_u64 v[2:3], s[0:1], 2, v[2:3]
	s_mov_b32 s5, 0x56000
	v_lshl_add_u64 v[58:59], v[2:3], 0, v[98:99]
	v_add_co_u32_e32 v2, vcc, s5, v18
	s_mov_b32 s12, 0xac000
	s_nop 0
	v_addc_co_u32_e32 v3, vcc, 0, v19, vcc
	v_add_co_u32_e32 v6, vcc, s12, v18
	s_mov_b32 s13, 0x102000
	s_nop 0
	v_addc_co_u32_e32 v7, vcc, 0, v19, vcc
	v_add_co_u32_e32 v10, vcc, s13, v18
	s_mov_b32 s14, 0x158000
	s_nop 0
	v_addc_co_u32_e32 v11, vcc, 0, v19, vcc
	v_add_co_u32_e32 v14, vcc, s14, v18
	s_mov_b32 s15, 0x1ae000
	s_nop 0
	v_addc_co_u32_e32 v15, vcc, 0, v19, vcc
	v_add_co_u32_e32 v20, vcc, s15, v18
	s_mov_b32 s16, 0x204000
	s_nop 0
	v_addc_co_u32_e32 v21, vcc, 0, v19, vcc
	v_add_co_u32_e32 v22, vcc, s16, v18
	s_mov_b32 s17, 0x25a000
	s_nop 0
	v_addc_co_u32_e32 v23, vcc, 0, v19, vcc
	s_waitcnt vmcnt(0)
	global_load_dwordx4 v[2:5], v[2:3], off nt
	s_nop 0
	global_load_dwordx4 v[6:9], v[6:7], off nt
	s_nop 0
	global_load_dwordx4 v[10:13], v[10:11], off nt
	s_nop 0
	global_load_dwordx4 v[14:17], v[14:15], off nt
	s_nop 0
	global_load_dwordx4 v[26:29], v[20:21], off nt
	global_load_dwordx4 v[34:37], v[22:23], off nt
	v_add_co_u32_e32 v22, vcc, s17, v18
	s_abs_i32 s0, s8
	s_nop 0
	v_addc_co_u32_e32 v23, vcc, 0, v19, vcc
	v_add_co_u32_e32 v24, vcc, s5, v58
	global_load_dwordx4 v[30:33], v[18:19], off nt
	s_nop 0
	global_load_dwordx4 v[18:21], v[58:59], off nt
	v_addc_co_u32_e32 v25, vcc, 0, v59, vcc
	v_add_co_u32_e32 v38, vcc, s12, v58
	global_load_dwordx4 v[42:45], v[22:23], off nt
	s_nop 0
	global_load_dwordx4 v[22:25], v[24:25], off nt
	v_addc_co_u32_e32 v39, vcc, 0, v59, vcc
	v_add_co_u32_e32 v46, vcc, s13, v58
	v_cvt_f32_u32_e32 v66, s0
	s_nop 0
	v_addc_co_u32_e32 v47, vcc, 0, v59, vcc
	v_add_co_u32_e32 v50, vcc, s14, v58
	global_load_dwordx4 v[38:41], v[38:39], off nt
	s_nop 0
	global_load_dwordx4 v[46:49], v[46:47], off nt
	v_addc_co_u32_e32 v51, vcc, 0, v59, vcc
	v_add_co_u32_e32 v54, vcc, s15, v58
	v_rcp_iflag_f32_e32 v66, v66
	s_nop 0
	v_addc_co_u32_e32 v55, vcc, 0, v59, vcc
	v_add_co_u32_e32 v60, vcc, 0x204000, v58
	global_load_dwordx4 v[50:53], v[50:51], off nt
	s_nop 0
	global_load_dwordx4 v[54:57], v[54:55], off nt
	v_addc_co_u32_e32 v61, vcc, 0, v59, vcc
	v_add_co_u32_e32 v62, vcc, 0x25a000, v58
	v_mul_f32_e32 v66, 0x4f7ffffe, v66
	s_nop 0
	v_addc_co_u32_e32 v63, vcc, 0, v59, vcc
	global_load_dwordx4 v[58:61], v[60:61], off nt
	s_nop 0
	global_load_dwordx4 v[62:65], v[62:63], off nt
	v_cvt_u32_f32_e32 v66, v66
	s_add_i32 s1, s10, 0x55ff
	s_sub_i32 s3, 0xffffaa01, s10
	s_xor_b32 s2, s1, s8
	s_max_i32 s1, s1, s3
	s_sub_i32 s3, 0, s0
	v_readfirstlane_b32 s18, v66
	s_mul_i32 s3, s3, s18
	s_mul_hi_u32 s3, s18, s3
	s_add_i32 s18, s18, s3
	s_mul_hi_u32 s3, s1, s18
	s_mul_i32 s18, s3, s0
	s_sub_i32 s1, s1, s18
	s_ashr_i32 s2, s2, 31
	s_add_i32 s18, s3, 1
	s_sub_i32 s20, s1, s0
	s_cmp_ge_u32 s1, s0
	s_cselect_b32 s3, s18, s3
	s_cselect_b32 s1, s20, s1
	s_add_i32 s18, s3, 1
	s_cmp_ge_u32 s1, s0
	s_cselect_b32 s0, s18, s3
	s_xor_b32 s0, s0, s2
	s_sub_i32 s0, s0, s2
	s_mov_b64 s[22:23], s[26:27]
	s_cmp_lt_i32 s0, 1
	s_cbranch_scc1 .LBB0_478
	s_add_i32 s0, s0, 2
	s_mul_hi_u32 s0, s0, 0xaaaaaaab
	v_readlane_b32 s24, v236, 3
	s_lshr_b32 s18, s0, 1
	s_mov_b32 s21, s9
	v_readlane_b32 s28, v236, 7
	v_readlane_b32 s29, v236, 8
	v_readlane_b32 s25, v236, 4
	v_readlane_b32 s26, v236, 5
	v_readlane_b32 s27, v236, 6
	v_readlane_b32 s30, v236, 9
	v_readlane_b32 s31, v236, 10
; #define LAS __attribute__((address_space(3)))
; __device__ __forceinline__ void p0_item_store(const f32x4 (&v)[8], int K, int nblk, int nb0, bf16* __restrict__ WT, int mode, LAS float* scr, int item, int lane) {
;     const int kb = item / nblk, nb = nb0 + item % nblk, k0 = 64 * kb, n0 = 32 * nb;
; #pragma unroll
;     for (int i = 0; i < 8; ++i) { LAS float* d = scr + (8 * i + (lane >> 3)) * 33 + 4 * (lane & 7); d[0] = v[i].x; d[1] = v[i].y; d[2] = v[i].z; d[3] = v[i].w; }
;     LDS_WAIT(); asm volatile("" ::: "memory");
;     const int c = lane & 7, r0 = map_row(n0, mode);
;     const float wsc = mode == 1 ? 1.44269504089f : (mode == 2 ? 0.69314718056f : 1.0f);
; #pragma unroll
;     for (int j = 0; j < 4; ++j) { const int n = (lane >> 3) + 8 * j; const LAS float* s = scr + (8 * c) * 33 + n;
;         v4u o; o.x = cvt_pk_bf16(s[0 * 33] * wsc, s[1 * 33] * wsc); o.y = cvt_pk_bf16(s[2 * 33] * wsc, s[3 * 33] * wsc); o.z = cvt_pk_bf16(s[4 * 33] * wsc, s[5 * 33] * wsc); o.w = cvt_pk_bf16(s[6 * 33] * wsc, s[7 * 33] * wsc);
;         *(v4u*)(WT + (size_t)(r0 + n) * K + k0 + 8 * c) = o; }
;     LDS_WAIT(); asm volatile("" ::: "memory");
; }
;     LAS float* scr = (LAS float*)(F.lds + RING_OFF + F.wave * 16384);
;     const int nblk = nbn ? nbn : N / 32, nall = (K / 64) * nblk, nitems = (int)((long)nall * f1 / 16);
;     int it = (int)((long)nall * f0 / 16) + w0; if (it >= nitems) return;
;     f32x4 va[8], vb[8], vc[8];
;     __builtin_amdgcn_s_waitcnt(0x0F70);
;     const int last = nitems - 1, ntri = ((nitems - it + nw - 1) / nw + 2) / 3;
;     int i1 = min(it + nw, last);
;     p0_item_load(W, N, nblk, nb0, it, F.lane, va);
;     p0_item_load(W, N, nblk, nb0, i1, F.lane, vb); __builtin_amdgcn_sched_barrier(0);
;     for (int p = 0; p < ntri; ++p) {
;         const int i2 = min(i1 + nw, last), i3 = min(i2 + nw, last), i4 = min(i3 + nw, last);
;         p0_item_load(W, N, nblk, nb0, i2, F.lane, vc); __builtin_amdgcn_sched_barrier(0);
;         p0_item_store(va, K, nblk, nb0, WT, mode, scr, it, F.lane); __builtin_amdgcn_sched_barrier(0);
;         p0_item_load(W, N, nblk, nb0, i3, F.lane, va); __builtin_amdgcn_sched_barrier(0);
;         p0_item_store(vb, K, nblk, nb0, WT, mode, scr, i1, F.lane); __builtin_amdgcn_sched_barrier(0);
;         p0_item_load(W, N, nblk, nb0, i4, F.lane, vb); __builtin_amdgcn_sched_barrier(0);
.LBB0_477:
	s_add_i32 s0, s19, s8
	s_min_i32 s20, s0, 0x55ff
	s_mul_hi_i32 s0, s20, 0x2fa0be83
	s_lshr_b32 s1, s0, 31
	s_ashr_i32 s0, s0, 6
	s_add_i32 s0, s0, s1
	s_mul_i32 s1, s0, 0x158
	s_lshl_b32 s0, s0, 6
	v_or_b32_e32 v66, s0, v108
	v_mov_b64_e32 v[104:105], s[28:29]
	s_sub_i32 s1, s20, s1
	v_mad_i64_i32 v[66:67], s[2:3], v66, s4, v[104:105]
	s_lshl_b32 s2, s1, 5
	s_ashr_i32 s3, s2, 31
	v_lshl_add_u64 v[66:67], s[2:3], 2, v[66:67]
	v_lshl_add_u64 v[90:91], v[66:67], 0, v[98:99]
	v_add_co_u32_e32 v70, vcc, s5, v90
	s_add_i32 s20, s20, s8
	s_nop 0
	v_addc_co_u32_e32 v71, vcc, 0, v91, vcc
	v_add_co_u32_e32 v74, vcc, s12, v90
	global_load_dwordx4 v[66:69], v[90:91], off nt
	s_nop 0
	global_load_dwordx4 v[70:73], v[70:71], off nt
	v_addc_co_u32_e32 v75, vcc, 0, v91, vcc
	v_add_co_u32_e32 v78, vcc, s13, v90
	s_min_i32 s3, s20, 0x55ff
	s_nop 0
	v_addc_co_u32_e32 v79, vcc, 0, v91, vcc
	v_add_co_u32_e32 v82, vcc, s14, v90
	global_load_dwordx4 v[74:77], v[74:75], off nt
	s_nop 0
	global_load_dwordx4 v[78:81], v[78:79], off nt
	v_addc_co_u32_e32 v83, vcc, 0, v91, vcc
	v_add_co_u32_e32 v86, vcc, s15, v90
	s_add_i32 s20, s3, s8
	s_nop 0
	v_addc_co_u32_e32 v87, vcc, 0, v91, vcc
	v_add_co_u32_e32 v92, vcc, s16, v90
	global_load_dwordx4 v[82:85], v[82:83], off nt
	s_nop 0
	global_load_dwordx4 v[86:89], v[86:87], off nt
	v_addc_co_u32_e32 v93, vcc, 0, v91, vcc
	v_add_co_u32_e32 v94, vcc, s17, v90
	s_min_i32 s20, s20, 0x55ff
	s_nop 0
	v_addc_co_u32_e32 v95, vcc, 0, v91, vcc
	global_load_dwordx4 v[90:93], v[92:93], off nt
	s_nop 0
	global_load_dwordx4 v[94:97], v[94:95], off nt
	v_add_u32_e32 v101, v109, v110
	v_add_u32_e32 v106, 0x420, v101
	v_add_u32_e32 v107, 0x428, v101
	v_add_u32_e32 v115, 0x840, v101
	v_add_u32_e32 v116, 0x848, v101
	v_add_u32_e32 v117, 0xc60, v101
	v_add_u32_e32 v118, 0xc68, v101
	v_add_u32_e32 v119, 0x1080, v101
	v_add_u32_e32 v120, 0x1088, v101
	v_add_u32_e32 v121, 0x14a0, v101
	v_add_u32_e32 v122, 0x14a8, v101
	v_add_u32_e32 v123, 0x18c0, v101
	v_add_u32_e32 v124, 0x18c8, v101
	v_add_u32_e32 v125, 0x1ce0, v101
	v_add_u32_e32 v126, 0x1ce8, v101
	s_waitcnt vmcnt(0)
	ds_write2_b32 v101, v30, v31 offset1:1
	ds_write2_b32 v101, v32, v33 offset0:2 offset1:3
	ds_write2_b32 v106, v2, v3 offset1:1
	ds_write2_b32 v107, v4, v5 offset1:1
	ds_write2_b32 v115, v6, v7 offset1:1
	ds_write2_b32 v116, v8, v9 offset1:1
	ds_write2_b32 v117, v10, v11 offset1:1
	ds_write2_b32 v118, v12, v13 offset1:1
	ds_write2_b32 v119, v14, v15 offset1:1
	ds_write2_b32 v120, v16, v17 offset1:1
	ds_write2_b32 v121, v26, v27 offset1:1
	ds_write2_b32 v122, v28, v29 offset1:1
	ds_write2_b32 v123, v34, v35 offset1:1
	ds_write2_b32 v124, v36, v37 offset1:1
	ds_write2_b32 v125, v42, v43 offset1:1
	ds_write2_b32 v126, v44, v45 offset1:1
	s_waitcnt lgkmcnt(0)
	ds_read2_b32 v[2:3], v114 offset1:33
	s_mul_hi_i32 s22, s21, 0x2fa0be83
	s_lshr_b32 s23, s22, 31
	s_ashr_i32 s22, s22, 6
	s_add_i32 s22, s22, s23
	s_waitcnt lgkmcnt(0)
	v_mul_f32_e32 v2, 0x3f317218, v2
	v_mul_f32_e32 v3, 0x3f317218, v3
	v_cvt_pk_bf16_f32 v2, v2, v3
	ds_read2_b32 v[4:5], v114 offset0:66 offset1:99
	s_mul_i32 s23, s22, 0x158
	s_sub_i32 s21, s21, s23
	s_lshl_b32 s23, s21, 5
	s_lshl_b32 s21, s21, 6
	s_waitcnt lgkmcnt(0)
	v_mul_f32_e32 v3, 0x3f317218, v4
	v_mul_f32_e32 v4, 0x3f317218, v5
	v_cvt_pk_bf16_f32 v3, v3, v4
	ds_read2_b32 v[4:5], v114 offset0:132 offset1:165
	s_and_b32 s21, s21, 0xffffff00
	s_or_b32 s23, s23, 0xffffff80
	s_add_i32 s21, s23, s21
	s_addk_i32 s21, 0x100
	s_waitcnt lgkmcnt(0)
	v_mul_f32_e32 v4, 0x3f317218, v4
	v_mul_f32_e32 v5, 0x3f317218, v5
	v_cvt_pk_bf16_f32 v4, v4, v5
	ds_read2_b32 v[6:7], v114 offset0:198 offset1:231
	s_lshl_b32 s22, s22, 6
	s_ashr_i32 s23, s22, 31
	v_lshl_add_u64 v[8:9], s[22:23], 1, v[102:103]
	s_waitcnt lgkmcnt(0)
	v_mul_f32_e32 v5, 0x3f317218, v6
	v_mul_f32_e32 v6, 0x3f317218, v7
	v_cvt_pk_bf16_f32 v5, v5, v6
	ds_read2_b32 v[10:11], v114 offset0:8 offset1:41
	v_or_b32_e32 v6, s21, v108
	v_ashrrev_i32_e32 v7, 31, v6
	v_lshlrev_b64 v[6:7], 13, v[6:7]
	v_lshl_add_u64 v[6:7], v[8:9], 0, v[6:7]
	global_store_dwordx4 v[6:7], v[2:5], off
	s_waitcnt lgkmcnt(0)
	s_nop 0
	v_mul_f32_e32 v2, 0x3f317218, v10
	v_mul_f32_e32 v3, 0x3f317218, v11
	v_cvt_pk_bf16_f32 v2, v2, v3
	ds_read2_b32 v[4:5], v114 offset0:74 offset1:107
	s_waitcnt lgkmcnt(0)
	v_mul_f32_e32 v3, 0x3f317218, v4
	v_mul_f32_e32 v4, 0x3f317218, v5
	v_cvt_pk_bf16_f32 v3, v3, v4
	ds_read2_b32 v[4:5], v114 offset0:140 offset1:173
	s_waitcnt lgkmcnt(0)
	v_mul_f32_e32 v4, 0x3f317218, v4
	v_mul_f32_e32 v5, 0x3f317218, v5
	v_cvt_pk_bf16_f32 v4, v4, v5
	ds_read2_b32 v[6:7], v114 offset0:206 offset1:239
	s_waitcnt lgkmcnt(0)
	v_mul_f32_e32 v5, 0x3f317218, v6
	v_mul_f32_e32 v6, 0x3f317218, v7
	v_cvt_pk_bf16_f32 v5, v5, v6
	ds_read2_b32 v[10:11], v114 offset0:16 offset1:49
	v_or_b32_e32 v6, s21, v111
	v_ashrrev_i32_e32 v7, 31, v6
	v_lshlrev_b64 v[6:7], 13, v[6:7]
	v_lshl_add_u64 v[6:7], v[8:9], 0, v[6:7]
	global_store_dwordx4 v[6:7], v[2:5], off
	s_waitcnt lgkmcnt(0)
	s_nop 0
	v_mul_f32_e32 v2, 0x3f317218, v10
	v_mul_f32_e32 v3, 0x3f317218, v11
	v_cvt_pk_bf16_f32 v2, v2, v3
	ds_read2_b32 v[4:5], v114 offset0:82 offset1:115
	s_waitcnt lgkmcnt(0)
	v_mul_f32_e32 v3, 0x3f317218, v4
	v_mul_f32_e32 v4, 0x3f317218, v5
	v_cvt_pk_bf16_f32 v3, v3, v4
	ds_read2_b32 v[4:5], v114 offset0:148 offset1:181
	s_waitcnt lgkmcnt(0)
	v_mul_f32_e32 v4, 0x3f317218, v4
	v_mul_f32_e32 v5, 0x3f317218, v5
	v_cvt_pk_bf16_f32 v4, v4, v5
	ds_read2_b32 v[6:7], v114 offset0:214 offset1:247
	s_waitcnt lgkmcnt(0)
; #define LAS __attribute__((address_space(3)))
; __device__ __forceinline__ void p0_item_store(const f32x4 (&v)[8], int K, int nblk, int nb0, bf16* __restrict__ WT, int mode, LAS float* scr, int item, int lane) {
;     const int kb = item / nblk, nb = nb0 + item % nblk, k0 = 64 * kb, n0 = 32 * nb;
; #pragma unroll
;     for (int i = 0; i < 8; ++i) { LAS float* d = scr + (8 * i + (lane >> 3)) * 33 + 4 * (lane & 7); d[0] = v[i].x; d[1] = v[i].y; d[2] = v[i].z; d[3] = v[i].w; }
;     LDS_WAIT(); asm volatile("" ::: "memory");
;     const int c = lane & 7, r0 = map_row(n0, mode);
;     const float wsc = mode == 1 ? 1.44269504089f : (mode == 2 ? 0.69314718056f : 1.0f);
; #pragma unroll
;     for (int j = 0; j < 4; ++j) { const int n = (lane >> 3) + 8 * j; const LAS float* s = scr + (8 * c) * 33 + n;
;         v4u o; o.x = cvt_pk_bf16(s[0 * 33] * wsc, s[1 * 33] * wsc); o.y = cvt_pk_bf16(s[2 * 33] * wsc, s[3 * 33] * wsc); o.z = cvt_pk_bf16(s[4 * 33] * wsc, s[5 * 33] * wsc); o.w = cvt_pk_bf16(s[6 * 33] * wsc, s[7 * 33] * wsc);
;         *(v4u*)(WT + (size_t)(r0 + n) * K + k0 + 8 * c) = o; }
;     LDS_WAIT(); asm volatile("" ::: "memory");
; }
;     LAS float* scr = (LAS float*)(F.lds + RING_OFF + F.wave * 16384);
;     const int nblk = nbn ? nbn : N / 32, nall = (K / 64) * nblk, nitems = (int)((long)nall * f1 / 16);
;     int it = (int)((long)nall * f0 / 16) + w0; if (it >= nitems) return;
;     f32x4 va[8], vb[8], vc[8];
;     __builtin_amdgcn_s_waitcnt(0x0F70);
;     const int last = nitems - 1, ntri = ((nitems - it + nw - 1) / nw + 2) / 3;
;     int i1 = min(it + nw, last);
;     p0_item_load(W, N, nblk, nb0, it, F.lane, va);
;     p0_item_load(W, N, nblk, nb0, i1, F.lane, vb); __builtin_amdgcn_sched_barrier(0);
;     for (int p = 0; p < ntri; ++p) {
;         const int i2 = min(i1 + nw, last), i3 = min(i2 + nw, last), i4 = min(i3 + nw, last);
;         p0_item_load(W, N, nblk, nb0, i2, F.lane, vc); __builtin_amdgcn_sched_barrier(0);
;         p0_item_store(va, K, nblk, nb0, WT, mode, scr, it, F.lane); __builtin_amdgcn_sched_barrier(0);
;         p0_item_load(W, N, nblk, nb0, i3, F.lane, va); __builtin_amdgcn_sched_barrier(0);
;         p0_item_store(vb, K, nblk, nb0, WT, mode, scr, i1, F.lane); __builtin_amdgcn_sched_barrier(0);
;         p0_item_load(W, N, nblk, nb0, i4, F.lane, vb); __builtin_amdgcn_sched_barrier(0);
	v_mul_f32_e32 v5, 0x3f317218, v6
	v_mul_f32_e32 v6, 0x3f317218, v7
	v_cvt_pk_bf16_f32 v5, v5, v6
	ds_read2_b32 v[10:11], v114 offset0:24 offset1:57
	v_or_b32_e32 v6, s21, v112
	v_ashrrev_i32_e32 v7, 31, v6
	v_lshlrev_b64 v[6:7], 13, v[6:7]
	v_lshl_add_u64 v[6:7], v[8:9], 0, v[6:7]
	global_store_dwordx4 v[6:7], v[2:5], off
	s_waitcnt lgkmcnt(0)
	s_nop 0
	v_mul_f32_e32 v2, 0x3f317218, v10
	v_mul_f32_e32 v3, 0x3f317218, v11
	v_cvt_pk_bf16_f32 v2, v2, v3
	ds_read2_b32 v[4:5], v114 offset0:90 offset1:123
	s_waitcnt lgkmcnt(0)
	v_mul_f32_e32 v3, 0x3f317218, v4
	v_mul_f32_e32 v4, 0x3f317218, v5
	v_cvt_pk_bf16_f32 v3, v3, v4
	ds_read2_b32 v[4:5], v114 offset0:156 offset1:189
	s_waitcnt lgkmcnt(0)
	v_mul_f32_e32 v4, 0x3f317218, v4
	v_mul_f32_e32 v5, 0x3f317218, v5
	v_cvt_pk_bf16_f32 v4, v4, v5
	ds_read2_b32 v[6:7], v114 offset0:222 offset1:255
	s_waitcnt lgkmcnt(0)
	v_mul_f32_e32 v5, 0x3f317218, v6
	v_mul_f32_e32 v6, 0x3f317218, v7
	v_cvt_pk_bf16_f32 v5, v5, v6
	v_or_b32_e32 v6, s21, v113
	v_ashrrev_i32_e32 v7, 31, v6
	v_lshlrev_b64 v[6:7], 13, v[6:7]
	v_lshl_add_u64 v[6:7], v[8:9], 0, v[6:7]
	global_store_dwordx4 v[6:7], v[2:5], off
	s_waitcnt lgkmcnt(0)
	s_mul_hi_i32 s21, s3, 0x2fa0be83
	s_lshr_b32 s22, s21, 31
	s_ashr_i32 s21, s21, 6
	s_add_i32 s21, s21, s22
	s_mul_i32 s22, s21, 0x158
	v_lshl_or_b32 v2, s21, 6, v108
	s_sub_i32 s24, s3, s22
	v_mad_i64_i32 v[2:3], s[22:23], v2, s4, v[104:105]
	s_lshl_b32 s22, s24, 5
	s_ashr_i32 s23, s22, 31
	v_lshl_add_u64 v[2:3], s[22:23], 2, v[2:3]
	v_lshl_add_u64 v[34:35], v[2:3], 0, v[98:99]
	v_add_co_u32_e32 v2, vcc, s5, v34
	s_nop 1
	v_addc_co_u32_e32 v3, vcc, 0, v35, vcc
	v_add_co_u32_e32 v6, vcc, s12, v34
	global_load_dwordx4 v[30:33], v[34:35], off nt
	s_nop 0
	global_load_dwordx4 v[2:5], v[2:3], off nt
	v_addc_co_u32_e32 v7, vcc, 0, v35, vcc
	v_add_co_u32_e32 v10, vcc, s13, v34
	s_nop 1
	v_addc_co_u32_e32 v11, vcc, 0, v35, vcc
	v_add_co_u32_e32 v14, vcc, s14, v34
	global_load_dwordx4 v[6:9], v[6:7], off nt
	s_nop 0
	global_load_dwordx4 v[10:13], v[10:11], off nt
	v_addc_co_u32_e32 v15, vcc, 0, v35, vcc
	v_add_co_u32_e32 v26, vcc, s15, v34
	s_nop 1
	v_addc_co_u32_e32 v27, vcc, 0, v35, vcc
	v_add_co_u32_e32 v36, vcc, s16, v34
	global_load_dwordx4 v[14:17], v[14:15], off nt
	s_nop 0
	global_load_dwordx4 v[26:29], v[26:27], off nt
	v_addc_co_u32_e32 v37, vcc, 0, v35, vcc
	v_add_co_u32_e32 v42, vcc, s17, v34
	s_nop 1
	v_addc_co_u32_e32 v43, vcc, 0, v35, vcc
	global_load_dwordx4 v[34:37], v[36:37], off nt
	s_nop 0
	global_load_dwordx4 v[42:45], v[42:43], off nt
	ds_write2_b32 v101, v18, v19 offset1:1
	ds_write2_b32 v101, v20, v21 offset0:2 offset1:3
	ds_write2_b32 v106, v22, v23 offset1:1
	ds_write2_b32 v107, v24, v25 offset1:1
	ds_write2_b32 v115, v38, v39 offset1:1
	ds_write2_b32 v116, v40, v41 offset1:1
	ds_write2_b32 v117, v46, v47 offset1:1
	ds_write2_b32 v118, v48, v49 offset1:1
	ds_write2_b32 v119, v50, v51 offset1:1
	ds_write2_b32 v120, v52, v53 offset1:1
	ds_write2_b32 v121, v54, v55 offset1:1
	ds_write2_b32 v122, v56, v57 offset1:1
	ds_write2_b32 v123, v58, v59 offset1:1
	ds_write2_b32 v124, v60, v61 offset1:1
	ds_write2_b32 v125, v62, v63 offset1:1
	ds_write2_b32 v126, v64, v65 offset1:1
	s_waitcnt lgkmcnt(0)
	ds_read2_b32 v[18:19], v114 offset1:33
	s_mul_hi_i32 s21, s19, 0x2fa0be83
	s_lshr_b32 s22, s21, 31
	s_ashr_i32 s21, s21, 6
	s_add_i32 s21, s21, s22
	s_waitcnt lgkmcnt(0)
	v_mul_f32_e32 v18, 0x3f317218, v18
	v_mul_f32_e32 v19, 0x3f317218, v19
	v_cvt_pk_bf16_f32 v18, v18, v19
	ds_read2_b32 v[20:21], v114 offset0:66 offset1:99
	s_mul_i32 s22, s21, 0x158
	s_sub_i32 s19, s19, s22
	s_lshl_b32 s22, s19, 5
	s_lshl_b32 s19, s19, 6
	s_waitcnt lgkmcnt(0)
	v_mul_f32_e32 v19, 0x3f317218, v20
	v_mul_f32_e32 v20, 0x3f317218, v21
	v_cvt_pk_bf16_f32 v19, v19, v20
	ds_read2_b32 v[20:21], v114 offset0:132 offset1:165
	s_and_b32 s19, s19, 0xffffff00
	s_or_b32 s22, s22, 0xffffff80
	s_add_i32 s19, s22, s19
	s_addk_i32 s19, 0x100
	s_waitcnt lgkmcnt(0)
	v_mul_f32_e32 v20, 0x3f317218, v20
	v_mul_f32_e32 v21, 0x3f317218, v21
	v_cvt_pk_bf16_f32 v20, v20, v21
	ds_read2_b32 v[22:23], v114 offset0:198 offset1:231
	s_lshl_b32 s22, s21, 6
	s_ashr_i32 s23, s22, 31
	v_lshl_add_u64 v[24:25], s[22:23], 1, v[102:103]
	s_waitcnt lgkmcnt(0)
	v_mul_f32_e32 v21, 0x3f317218, v22
	v_mul_f32_e32 v22, 0x3f317218, v23
	v_cvt_pk_bf16_f32 v21, v21, v22
	ds_read2_b32 v[38:39], v114 offset0:8 offset1:41
	v_or_b32_e32 v22, s19, v108
	v_ashrrev_i32_e32 v23, 31, v22
	v_lshlrev_b64 v[22:23], 13, v[22:23]
	v_lshl_add_u64 v[22:23], v[24:25], 0, v[22:23]
	global_store_dwordx4 v[22:23], v[18:21], off
	s_waitcnt lgkmcnt(0)
	s_nop 0
	v_mul_f32_e32 v18, 0x3f317218, v38
	v_mul_f32_e32 v19, 0x3f317218, v39
	v_cvt_pk_bf16_f32 v18, v18, v19
	ds_read2_b32 v[20:21], v114 offset0:74 offset1:107
	s_waitcnt lgkmcnt(0)
	v_mul_f32_e32 v19, 0x3f317218, v20
	v_mul_f32_e32 v20, 0x3f317218, v21
	v_cvt_pk_bf16_f32 v19, v19, v20
	ds_read2_b32 v[20:21], v114 offset0:140 offset1:173
	s_waitcnt lgkmcnt(0)
	v_mul_f32_e32 v20, 0x3f317218, v20
	v_mul_f32_e32 v21, 0x3f317218, v21
	v_cvt_pk_bf16_f32 v20, v20, v21
	ds_read2_b32 v[22:23], v114 offset0:206 offset1:239
	s_waitcnt lgkmcnt(0)
	v_mul_f32_e32 v21, 0x3f317218, v22
	v_mul_f32_e32 v22, 0x3f317218, v23
	v_cvt_pk_bf16_f32 v21, v21, v22
	ds_read2_b32 v[38:39], v114 offset0:16 offset1:49
	v_or_b32_e32 v22, s19, v111
	v_ashrrev_i32_e32 v23, 31, v22
	v_lshlrev_b64 v[22:23], 13, v[22:23]
	v_lshl_add_u64 v[22:23], v[24:25], 0, v[22:23]
	global_store_dwordx4 v[22:23], v[18:21], off
	s_waitcnt lgkmcnt(0)
	s_nop 0
	v_mul_f32_e32 v18, 0x3f317218, v38
	v_mul_f32_e32 v19, 0x3f317218, v39
	v_cvt_pk_bf16_f32 v18, v18, v19
	ds_read2_b32 v[20:21], v114 offset0:82 offset1:115
	s_waitcnt lgkmcnt(0)
; #define LAS __attribute__((address_space(3)))
; __device__ __forceinline__ void p0_item_store(const f32x4 (&v)[8], int K, int nblk, int nb0, bf16* __restrict__ WT, int mode, LAS float* scr, int item, int lane) {
;     const int kb = item / nblk, nb = nb0 + item % nblk, k0 = 64 * kb, n0 = 32 * nb;
; #pragma unroll
;     for (int i = 0; i < 8; ++i) { LAS float* d = scr + (8 * i + (lane >> 3)) * 33 + 4 * (lane & 7); d[0] = v[i].x; d[1] = v[i].y; d[2] = v[i].z; d[3] = v[i].w; }
;     LDS_WAIT(); asm volatile("" ::: "memory");
;     const int c = lane & 7, r0 = map_row(n0, mode);
;     const float wsc = mode == 1 ? 1.44269504089f : (mode == 2 ? 0.69314718056f : 1.0f);
; #pragma unroll
;     for (int j = 0; j < 4; ++j) { const int n = (lane >> 3) + 8 * j; const LAS float* s = scr + (8 * c) * 33 + n;
;         v4u o; o.x = cvt_pk_bf16(s[0 * 33] * wsc, s[1 * 33] * wsc); o.y = cvt_pk_bf16(s[2 * 33] * wsc, s[3 * 33] * wsc); o.z = cvt_pk_bf16(s[4 * 33] * wsc, s[5 * 33] * wsc); o.w = cvt_pk_bf16(s[6 * 33] * wsc, s[7 * 33] * wsc);
;         *(v4u*)(WT + (size_t)(r0 + n) * K + k0 + 8 * c) = o; }
;     LDS_WAIT(); asm volatile("" ::: "memory");
; }
;     LAS float* scr = (LAS float*)(F.lds + RING_OFF + F.wave * 16384);
;     const int nblk = nbn ? nbn : N / 32, nall = (K / 64) * nblk, nitems = (int)((long)nall * f1 / 16);
;     int it = (int)((long)nall * f0 / 16) + w0; if (it >= nitems) return;
;     f32x4 va[8], vb[8], vc[8];
;     __builtin_amdgcn_s_waitcnt(0x0F70);
;     const int last = nitems - 1, ntri = ((nitems - it + nw - 1) / nw + 2) / 3;
;     int i1 = min(it + nw, last);
;     p0_item_load(W, N, nblk, nb0, it, F.lane, va);
;     p0_item_load(W, N, nblk, nb0, i1, F.lane, vb); __builtin_amdgcn_sched_barrier(0);
;     for (int p = 0; p < ntri; ++p) {
;         const int i2 = min(i1 + nw, last), i3 = min(i2 + nw, last), i4 = min(i3 + nw, last);
;         p0_item_load(W, N, nblk, nb0, i2, F.lane, vc); __builtin_amdgcn_sched_barrier(0);
;         p0_item_store(va, K, nblk, nb0, WT, mode, scr, it, F.lane); __builtin_amdgcn_sched_barrier(0);
;         p0_item_load(W, N, nblk, nb0, i3, F.lane, va); __builtin_amdgcn_sched_barrier(0);
;         p0_item_store(vb, K, nblk, nb0, WT, mode, scr, i1, F.lane); __builtin_amdgcn_sched_barrier(0);
;         p0_item_load(W, N, nblk, nb0, i4, F.lane, vb); __builtin_amdgcn_sched_barrier(0);
	v_mul_f32_e32 v19, 0x3f317218, v20
	v_mul_f32_e32 v20, 0x3f317218, v21
	v_cvt_pk_bf16_f32 v19, v19, v20
	ds_read2_b32 v[20:21], v114 offset0:148 offset1:181
	s_waitcnt lgkmcnt(0)
	v_mul_f32_e32 v20, 0x3f317218, v20
	v_mul_f32_e32 v21, 0x3f317218, v21
	v_cvt_pk_bf16_f32 v20, v20, v21
	ds_read2_b32 v[22:23], v114 offset0:214 offset1:247
	s_waitcnt lgkmcnt(0)
	v_mul_f32_e32 v21, 0x3f317218, v22
	v_mul_f32_e32 v22, 0x3f317218, v23
	v_cvt_pk_bf16_f32 v21, v21, v22
	ds_read2_b32 v[38:39], v114 offset0:24 offset1:57
	v_or_b32_e32 v22, s19, v112
	v_ashrrev_i32_e32 v23, 31, v22
	v_lshlrev_b64 v[22:23], 13, v[22:23]
	v_lshl_add_u64 v[22:23], v[24:25], 0, v[22:23]
	global_store_dwordx4 v[22:23], v[18:21], off
	s_waitcnt lgkmcnt(0)
	s_nop 0
	v_mul_f32_e32 v18, 0x3f317218, v38
	v_mul_f32_e32 v19, 0x3f317218, v39
	v_cvt_pk_bf16_f32 v18, v18, v19
	ds_read2_b32 v[20:21], v114 offset0:90 offset1:123
	s_waitcnt lgkmcnt(0)
	v_mul_f32_e32 v19, 0x3f317218, v20
	v_mul_f32_e32 v20, 0x3f317218, v21
	v_cvt_pk_bf16_f32 v19, v19, v20
	ds_read2_b32 v[20:21], v114 offset0:156 offset1:189
	s_waitcnt lgkmcnt(0)
	v_mul_f32_e32 v20, 0x3f317218, v20
	v_mul_f32_e32 v21, 0x3f317218, v21
	v_cvt_pk_bf16_f32 v20, v20, v21
	ds_read2_b32 v[22:23], v114 offset0:222 offset1:255
	s_waitcnt lgkmcnt(0)
	v_mul_f32_e32 v21, 0x3f317218, v22
	v_mul_f32_e32 v22, 0x3f317218, v23
	v_cvt_pk_bf16_f32 v21, v21, v22
	v_or_b32_e32 v22, s19, v113
	v_ashrrev_i32_e32 v23, 31, v22
	v_lshlrev_b64 v[22:23], 13, v[22:23]
	v_lshl_add_u64 v[22:23], v[24:25], 0, v[22:23]
	global_store_dwordx4 v[22:23], v[18:21], off
	s_waitcnt lgkmcnt(0)
	s_mul_hi_i32 s19, s20, 0x2fa0be83
	s_lshr_b32 s21, s19, 31
	s_ashr_i32 s19, s19, 6
	s_add_i32 s19, s19, s21
	s_mul_i32 s21, s19, 0x158
	v_lshl_or_b32 v18, s19, 6, v108
	s_sub_i32 s21, s20, s21
	v_mad_i64_i32 v[18:19], s[22:23], v18, s4, v[104:105]
	s_lshl_b32 s22, s21, 5
	s_ashr_i32 s23, s22, 31
	v_lshl_add_u64 v[18:19], s[22:23], 2, v[18:19]
	v_lshl_add_u64 v[58:59], v[18:19], 0, v[98:99]
	v_add_co_u32_e32 v22, vcc, s5, v58
	s_nop 1
	v_addc_co_u32_e32 v23, vcc, 0, v59, vcc
	v_add_co_u32_e32 v38, vcc, s12, v58
	global_load_dwordx4 v[18:21], v[58:59], off nt
	s_nop 0
	global_load_dwordx4 v[22:25], v[22:23], off nt
	v_addc_co_u32_e32 v39, vcc, 0, v59, vcc
	v_add_co_u32_e32 v46, vcc, s13, v58
	s_nop 1
	v_addc_co_u32_e32 v47, vcc, 0, v59, vcc
	v_add_co_u32_e32 v50, vcc, s14, v58
	global_load_dwordx4 v[38:41], v[38:39], off nt
	s_nop 0
	global_load_dwordx4 v[46:49], v[46:47], off nt
	v_addc_co_u32_e32 v51, vcc, 0, v59, vcc
	v_add_co_u32_e32 v54, vcc, s15, v58
	s_nop 1
	v_addc_co_u32_e32 v55, vcc, 0, v59, vcc
	v_add_co_u32_e32 v60, vcc, s16, v58
	global_load_dwordx4 v[50:53], v[50:51], off nt
	s_nop 0
	global_load_dwordx4 v[54:57], v[54:55], off nt
	v_addc_co_u32_e32 v61, vcc, 0, v59, vcc
	v_add_co_u32_e32 v62, vcc, s17, v58
	s_nop 1
	v_addc_co_u32_e32 v63, vcc, 0, v59, vcc
	global_load_dwordx4 v[58:61], v[60:61], off nt
	s_nop 0
	global_load_dwordx4 v[62:65], v[62:63], off nt
	ds_write2_b32 v101, v66, v67 offset1:1
	ds_write2_b32 v101, v68, v69 offset0:2 offset1:3
	ds_write2_b32 v106, v70, v71 offset1:1
	ds_write2_b32 v107, v72, v73 offset1:1
	ds_write2_b32 v115, v74, v75 offset1:1
	ds_write2_b32 v116, v76, v77 offset1:1
	ds_write2_b32 v117, v78, v79 offset1:1
	ds_write2_b32 v118, v80, v81 offset1:1
	ds_write2_b32 v119, v82, v83 offset1:1
	ds_write2_b32 v120, v84, v85 offset1:1
	ds_write2_b32 v121, v86, v87 offset1:1
	ds_write2_b32 v122, v88, v89 offset1:1
	ds_write2_b32 v123, v90, v91 offset1:1
	ds_write2_b32 v124, v92, v93 offset1:1
	ds_write2_b32 v125, v94, v95 offset1:1
	ds_write2_b32 v126, v96, v97 offset1:1
	s_waitcnt lgkmcnt(0)
	ds_read2_b32 v[66:67], v114 offset1:33
	s_lshl_b32 s1, s1, 6
	s_and_b32 s1, s1, 0xffffff00
	s_or_b32 s2, s2, 0xffffff80
	s_add_i32 s1, s2, s1
	s_waitcnt lgkmcnt(0)
; #define LAS __attribute__((address_space(3)))
; __device__ __forceinline__ void p0_item_store(const f32x4 (&v)[8], int K, int nblk, int nb0, bf16* __restrict__ WT, int mode, LAS float* scr, int item, int lane) {
;     const int kb = item / nblk, nb = nb0 + item % nblk, k0 = 64 * kb, n0 = 32 * nb;
; #pragma unroll
;     for (int i = 0; i < 8; ++i) { LAS float* d = scr + (8 * i + (lane >> 3)) * 33 + 4 * (lane & 7); d[0] = v[i].x; d[1] = v[i].y; d[2] = v[i].z; d[3] = v[i].w; }
;     LDS_WAIT(); asm volatile("" ::: "memory");
;     const int c = lane & 7, r0 = map_row(n0, mode);
;     const float wsc = mode == 1 ? 1.44269504089f : (mode == 2 ? 0.69314718056f : 1.0f);
; #pragma unroll
;     for (int j = 0; j < 4; ++j) { const int n = (lane >> 3) + 8 * j; const LAS float* s = scr + (8 * c) * 33 + n;
;         v4u o; o.x = cvt_pk_bf16(s[0 * 33] * wsc, s[1 * 33] * wsc); o.y = cvt_pk_bf16(s[2 * 33] * wsc, s[3 * 33] * wsc); o.z = cvt_pk_bf16(s[4 * 33] * wsc, s[5 * 33] * wsc); o.w = cvt_pk_bf16(s[6 * 33] * wsc, s[7 * 33] * wsc);
;         *(v4u*)(WT + (size_t)(r0 + n) * K + k0 + 8 * c) = o; }
;     LDS_WAIT(); asm volatile("" ::: "memory");
; }
;     LAS float* scr = (LAS float*)(F.lds + RING_OFF + F.wave * 16384);
;     const int nblk = nbn ? nbn : N / 32, nall = (K / 64) * nblk, nitems = (int)((long)nall * f1 / 16);
;     int it = (int)((long)nall * f0 / 16) + w0; if (it >= nitems) return;
;     f32x4 va[8], vb[8], vc[8];
;     __builtin_amdgcn_s_waitcnt(0x0F70);
;     const int last = nitems - 1, ntri = ((nitems - it + nw - 1) / nw + 2) / 3;
;     int i1 = min(it + nw, last);
;     p0_item_load(W, N, nblk, nb0, it, F.lane, va);
;     p0_item_load(W, N, nblk, nb0, i1, F.lane, vb); __builtin_amdgcn_sched_barrier(0);
;     for (int p = 0; p < ntri; ++p) {
;         const int i2 = min(i1 + nw, last), i3 = min(i2 + nw, last), i4 = min(i3 + nw, last);
;         p0_item_load(W, N, nblk, nb0, i2, F.lane, vc); __builtin_amdgcn_sched_barrier(0);
;         p0_item_store(va, K, nblk, nb0, WT, mode, scr, it, F.lane); __builtin_amdgcn_sched_barrier(0);
;         p0_item_load(W, N, nblk, nb0, i3, F.lane, va); __builtin_amdgcn_sched_barrier(0);
;         p0_item_store(vb, K, nblk, nb0, WT, mode, scr, i1, F.lane); __builtin_amdgcn_sched_barrier(0);
;         p0_item_load(W, N, nblk, nb0, i4, F.lane, vb); __builtin_amdgcn_sched_barrier(0);
	v_mul_f32_e32 v66, 0x3f317218, v66
	v_mul_f32_e32 v67, 0x3f317218, v67
	v_cvt_pk_bf16_f32 v66, v66, v67
	ds_read2_b32 v[68:69], v114 offset0:66 offset1:99
	s_add_i32 s2, s1, 0x100
	s_ashr_i32 s1, s0, 31
	v_lshl_add_u64 v[72:73], s[0:1], 1, v[102:103]
	s_waitcnt lgkmcnt(0)
	v_mul_f32_e32 v67, 0x3f317218, v68
	v_mul_f32_e32 v68, 0x3f317218, v69
	v_cvt_pk_bf16_f32 v67, v67, v68
	ds_read2_b32 v[68:69], v114 offset0:132 offset1:165
	s_waitcnt lgkmcnt(0)
	v_mul_f32_e32 v68, 0x3f317218, v68
	v_mul_f32_e32 v69, 0x3f317218, v69
	v_cvt_pk_bf16_f32 v68, v68, v69
	ds_read2_b32 v[70:71], v114 offset0:198 offset1:231
	s_waitcnt lgkmcnt(0)
	v_mul_f32_e32 v69, 0x3f317218, v70
	v_mul_f32_e32 v70, 0x3f317218, v71
	v_cvt_pk_bf16_f32 v69, v69, v70
	ds_read2_b32 v[74:75], v114 offset0:8 offset1:41
	v_or_b32_e32 v70, s2, v108
	v_ashrrev_i32_e32 v71, 31, v70
	v_lshlrev_b64 v[70:71], 13, v[70:71]
	v_lshl_add_u64 v[70:71], v[72:73], 0, v[70:71]
	global_store_dwordx4 v[70:71], v[66:69], off
	s_waitcnt lgkmcnt(0)
	s_nop 0
	v_mul_f32_e32 v66, 0x3f317218, v74
	v_mul_f32_e32 v67, 0x3f317218, v75
	v_cvt_pk_bf16_f32 v66, v66, v67
	ds_read2_b32 v[68:69], v114 offset0:74 offset1:107
	s_waitcnt lgkmcnt(0)
	v_mul_f32_e32 v67, 0x3f317218, v68
	v_mul_f32_e32 v68, 0x3f317218, v69
	v_cvt_pk_bf16_f32 v67, v67, v68
	ds_read2_b32 v[68:69], v114 offset0:140 offset1:173
	s_waitcnt lgkmcnt(0)
	v_mul_f32_e32 v68, 0x3f317218, v68
	v_mul_f32_e32 v69, 0x3f317218, v69
	v_cvt_pk_bf16_f32 v68, v68, v69
	ds_read2_b32 v[70:71], v114 offset0:206 offset1:239
	s_waitcnt lgkmcnt(0)
	v_mul_f32_e32 v69, 0x3f317218, v70
	v_mul_f32_e32 v70, 0x3f317218, v71
	v_cvt_pk_bf16_f32 v69, v69, v70
	ds_read2_b32 v[74:75], v114 offset0:16 offset1:49
	v_or_b32_e32 v70, s2, v111
	v_ashrrev_i32_e32 v71, 31, v70
	v_lshlrev_b64 v[70:71], 13, v[70:71]
	v_lshl_add_u64 v[70:71], v[72:73], 0, v[70:71]
	global_store_dwordx4 v[70:71], v[66:69], off
	s_waitcnt lgkmcnt(0)
	s_nop 0
	v_mul_f32_e32 v66, 0x3f317218, v74
	v_mul_f32_e32 v67, 0x3f317218, v75
	v_cvt_pk_bf16_f32 v66, v66, v67
	ds_read2_b32 v[68:69], v114 offset0:82 offset1:115
	s_waitcnt lgkmcnt(0)
	v_mul_f32_e32 v67, 0x3f317218, v68
	v_mul_f32_e32 v68, 0x3f317218, v69
	v_cvt_pk_bf16_f32 v67, v67, v68
	ds_read2_b32 v[68:69], v114 offset0:148 offset1:181
	s_waitcnt lgkmcnt(0)
	v_mul_f32_e32 v68, 0x3f317218, v68
	v_mul_f32_e32 v69, 0x3f317218, v69
	v_cvt_pk_bf16_f32 v68, v68, v69
	ds_read2_b32 v[70:71], v114 offset0:214 offset1:247
	s_waitcnt lgkmcnt(0)
	v_mul_f32_e32 v69, 0x3f317218, v70
	v_mul_f32_e32 v70, 0x3f317218, v71
	v_cvt_pk_bf16_f32 v69, v69, v70
	ds_read2_b32 v[74:75], v114 offset0:24 offset1:57
	v_or_b32_e32 v70, s2, v112
	v_ashrrev_i32_e32 v71, 31, v70
	v_lshlrev_b64 v[70:71], 13, v[70:71]
	v_lshl_add_u64 v[70:71], v[72:73], 0, v[70:71]
	global_store_dwordx4 v[70:71], v[66:69], off
	s_waitcnt lgkmcnt(0)
	s_nop 0
	v_mul_f32_e32 v66, 0x3f317218, v74
	v_mul_f32_e32 v67, 0x3f317218, v75
	v_cvt_pk_bf16_f32 v66, v66, v67
	ds_read2_b32 v[68:69], v114 offset0:90 offset1:123
	s_waitcnt lgkmcnt(0)
	v_mul_f32_e32 v67, 0x3f317218, v68
	v_mul_f32_e32 v68, 0x3f317218, v69
	v_cvt_pk_bf16_f32 v67, v67, v68
	ds_read2_b32 v[68:69], v114 offset0:156 offset1:189
	s_waitcnt lgkmcnt(0)
	v_mul_f32_e32 v68, 0x3f317218, v68
	v_mul_f32_e32 v69, 0x3f317218, v69
	v_cvt_pk_bf16_f32 v68, v68, v69
	ds_read2_b32 v[70:71], v114 offset0:222 offset1:255
	s_waitcnt lgkmcnt(0)
	v_mul_f32_e32 v69, 0x3f317218, v70
	v_mul_f32_e32 v70, 0x3f317218, v71
	v_cvt_pk_bf16_f32 v69, v69, v70
	v_or_b32_e32 v70, s2, v113
	v_ashrrev_i32_e32 v71, 31, v70
	v_lshlrev_b64 v[70:71], 13, v[70:71]
	v_lshl_add_u64 v[70:71], v[72:73], 0, v[70:71]
	global_store_dwordx4 v[70:71], v[66:69], off
	s_waitcnt lgkmcnt(0)
	s_add_i32 s18, s18, -1
	s_cmp_lg_u32 s18, 0
	s_mov_b32 s21, s3
	s_mov_b32 s19, s20
	s_cbranch_scc1 .LBB0_477

; #define PG8_STAGE(bufoff, gbase, voff) do { _Pragma("unroll") for (int _i = 0; _i < 2; ++_i) \
;         __builtin_amdgcn_global_load_lds((const unsigned*)((const char*)(gbase) + (voff)[_i]), (PG8_LAS unsigned*)(lds + (bufoff) + ldsw + _i * 8192), 16, 0, 0); } while (0)
; #define PG8_LDA(dst, b, h) do { _Pragma("unroll") for (int m = 0; m < 4; ++m) _Pragma("unroll") for (int k = 0; k < 2; ++k) dst[m][k] = *(const PG8_LAS bf16x8*)(lds + PG8_SA(b, h) + aoff + m * 2048 + k * 1024); } while (0)
; #define PG8_LDB(dst, b, h) do { _Pragma("unroll") for (int n = 0; n < 2; ++n) _Pragma("unroll") for (int k = 0; k < 2; ++k) dst[n][k] = *(const PG8_LAS bf16x8*)(lds + PG8_SB(b, h) + boff + n * 2048 + k * 1024); } while (0)
; #define PG8_MMA(ai, bj, At, Bt) do { __builtin_amdgcn_s_setprio(1); _Pragma("unroll") for (int m = 0; m < 4; ++m) _Pragma("unroll") for (int n = 0; n < 2; ++n) _Pragma("unroll") for (int k = 0; k < 2; ++k) \
;         acc[ai][bj][m][n] = __builtin_amdgcn_mfma_f32_16x16x32_bf16(Bt[n][k], At[m][k], acc[ai][bj][m][n], 0, 0, 0); __builtin_amdgcn_s_setprio(0); } while (0)
; #define PG8_WAIT_V(n) asm volatile("s_waitcnt vmcnt(" #n ")" ::: "memory")
; #define PG8_WAIT_L(n) asm volatile("s_waitcnt lgkmcnt(" #n ")" ::: "memory")
; #define PG8_BAR __builtin_amdgcn_s_barrier()
; #define PG8_SCHED __builtin_amdgcn_sched_barrier(0)
; template <class Epi, class Sched, bool ALIGN_EPI = false, bool SP2 = true>
; __device__ __forceinline__ void gemm_phase(PG8_LAS unsigned char* lds, const Gemm g, const Sched& S, const Epi& E) {
;     ...
;             PG8_LDB(B0, 0, 0); PG8_LDB(B1, 0, 1); PG8_SCHED; PG8_LDA(At, 0, 0); PG8_STAGE(PG8_SA(1, 1), a1 + hstep, voffA);
;             PG8_WAIT_V(8); PG8_WAIT_L(0); PG8_BAR; PG8_MMA(0, 0, At, B0); PG8_MMA(0, 1, At, B1); PG8_BAR; PG8_SCHED;
;             if (full) { PG8_LDA(At, 0, 1); } PG8_STAGE(PG8_SB(0, 0), b2, voffB); PG8_STAGE(PG8_SB(0, 1), b2 + hstep, voffB); PG8_STAGE(PG8_SA(0, 0), a2, voffA);
;             PG8_WAIT_V(8); PG8_WAIT_L(0); PG8_BAR; if (full) { PG8_MMA(1, 0, At, B0); PG8_MMA(1, 1, At, B1); } PG8_BAR; PG8_SCHED;
.LBB0_503:
	ds_read_b128 v[150:153], v209
	ds_read_b128 v[154:157], v209 offset:1024
	ds_read_b128 v[158:161], v209 offset:2048
	ds_read_b128 v[162:165], v209 offset:3072
	ds_read_b128 v[134:137], v224
	ds_read_b128 v[138:141], v224 offset:1024
	ds_read_b128 v[142:145], v224 offset:2048
	ds_read_b128 v[146:149], v224 offset:3072
	s_add_i32 m0, s31, 0xc000
	s_waitcnt lgkmcnt(7)
	ds_read_b128 v[178:181], v225
	ds_read_b128 v[194:197], v225 offset:1024
	ds_read_b128 v[174:177], v225 offset:2048
	ds_read_b128 v[190:193], v225 offset:3072
	ds_read_b128 v[170:173], v225 offset:4096
	ds_read_b128 v[186:189], v225 offset:5120
	ds_read_b128 v[166:169], v225 offset:6144
	ds_read_b128 v[182:185], v225 offset:7168
	global_load_lds_dwordx4 v210, s[34:35]
	s_add_i32 m0, s31, 0xe000
	s_nop 0
	global_load_lds_dwordx4 v212, s[34:35]
	s_waitcnt vmcnt(8)
	s_waitcnt lgkmcnt(0)
	s_setprio 1
	s_barrier
	v_mfma_f32_16x16x32_bf16 v[130:133], v[150:153], v[178:181], v[130:133]
	v_mfma_f32_16x16x32_bf16 v[126:129], v[158:161], v[178:181], v[126:129]
	v_mfma_f32_16x16x32_bf16 v[114:117], v[150:153], v[174:177], v[114:117]
	v_mfma_f32_16x16x32_bf16 v[110:113], v[158:161], v[174:177], v[110:113]
	v_mfma_f32_16x16x32_bf16 v[98:101], v[150:153], v[170:173], v[98:101]
	v_mfma_f32_16x16x32_bf16 v[94:97], v[158:161], v[170:173], v[94:97]
	v_mfma_f32_16x16x32_bf16 v[82:85], v[150:153], v[166:169], v[82:85]
	v_mfma_f32_16x16x32_bf16 v[78:81], v[158:161], v[166:169], v[78:81]
	v_mfma_f32_16x16x32_bf16 v[130:133], v[154:157], v[194:197], v[130:133]
	v_mfma_f32_16x16x32_bf16 v[126:129], v[162:165], v[194:197], v[126:129]
	v_mfma_f32_16x16x32_bf16 v[114:117], v[154:157], v[190:193], v[114:117]
	v_mfma_f32_16x16x32_bf16 v[110:113], v[162:165], v[190:193], v[110:113]
	v_mfma_f32_16x16x32_bf16 v[98:101], v[154:157], v[186:189], v[98:101]
	v_mfma_f32_16x16x32_bf16 v[94:97], v[162:165], v[186:189], v[94:97]
	v_mfma_f32_16x16x32_bf16 v[82:85], v[154:157], v[182:185], v[82:85]
	v_mfma_f32_16x16x32_bf16 v[78:81], v[162:165], v[182:185], v[78:81]
	v_mfma_f32_16x16x32_bf16 v[122:125], v[134:137], v[178:181], v[122:125]
	v_mfma_f32_16x16x32_bf16 v[118:121], v[142:145], v[178:181], v[118:121]
	v_mfma_f32_16x16x32_bf16 v[106:109], v[134:137], v[174:177], v[106:109]
	v_mfma_f32_16x16x32_bf16 v[102:105], v[142:145], v[174:177], v[102:105]
	v_mfma_f32_16x16x32_bf16 v[90:93], v[134:137], v[170:173], v[90:93]
	v_mfma_f32_16x16x32_bf16 v[86:89], v[142:145], v[170:173], v[86:89]
	v_mfma_f32_16x16x32_bf16 v[74:77], v[134:137], v[166:169], v[74:77]
	v_mfma_f32_16x16x32_bf16 v[70:73], v[142:145], v[166:169], v[70:73]
	v_mfma_f32_16x16x32_bf16 v[122:125], v[138:141], v[194:197], v[122:125]
	v_mfma_f32_16x16x32_bf16 v[118:121], v[146:149], v[194:197], v[118:121]
	v_mfma_f32_16x16x32_bf16 v[106:109], v[138:141], v[190:193], v[106:109]
	v_mfma_f32_16x16x32_bf16 v[102:105], v[146:149], v[190:193], v[102:105]
	v_mfma_f32_16x16x32_bf16 v[90:93], v[138:141], v[186:189], v[90:93]
	v_mfma_f32_16x16x32_bf16 v[86:89], v[146:149], v[186:189], v[86:89]
	v_mfma_f32_16x16x32_bf16 v[74:77], v[138:141], v[182:185], v[74:77]
	v_mfma_f32_16x16x32_bf16 v[70:73], v[146:149], v[182:185], v[70:73]
	s_barrier
	s_setprio 0
	v_cmp_ne_u32_e64 s[0:1], 1, v215
	s_andn2_b64 vcc, exec, s[2:3]
	s_cbranch_vccnz .LBB0_505
	ds_read_b128 v[178:181], v225 offset:16384
	ds_read_b128 v[194:197], v225 offset:17408
	ds_read_b128 v[174:177], v225 offset:18432
	ds_read_b128 v[190:193], v225 offset:19456
	ds_read_b128 v[170:173], v225 offset:20480
	ds_read_b128 v[186:189], v225 offset:21504
	ds_read_b128 v[166:169], v225 offset:22528
	ds_read_b128 v[182:185], v225 offset:23552

; #define PG8_STAGE(bufoff, gbase, voff) do { _Pragma("unroll") for (int _i = 0; _i < 2; ++_i) \
;         __builtin_amdgcn_global_load_lds((const unsigned*)((const char*)(gbase) + (voff)[_i]), (PG8_LAS unsigned*)(lds + (bufoff) + ldsw + _i * 8192), 16, 0, 0); } while (0)
; #define PG8_LDA(dst, b, h) do { _Pragma("unroll") for (int m = 0; m < 4; ++m) _Pragma("unroll") for (int k = 0; k < 2; ++k) dst[m][k] = *(const PG8_LAS bf16x8*)(lds + PG8_SA(b, h) + aoff + m * 2048 + k * 1024); } while (0)
; #define PG8_LDB(dst, b, h) do { _Pragma("unroll") for (int n = 0; n < 2; ++n) _Pragma("unroll") for (int k = 0; k < 2; ++k) dst[n][k] = *(const PG8_LAS bf16x8*)(lds + PG8_SB(b, h) + boff + n * 2048 + k * 1024); } while (0)
; #define PG8_MMA(ai, bj, At, Bt) do { __builtin_amdgcn_s_setprio(1); _Pragma("unroll") for (int m = 0; m < 4; ++m) _Pragma("unroll") for (int n = 0; n < 2; ++n) _Pragma("unroll") for (int k = 0; k < 2; ++k) \
;         acc[ai][bj][m][n] = __builtin_amdgcn_mfma_f32_16x16x32_bf16(Bt[n][k], At[m][k], acc[ai][bj][m][n], 0, 0, 0); __builtin_amdgcn_s_setprio(0); } while (0)
; #define PG8_WAIT_V(n) asm volatile("s_waitcnt vmcnt(" #n ")" ::: "memory")
; #define PG8_WAIT_L(n) asm volatile("s_waitcnt lgkmcnt(" #n ")" ::: "memory")
; #define PG8_BAR __builtin_amdgcn_s_barrier()
; #define PG8_SCHED __builtin_amdgcn_sched_barrier(0)
; template <class Epi, class Sched, bool ALIGN_EPI = false, bool SP2 = true>
; __device__ __forceinline__ void gemm_phase(PG8_LAS unsigned char* lds, const Gemm g, const Sched& S, const Epi& E) {
;     ...
;             PG8_LDB(B0, 1, 0); PG8_LDB(B1, 1, 1); PG8_SCHED; PG8_LDA(At, 1, 0); PG8_STAGE(PG8_SA(0, 1), a2 + hstep, voffA);
;             PG8_WAIT_V(8); PG8_WAIT_L(0); PG8_BAR; PG8_MMA(0, 0, At, B0); PG8_MMA(0, 1, At, B1); PG8_BAR; PG8_SCHED;
;             if (full) { PG8_LDA(At, 1, 1); } PG8_STAGE(PG8_SB(1, 0), b3, voffB); PG8_STAGE(PG8_SB(1, 1), b3 + hstep, voffB); PG8_STAGE(PG8_SA(1, 0), a3, voffA);
;             PG8_WAIT_V(8); PG8_WAIT_L(0); PG8_BAR; if (full) { PG8_MMA(1, 0, At, B0); PG8_MMA(1, 1, At, B1); } PG8_BAR; PG8_SCHED;
.LBB0_507:
	s_barrier
	s_setprio 0
	ds_read_b128 v[150:153], v209 offset:32768
	ds_read_b128 v[154:157], v209 offset:33792
	ds_read_b128 v[158:161], v209 offset:34816
	ds_read_b128 v[162:165], v209 offset:35840
	ds_read_b128 v[134:137], v224 offset:32768
	ds_read_b128 v[138:141], v224 offset:33792
	ds_read_b128 v[142:145], v224 offset:34816
	ds_read_b128 v[146:149], v224 offset:35840
	s_add_u32 s38, s38, 0x100000
	s_addc_u32 s39, s39, 0
	s_mov_b32 m0, s52
	s_waitcnt lgkmcnt(7)
	ds_read_b128 v[178:181], v225 offset:32768
	ds_read_b128 v[194:197], v225 offset:33792
	ds_read_b128 v[174:177], v225 offset:34816
	ds_read_b128 v[190:193], v225 offset:35840
	ds_read_b128 v[170:173], v225 offset:36864
	ds_read_b128 v[186:189], v225 offset:37888
	ds_read_b128 v[166:169], v225 offset:38912
	ds_read_b128 v[182:185], v225 offset:39936
	global_load_lds_dwordx4 v200, s[38:39]
	s_mov_b32 m0, s53
	s_nop 0
	global_load_lds_dwordx4 v204, s[38:39]
	s_waitcnt vmcnt(8)
	s_waitcnt lgkmcnt(0)
	s_setprio 1
	s_barrier
	v_mfma_f32_16x16x32_bf16 v[130:133], v[150:153], v[178:181], v[130:133]
	v_mfma_f32_16x16x32_bf16 v[126:129], v[158:161], v[178:181], v[126:129]
	v_mfma_f32_16x16x32_bf16 v[114:117], v[150:153], v[174:177], v[114:117]
	v_mfma_f32_16x16x32_bf16 v[110:113], v[158:161], v[174:177], v[110:113]
	v_mfma_f32_16x16x32_bf16 v[98:101], v[150:153], v[170:173], v[98:101]
	v_mfma_f32_16x16x32_bf16 v[94:97], v[158:161], v[170:173], v[94:97]
	v_mfma_f32_16x16x32_bf16 v[82:85], v[150:153], v[166:169], v[82:85]
	v_mfma_f32_16x16x32_bf16 v[78:81], v[158:161], v[166:169], v[78:81]
	v_mfma_f32_16x16x32_bf16 v[130:133], v[154:157], v[194:197], v[130:133]
	v_mfma_f32_16x16x32_bf16 v[126:129], v[162:165], v[194:197], v[126:129]
	v_mfma_f32_16x16x32_bf16 v[114:117], v[154:157], v[190:193], v[114:117]
	v_mfma_f32_16x16x32_bf16 v[110:113], v[162:165], v[190:193], v[110:113]
	v_mfma_f32_16x16x32_bf16 v[98:101], v[154:157], v[186:189], v[98:101]
	v_mfma_f32_16x16x32_bf16 v[94:97], v[162:165], v[186:189], v[94:97]
	v_mfma_f32_16x16x32_bf16 v[82:85], v[154:157], v[182:185], v[82:85]
	v_mfma_f32_16x16x32_bf16 v[78:81], v[162:165], v[182:185], v[78:81]
	v_mfma_f32_16x16x32_bf16 v[122:125], v[134:137], v[178:181], v[122:125]
	v_mfma_f32_16x16x32_bf16 v[118:121], v[142:145], v[178:181], v[118:121]
	v_mfma_f32_16x16x32_bf16 v[106:109], v[134:137], v[174:177], v[106:109]
	v_mfma_f32_16x16x32_bf16 v[102:105], v[142:145], v[174:177], v[102:105]
	v_mfma_f32_16x16x32_bf16 v[90:93], v[134:137], v[170:173], v[90:93]
	v_mfma_f32_16x16x32_bf16 v[86:89], v[142:145], v[170:173], v[86:89]
	v_mfma_f32_16x16x32_bf16 v[74:77], v[134:137], v[166:169], v[74:77]
	v_mfma_f32_16x16x32_bf16 v[70:73], v[142:145], v[166:169], v[70:73]
	v_mfma_f32_16x16x32_bf16 v[122:125], v[138:141], v[194:197], v[122:125]
	v_mfma_f32_16x16x32_bf16 v[118:121], v[146:149], v[194:197], v[118:121]
	v_mfma_f32_16x16x32_bf16 v[106:109], v[138:141], v[190:193], v[106:109]
	v_mfma_f32_16x16x32_bf16 v[102:105], v[146:149], v[190:193], v[102:105]
	v_mfma_f32_16x16x32_bf16 v[90:93], v[138:141], v[186:189], v[90:93]
	v_mfma_f32_16x16x32_bf16 v[86:89], v[146:149], v[186:189], v[86:89]
	v_mfma_f32_16x16x32_bf16 v[74:77], v[138:141], v[182:185], v[74:77]
	v_mfma_f32_16x16x32_bf16 v[70:73], v[146:149], v[182:185], v[70:73]
	s_barrier
	s_setprio 0
	s_and_b64 vcc, exec, s[0:1]
	s_cbranch_vccnz .LBB0_509
	ds_read_b128 v[178:181], v225 offset:49152
	ds_read_b128 v[194:197], v225 offset:50176
	ds_read_b128 v[174:177], v225 offset:51200
	ds_read_b128 v[190:193], v225 offset:52224
	ds_read_b128 v[170:173], v225 offset:53248
	ds_read_b128 v[186:189], v225 offset:54272
	ds_read_b128 v[166:169], v225 offset:55296
	ds_read_b128 v[182:185], v225 offset:56320

; #define PG8_STAGE(bufoff, gbase, voff) do { _Pragma("unroll") for (int _i = 0; _i < 2; ++_i) \
;         __builtin_amdgcn_global_load_lds((const unsigned*)((const char*)(gbase) + (voff)[_i]), (PG8_LAS unsigned*)(lds + (bufoff) + ldsw + _i * 8192), 16, 0, 0); } while (0)
; #define PG8_LDA(dst, b, h) do { _Pragma("unroll") for (int m = 0; m < 4; ++m) _Pragma("unroll") for (int k = 0; k < 2; ++k) dst[m][k] = *(const PG8_LAS bf16x8*)(lds + PG8_SA(b, h) + aoff + m * 2048 + k * 1024); } while (0)
; #define PG8_LDB(dst, b, h) do { _Pragma("unroll") for (int n = 0; n < 2; ++n) _Pragma("unroll") for (int k = 0; k < 2; ++k) dst[n][k] = *(const PG8_LAS bf16x8*)(lds + PG8_SB(b, h) + boff + n * 2048 + k * 1024); } while (0)
; #define PG8_MMA(ai, bj, At, Bt) do { __builtin_amdgcn_s_setprio(1); _Pragma("unroll") for (int m = 0; m < 4; ++m) _Pragma("unroll") for (int n = 0; n < 2; ++n) _Pragma("unroll") for (int k = 0; k < 2; ++k) \
;         acc[ai][bj][m][n] = __builtin_amdgcn_mfma_f32_16x16x32_bf16(Bt[n][k], At[m][k], acc[ai][bj][m][n], 0, 0, 0); __builtin_amdgcn_s_setprio(0); } while (0)
; #define PG8_WAIT_V(n) asm volatile("s_waitcnt vmcnt(" #n ")" ::: "memory")
; #define PG8_WAIT_L(n) asm volatile("s_waitcnt lgkmcnt(" #n ")" ::: "memory")
; #define PG8_BAR __builtin_amdgcn_s_barrier()
; #define PG8_SCHED __builtin_amdgcn_sched_barrier(0)
; template <class Epi, class Sched, bool ALIGN_EPI = false, bool SP2 = true>
; __device__ __forceinline__ void gemm_phase(PG8_LAS unsigned char* lds, const Gemm g, const Sched& S, const Epi& E) {
;     ...
;             PG8_LDB(B0, 0, 0); PG8_LDB(B1, 0, 1); PG8_SCHED; PG8_LDA(At, 0, 0); PG8_STAGE(PG8_SA(1, 1), a1 + hstep, voffA);
;             PG8_WAIT_V(8); PG8_WAIT_L(0); PG8_BAR; PG8_MMA(0, 0, At, B0); PG8_MMA(0, 1, At, B1); PG8_BAR; PG8_SCHED;
;             if (full) { PG8_LDA(At, 0, 1); } PG8_STAGE(PG8_SB(0, 0), b2, voffB); PG8_STAGE(PG8_SB(0, 1), b2 + hstep, voffB); PG8_STAGE(PG8_SA(0, 0), a2, voffA);
;             PG8_WAIT_V(8); PG8_WAIT_L(0); PG8_BAR; if (full) { PG8_MMA(1, 0, At, B0); PG8_MMA(1, 1, At, B1); } PG8_BAR; PG8_SCHED;
.LBB0_918:
	ds_read_b128 v[150:153], v209
	ds_read_b128 v[154:157], v209 offset:1024
	ds_read_b128 v[158:161], v209 offset:2048
	ds_read_b128 v[162:165], v209 offset:3072
	ds_read_b128 v[134:137], v224
	ds_read_b128 v[138:141], v224 offset:1024
	ds_read_b128 v[142:145], v224 offset:2048
	ds_read_b128 v[146:149], v224 offset:3072
	s_add_i32 m0, s31, 0xc000
	s_waitcnt lgkmcnt(7)
	ds_read_b128 v[178:181], v225
	ds_read_b128 v[194:197], v225 offset:1024
	ds_read_b128 v[174:177], v225 offset:2048
	ds_read_b128 v[190:193], v225 offset:3072
	ds_read_b128 v[170:173], v225 offset:4096
	ds_read_b128 v[186:189], v225 offset:5120
	ds_read_b128 v[166:169], v225 offset:6144
	ds_read_b128 v[182:185], v225 offset:7168
	global_load_lds_dwordx4 v212, s[2:3]
	s_add_i32 m0, s31, 0xe000
	s_nop 0
	global_load_lds_dwordx4 v214, s[2:3]
	s_waitcnt vmcnt(8)
	s_waitcnt lgkmcnt(0)
	s_setprio 1
	s_barrier
	v_mfma_f32_16x16x32_bf16 v[130:133], v[150:153], v[178:181], v[130:133]
	v_mfma_f32_16x16x32_bf16 v[126:129], v[158:161], v[178:181], v[126:129]
	v_mfma_f32_16x16x32_bf16 v[114:117], v[150:153], v[174:177], v[114:117]
	v_mfma_f32_16x16x32_bf16 v[110:113], v[158:161], v[174:177], v[110:113]
	v_mfma_f32_16x16x32_bf16 v[98:101], v[150:153], v[170:173], v[98:101]
	v_mfma_f32_16x16x32_bf16 v[94:97], v[158:161], v[170:173], v[94:97]
	v_mfma_f32_16x16x32_bf16 v[82:85], v[150:153], v[166:169], v[82:85]
	v_mfma_f32_16x16x32_bf16 v[78:81], v[158:161], v[166:169], v[78:81]
	v_mfma_f32_16x16x32_bf16 v[130:133], v[154:157], v[194:197], v[130:133]
	v_mfma_f32_16x16x32_bf16 v[126:129], v[162:165], v[194:197], v[126:129]
	v_mfma_f32_16x16x32_bf16 v[114:117], v[154:157], v[190:193], v[114:117]
	v_mfma_f32_16x16x32_bf16 v[110:113], v[162:165], v[190:193], v[110:113]
	v_mfma_f32_16x16x32_bf16 v[98:101], v[154:157], v[186:189], v[98:101]
	v_mfma_f32_16x16x32_bf16 v[94:97], v[162:165], v[186:189], v[94:97]
	v_mfma_f32_16x16x32_bf16 v[82:85], v[154:157], v[182:185], v[82:85]
	v_mfma_f32_16x16x32_bf16 v[78:81], v[162:165], v[182:185], v[78:81]
	v_mfma_f32_16x16x32_bf16 v[122:125], v[134:137], v[178:181], v[122:125]
	v_mfma_f32_16x16x32_bf16 v[118:121], v[142:145], v[178:181], v[118:121]
	v_mfma_f32_16x16x32_bf16 v[106:109], v[134:137], v[174:177], v[106:109]
	v_mfma_f32_16x16x32_bf16 v[102:105], v[142:145], v[174:177], v[102:105]
	v_mfma_f32_16x16x32_bf16 v[90:93], v[134:137], v[170:173], v[90:93]
	v_mfma_f32_16x16x32_bf16 v[86:89], v[142:145], v[170:173], v[86:89]
	v_mfma_f32_16x16x32_bf16 v[74:77], v[134:137], v[166:169], v[74:77]
	v_mfma_f32_16x16x32_bf16 v[70:73], v[142:145], v[166:169], v[70:73]
	v_mfma_f32_16x16x32_bf16 v[122:125], v[138:141], v[194:197], v[122:125]
	v_mfma_f32_16x16x32_bf16 v[118:121], v[146:149], v[194:197], v[118:121]
	v_mfma_f32_16x16x32_bf16 v[106:109], v[138:141], v[190:193], v[106:109]
	v_mfma_f32_16x16x32_bf16 v[102:105], v[146:149], v[190:193], v[102:105]
	v_mfma_f32_16x16x32_bf16 v[90:93], v[138:141], v[186:189], v[90:93]
	v_mfma_f32_16x16x32_bf16 v[86:89], v[146:149], v[186:189], v[86:89]
	v_mfma_f32_16x16x32_bf16 v[74:77], v[138:141], v[182:185], v[74:77]
	v_mfma_f32_16x16x32_bf16 v[70:73], v[146:149], v[182:185], v[70:73]
	s_barrier
	s_setprio 0
	v_cmp_ne_u32_e64 s[4:5], 1, v226
	s_andn2_b64 vcc, exec, s[36:37]
	s_cbranch_vccnz .LBB0_920
	ds_read_b128 v[178:181], v225 offset:16384
	ds_read_b128 v[194:197], v225 offset:17408
	ds_read_b128 v[174:177], v225 offset:18432
	ds_read_b128 v[190:193], v225 offset:19456
	ds_read_b128 v[170:173], v225 offset:20480
	ds_read_b128 v[186:189], v225 offset:21504
	ds_read_b128 v[166:169], v225 offset:22528
	ds_read_b128 v[182:185], v225 offset:23552

; #define PG8_STAGE(bufoff, gbase, voff) do { _Pragma("unroll") for (int _i = 0; _i < 2; ++_i) \
;         __builtin_amdgcn_global_load_lds((const unsigned*)((const char*)(gbase) + (voff)[_i]), (PG8_LAS unsigned*)(lds + (bufoff) + ldsw + _i * 8192), 16, 0, 0); } while (0)
; #define PG8_LDA(dst, b, h) do { _Pragma("unroll") for (int m = 0; m < 4; ++m) _Pragma("unroll") for (int k = 0; k < 2; ++k) dst[m][k] = *(const PG8_LAS bf16x8*)(lds + PG8_SA(b, h) + aoff + m * 2048 + k * 1024); } while (0)
; #define PG8_LDB(dst, b, h) do { _Pragma("unroll") for (int n = 0; n < 2; ++n) _Pragma("unroll") for (int k = 0; k < 2; ++k) dst[n][k] = *(const PG8_LAS bf16x8*)(lds + PG8_SB(b, h) + boff + n * 2048 + k * 1024); } while (0)
; #define PG8_MMA(ai, bj, At, Bt) do { __builtin_amdgcn_s_setprio(1); _Pragma("unroll") for (int m = 0; m < 4; ++m) _Pragma("unroll") for (int n = 0; n < 2; ++n) _Pragma("unroll") for (int k = 0; k < 2; ++k) \
;         acc[ai][bj][m][n] = __builtin_amdgcn_mfma_f32_16x16x32_bf16(Bt[n][k], At[m][k], acc[ai][bj][m][n], 0, 0, 0); __builtin_amdgcn_s_setprio(0); } while (0)
; #define PG8_WAIT_V(n) asm volatile("s_waitcnt vmcnt(" #n ")" ::: "memory")
; #define PG8_WAIT_L(n) asm volatile("s_waitcnt lgkmcnt(" #n ")" ::: "memory")
; #define PG8_BAR __builtin_amdgcn_s_barrier()
; #define PG8_SCHED __builtin_amdgcn_sched_barrier(0)
; template <class Epi, class Sched, bool ALIGN_EPI = false, bool SP2 = true>
; __device__ __forceinline__ void gemm_phase(PG8_LAS unsigned char* lds, const Gemm g, const Sched& S, const Epi& E) {
;     ...
;             PG8_LDB(B0, 1, 0); PG8_LDB(B1, 1, 1); PG8_SCHED; PG8_LDA(At, 1, 0); PG8_STAGE(PG8_SA(0, 1), a2 + hstep, voffA);
;             PG8_WAIT_V(8); PG8_WAIT_L(0); PG8_BAR; PG8_MMA(0, 0, At, B0); PG8_MMA(0, 1, At, B1); PG8_BAR; PG8_SCHED;
;             if (full) { PG8_LDA(At, 1, 1); } PG8_STAGE(PG8_SB(1, 0), b3, voffB); PG8_STAGE(PG8_SB(1, 1), b3 + hstep, voffB); PG8_STAGE(PG8_SA(1, 0), a3, voffA);
;             PG8_WAIT_V(8); PG8_WAIT_L(0); PG8_BAR; if (full) { PG8_MMA(1, 0, At, B0); PG8_MMA(1, 1, At, B1); } PG8_BAR; PG8_SCHED;
.LBB0_922:
	s_barrier
	s_setprio 0
	ds_read_b128 v[150:153], v209 offset:32768
	ds_read_b128 v[154:157], v209 offset:33792
	ds_read_b128 v[158:161], v209 offset:34816
	ds_read_b128 v[162:165], v209 offset:35840
	ds_read_b128 v[134:137], v224 offset:32768
	ds_read_b128 v[138:141], v224 offset:33792
	ds_read_b128 v[142:145], v224 offset:34816
	ds_read_b128 v[146:149], v224 offset:35840
	s_add_u32 s40, s40, 0x80000
	s_addc_u32 s41, s41, 0
	s_mov_b32 m0, s53
	s_waitcnt lgkmcnt(7)
	ds_read_b128 v[178:181], v225 offset:32768
	ds_read_b128 v[194:197], v225 offset:33792
	ds_read_b128 v[174:177], v225 offset:34816
	ds_read_b128 v[190:193], v225 offset:35840
	ds_read_b128 v[170:173], v225 offset:36864
	ds_read_b128 v[186:189], v225 offset:37888
	ds_read_b128 v[166:169], v225 offset:38912
	ds_read_b128 v[182:185], v225 offset:39936
	global_load_lds_dwordx4 v200, s[40:41]
	s_mov_b32 m0, s54
	s_nop 0
	global_load_lds_dwordx4 v204, s[40:41]
	s_waitcnt vmcnt(8)
	s_waitcnt lgkmcnt(0)
	s_setprio 1
	s_barrier
	v_mfma_f32_16x16x32_bf16 v[130:133], v[150:153], v[178:181], v[130:133]
	v_mfma_f32_16x16x32_bf16 v[126:129], v[158:161], v[178:181], v[126:129]
	v_mfma_f32_16x16x32_bf16 v[114:117], v[150:153], v[174:177], v[114:117]
	v_mfma_f32_16x16x32_bf16 v[110:113], v[158:161], v[174:177], v[110:113]
	v_mfma_f32_16x16x32_bf16 v[98:101], v[150:153], v[170:173], v[98:101]
	v_mfma_f32_16x16x32_bf16 v[94:97], v[158:161], v[170:173], v[94:97]
	v_mfma_f32_16x16x32_bf16 v[82:85], v[150:153], v[166:169], v[82:85]
	v_mfma_f32_16x16x32_bf16 v[78:81], v[158:161], v[166:169], v[78:81]
	v_mfma_f32_16x16x32_bf16 v[130:133], v[154:157], v[194:197], v[130:133]
	v_mfma_f32_16x16x32_bf16 v[126:129], v[162:165], v[194:197], v[126:129]
	v_mfma_f32_16x16x32_bf16 v[114:117], v[154:157], v[190:193], v[114:117]
	v_mfma_f32_16x16x32_bf16 v[110:113], v[162:165], v[190:193], v[110:113]
	v_mfma_f32_16x16x32_bf16 v[98:101], v[154:157], v[186:189], v[98:101]
	v_mfma_f32_16x16x32_bf16 v[94:97], v[162:165], v[186:189], v[94:97]
	v_mfma_f32_16x16x32_bf16 v[82:85], v[154:157], v[182:185], v[82:85]
	v_mfma_f32_16x16x32_bf16 v[78:81], v[162:165], v[182:185], v[78:81]
	v_mfma_f32_16x16x32_bf16 v[122:125], v[134:137], v[178:181], v[122:125]
	v_mfma_f32_16x16x32_bf16 v[118:121], v[142:145], v[178:181], v[118:121]
	v_mfma_f32_16x16x32_bf16 v[106:109], v[134:137], v[174:177], v[106:109]
	v_mfma_f32_16x16x32_bf16 v[102:105], v[142:145], v[174:177], v[102:105]
	v_mfma_f32_16x16x32_bf16 v[90:93], v[134:137], v[170:173], v[90:93]
	v_mfma_f32_16x16x32_bf16 v[86:89], v[142:145], v[170:173], v[86:89]
	v_mfma_f32_16x16x32_bf16 v[74:77], v[134:137], v[166:169], v[74:77]
	v_mfma_f32_16x16x32_bf16 v[70:73], v[142:145], v[166:169], v[70:73]
	v_mfma_f32_16x16x32_bf16 v[122:125], v[138:141], v[194:197], v[122:125]
	v_mfma_f32_16x16x32_bf16 v[118:121], v[146:149], v[194:197], v[118:121]
	v_mfma_f32_16x16x32_bf16 v[106:109], v[138:141], v[190:193], v[106:109]
	v_mfma_f32_16x16x32_bf16 v[102:105], v[146:149], v[190:193], v[102:105]
	v_mfma_f32_16x16x32_bf16 v[90:93], v[138:141], v[186:189], v[90:93]
	v_mfma_f32_16x16x32_bf16 v[86:89], v[146:149], v[186:189], v[86:89]
	v_mfma_f32_16x16x32_bf16 v[74:77], v[138:141], v[182:185], v[74:77]
	v_mfma_f32_16x16x32_bf16 v[70:73], v[146:149], v[182:185], v[70:73]
	s_barrier
	s_setprio 0
	s_and_b64 vcc, exec, s[4:5]
	s_cbranch_vccnz .LBB0_924
	ds_read_b128 v[178:181], v225 offset:49152
	ds_read_b128 v[194:197], v225 offset:50176
	ds_read_b128 v[174:177], v225 offset:51200
	ds_read_b128 v[190:193], v225 offset:52224
	ds_read_b128 v[170:173], v225 offset:53248
	ds_read_b128 v[186:189], v225 offset:54272
	ds_read_b128 v[166:169], v225 offset:55296
	ds_read_b128 v[182:185], v225 offset:56320

; #define PG8_STAGE(bufoff, gbase, voff) do { _Pragma("unroll") for (int _i = 0; _i < 2; ++_i) \
;         __builtin_amdgcn_global_load_lds((const unsigned*)((const char*)(gbase) + (voff)[_i]), (PG8_LAS unsigned*)(lds + (bufoff) + ldsw + _i * 8192), 16, 0, 0); } while (0)
; #define PG8_LDA(dst, b, h) do { _Pragma("unroll") for (int m = 0; m < 4; ++m) _Pragma("unroll") for (int k = 0; k < 2; ++k) dst[m][k] = *(const PG8_LAS bf16x8*)(lds + PG8_SA(b, h) + aoff + m * 2048 + k * 1024); } while (0)
; #define PG8_LDB(dst, b, h) do { _Pragma("unroll") for (int n = 0; n < 2; ++n) _Pragma("unroll") for (int k = 0; k < 2; ++k) dst[n][k] = *(const PG8_LAS bf16x8*)(lds + PG8_SB(b, h) + boff + n * 2048 + k * 1024); } while (0)
; #define PG8_MMA(ai, bj, At, Bt) do { __builtin_amdgcn_s_setprio(1); _Pragma("unroll") for (int m = 0; m < 4; ++m) _Pragma("unroll") for (int n = 0; n < 2; ++n) _Pragma("unroll") for (int k = 0; k < 2; ++k) \
;         acc[ai][bj][m][n] = __builtin_amdgcn_mfma_f32_16x16x32_bf16(Bt[n][k], At[m][k], acc[ai][bj][m][n], 0, 0, 0); __builtin_amdgcn_s_setprio(0); } while (0)
; #define PG8_WAIT_V(n) asm volatile("s_waitcnt vmcnt(" #n ")" ::: "memory")
; #define PG8_WAIT_L(n) asm volatile("s_waitcnt lgkmcnt(" #n ")" ::: "memory")
; #define PG8_BAR __builtin_amdgcn_s_barrier()
; #define PG8_SCHED __builtin_amdgcn_sched_barrier(0)
; template <class Epi, class Sched, bool ALIGN_EPI = false, bool SP2 = true>
; __device__ __forceinline__ void gemm_phase(PG8_LAS unsigned char* lds, const Gemm g, const Sched& S, const Epi& E) {
;     ...
;             PG8_LDB(B0, 0, 0); PG8_LDB(B1, 0, 1); PG8_SCHED; PG8_LDA(At, 0, 0); PG8_STAGE(PG8_SA(1, 1), a1 + hstep, voffA);
;             PG8_WAIT_V(8); PG8_WAIT_L(0); PG8_BAR; PG8_MMA(0, 0, At, B0); PG8_MMA(0, 1, At, B1); PG8_BAR; PG8_SCHED;
;             if (full) { PG8_LDA(At, 0, 1); } PG8_STAGE(PG8_SB(0, 0), b2, voffB); PG8_STAGE(PG8_SB(0, 1), b2 + hstep, voffB); PG8_STAGE(PG8_SA(0, 0), a2, voffA);
;             PG8_WAIT_V(8); PG8_WAIT_L(0); PG8_BAR; if (full) { PG8_MMA(1, 0, At, B0); PG8_MMA(1, 1, At, B1); } PG8_BAR; PG8_SCHED;
.LBB0_1023:
	ds_read_b128 v[150:153], v209
	ds_read_b128 v[154:157], v209 offset:1024
	ds_read_b128 v[158:161], v209 offset:2048
	ds_read_b128 v[162:165], v209 offset:3072
	ds_read_b128 v[134:137], v230
	ds_read_b128 v[138:141], v230 offset:1024
	ds_read_b128 v[142:145], v230 offset:2048
	ds_read_b128 v[146:149], v230 offset:3072
	s_add_i32 m0, s43, 0xc000
	s_waitcnt lgkmcnt(7)
	ds_read_b128 v[178:181], v231
	ds_read_b128 v[194:197], v231 offset:1024
	ds_read_b128 v[174:177], v231 offset:2048
	ds_read_b128 v[190:193], v231 offset:3072
	ds_read_b128 v[170:173], v231 offset:4096
	ds_read_b128 v[186:189], v231 offset:5120
	ds_read_b128 v[166:169], v231 offset:6144
	ds_read_b128 v[182:185], v231 offset:7168
	global_load_lds_dwordx4 v218, s[44:45]
	s_add_i32 m0, s43, 0xe000
	s_nop 0
	global_load_lds_dwordx4 v220, s[44:45]
	s_waitcnt vmcnt(8)
	s_waitcnt lgkmcnt(0)
	s_setprio 1
	s_barrier
	v_mfma_f32_16x16x32_bf16 v[130:133], v[150:153], v[178:181], v[130:133]
	v_mfma_f32_16x16x32_bf16 v[126:129], v[158:161], v[178:181], v[126:129]
	v_mfma_f32_16x16x32_bf16 v[114:117], v[150:153], v[174:177], v[114:117]
	v_mfma_f32_16x16x32_bf16 v[110:113], v[158:161], v[174:177], v[110:113]
	v_mfma_f32_16x16x32_bf16 v[98:101], v[150:153], v[170:173], v[98:101]
	v_mfma_f32_16x16x32_bf16 v[94:97], v[158:161], v[170:173], v[94:97]
	v_mfma_f32_16x16x32_bf16 v[82:85], v[150:153], v[166:169], v[82:85]
	v_mfma_f32_16x16x32_bf16 v[78:81], v[158:161], v[166:169], v[78:81]
	v_mfma_f32_16x16x32_bf16 v[130:133], v[154:157], v[194:197], v[130:133]
	v_mfma_f32_16x16x32_bf16 v[126:129], v[162:165], v[194:197], v[126:129]
	v_mfma_f32_16x16x32_bf16 v[114:117], v[154:157], v[190:193], v[114:117]
	v_mfma_f32_16x16x32_bf16 v[110:113], v[162:165], v[190:193], v[110:113]
	v_mfma_f32_16x16x32_bf16 v[98:101], v[154:157], v[186:189], v[98:101]
	v_mfma_f32_16x16x32_bf16 v[94:97], v[162:165], v[186:189], v[94:97]
	v_mfma_f32_16x16x32_bf16 v[82:85], v[154:157], v[182:185], v[82:85]
	v_mfma_f32_16x16x32_bf16 v[78:81], v[162:165], v[182:185], v[78:81]
	v_mfma_f32_16x16x32_bf16 v[122:125], v[134:137], v[178:181], v[122:125]
	v_mfma_f32_16x16x32_bf16 v[118:121], v[142:145], v[178:181], v[118:121]
	v_mfma_f32_16x16x32_bf16 v[106:109], v[134:137], v[174:177], v[106:109]
	v_mfma_f32_16x16x32_bf16 v[102:105], v[142:145], v[174:177], v[102:105]
	v_mfma_f32_16x16x32_bf16 v[90:93], v[134:137], v[170:173], v[90:93]
	v_mfma_f32_16x16x32_bf16 v[86:89], v[142:145], v[170:173], v[86:89]
	v_mfma_f32_16x16x32_bf16 v[74:77], v[134:137], v[166:169], v[74:77]
	v_mfma_f32_16x16x32_bf16 v[70:73], v[142:145], v[166:169], v[70:73]
	v_mfma_f32_16x16x32_bf16 v[122:125], v[138:141], v[194:197], v[122:125]
	v_mfma_f32_16x16x32_bf16 v[118:121], v[146:149], v[194:197], v[118:121]
	v_mfma_f32_16x16x32_bf16 v[106:109], v[138:141], v[190:193], v[106:109]
	v_mfma_f32_16x16x32_bf16 v[102:105], v[146:149], v[190:193], v[102:105]
	v_mfma_f32_16x16x32_bf16 v[90:93], v[138:141], v[186:189], v[90:93]
	v_mfma_f32_16x16x32_bf16 v[86:89], v[146:149], v[186:189], v[86:89]
	v_mfma_f32_16x16x32_bf16 v[74:77], v[138:141], v[182:185], v[74:77]
	v_mfma_f32_16x16x32_bf16 v[70:73], v[146:149], v[182:185], v[70:73]
	s_barrier
	s_setprio 0
	v_cmp_ne_u32_e64 s[4:5], 1, v232
	s_andn2_b64 vcc, exec, s[2:3]
	s_cbranch_vccnz .LBB0_1025
	ds_read_b128 v[178:181], v231 offset:16384
	ds_read_b128 v[194:197], v231 offset:17408
	ds_read_b128 v[174:177], v231 offset:18432
	ds_read_b128 v[190:193], v231 offset:19456
	ds_read_b128 v[170:173], v231 offset:20480
	ds_read_b128 v[186:189], v231 offset:21504
	ds_read_b128 v[166:169], v231 offset:22528
	ds_read_b128 v[182:185], v231 offset:23552

; #define PG8_STAGE(bufoff, gbase, voff) do { _Pragma("unroll") for (int _i = 0; _i < 2; ++_i) \
;         __builtin_amdgcn_global_load_lds((const unsigned*)((const char*)(gbase) + (voff)[_i]), (PG8_LAS unsigned*)(lds + (bufoff) + ldsw + _i * 8192), 16, 0, 0); } while (0)
; #define PG8_LDA(dst, b, h) do { _Pragma("unroll") for (int m = 0; m < 4; ++m) _Pragma("unroll") for (int k = 0; k < 2; ++k) dst[m][k] = *(const PG8_LAS bf16x8*)(lds + PG8_SA(b, h) + aoff + m * 2048 + k * 1024); } while (0)
; #define PG8_LDB(dst, b, h) do { _Pragma("unroll") for (int n = 0; n < 2; ++n) _Pragma("unroll") for (int k = 0; k < 2; ++k) dst[n][k] = *(const PG8_LAS bf16x8*)(lds + PG8_SB(b, h) + boff + n * 2048 + k * 1024); } while (0)
; #define PG8_MMA(ai, bj, At, Bt) do { __builtin_amdgcn_s_setprio(1); _Pragma("unroll") for (int m = 0; m < 4; ++m) _Pragma("unroll") for (int n = 0; n < 2; ++n) _Pragma("unroll") for (int k = 0; k < 2; ++k) \
;         acc[ai][bj][m][n] = __builtin_amdgcn_mfma_f32_16x16x32_bf16(Bt[n][k], At[m][k], acc[ai][bj][m][n], 0, 0, 0); __builtin_amdgcn_s_setprio(0); } while (0)
; #define PG8_WAIT_V(n) asm volatile("s_waitcnt vmcnt(" #n ")" ::: "memory")
; #define PG8_WAIT_L(n) asm volatile("s_waitcnt lgkmcnt(" #n ")" ::: "memory")
; #define PG8_BAR __builtin_amdgcn_s_barrier()
; #define PG8_SCHED __builtin_amdgcn_sched_barrier(0)
; template <class Epi, class Sched, bool ALIGN_EPI = false, bool SP2 = true>
; __device__ __forceinline__ void gemm_phase(PG8_LAS unsigned char* lds, const Gemm g, const Sched& S, const Epi& E) {
;     ...
;             PG8_LDB(B0, 1, 0); PG8_LDB(B1, 1, 1); PG8_SCHED; PG8_LDA(At, 1, 0); PG8_STAGE(PG8_SA(0, 1), a2 + hstep, voffA);
;             PG8_WAIT_V(8); PG8_WAIT_L(0); PG8_BAR; PG8_MMA(0, 0, At, B0); PG8_MMA(0, 1, At, B1); PG8_BAR; PG8_SCHED;
;             if (full) { PG8_LDA(At, 1, 1); } PG8_STAGE(PG8_SB(1, 0), b3, voffB); PG8_STAGE(PG8_SB(1, 1), b3 + hstep, voffB); PG8_STAGE(PG8_SA(1, 0), a3, voffA);
;             PG8_WAIT_V(8); PG8_WAIT_L(0); PG8_BAR; if (full) { PG8_MMA(1, 0, At, B0); PG8_MMA(1, 1, At, B1); } PG8_BAR; PG8_SCHED;
.LBB0_1027:
	s_barrier
	s_setprio 0
	ds_read_b128 v[150:153], v209 offset:32768
	ds_read_b128 v[154:157], v209 offset:33792
	ds_read_b128 v[158:161], v209 offset:34816
	ds_read_b128 v[162:165], v209 offset:35840
	ds_read_b128 v[134:137], v230 offset:32768
	ds_read_b128 v[138:141], v230 offset:33792
	ds_read_b128 v[142:145], v230 offset:34816
	ds_read_b128 v[146:149], v230 offset:35840
	s_add_u32 s48, s48, 0x80000
	s_addc_u32 s49, s49, 0
	s_mov_b32 m0, s62
	s_waitcnt lgkmcnt(7)
	ds_read_b128 v[178:181], v231 offset:32768
	ds_read_b128 v[194:197], v231 offset:33792
	ds_read_b128 v[174:177], v231 offset:34816
	ds_read_b128 v[190:193], v231 offset:35840
	ds_read_b128 v[170:173], v231 offset:36864
	ds_read_b128 v[186:189], v231 offset:37888
	ds_read_b128 v[166:169], v231 offset:38912
	ds_read_b128 v[182:185], v231 offset:39936
	global_load_lds_dwordx4 v200, s[48:49]
	s_mov_b32 m0, s63
	s_nop 0
	global_load_lds_dwordx4 v204, s[48:49]
	s_waitcnt vmcnt(8)
	s_waitcnt lgkmcnt(0)
	s_setprio 1
	s_barrier
	v_mfma_f32_16x16x32_bf16 v[130:133], v[150:153], v[178:181], v[130:133]
	v_mfma_f32_16x16x32_bf16 v[126:129], v[158:161], v[178:181], v[126:129]
	v_mfma_f32_16x16x32_bf16 v[114:117], v[150:153], v[174:177], v[114:117]
	v_mfma_f32_16x16x32_bf16 v[110:113], v[158:161], v[174:177], v[110:113]
	v_mfma_f32_16x16x32_bf16 v[98:101], v[150:153], v[170:173], v[98:101]
	v_mfma_f32_16x16x32_bf16 v[94:97], v[158:161], v[170:173], v[94:97]
	v_mfma_f32_16x16x32_bf16 v[82:85], v[150:153], v[166:169], v[82:85]
	v_mfma_f32_16x16x32_bf16 v[78:81], v[158:161], v[166:169], v[78:81]
	v_mfma_f32_16x16x32_bf16 v[130:133], v[154:157], v[194:197], v[130:133]
	v_mfma_f32_16x16x32_bf16 v[126:129], v[162:165], v[194:197], v[126:129]
	v_mfma_f32_16x16x32_bf16 v[114:117], v[154:157], v[190:193], v[114:117]
	v_mfma_f32_16x16x32_bf16 v[110:113], v[162:165], v[190:193], v[110:113]
	v_mfma_f32_16x16x32_bf16 v[98:101], v[154:157], v[186:189], v[98:101]
	v_mfma_f32_16x16x32_bf16 v[94:97], v[162:165], v[186:189], v[94:97]
	v_mfma_f32_16x16x32_bf16 v[82:85], v[154:157], v[182:185], v[82:85]
	v_mfma_f32_16x16x32_bf16 v[78:81], v[162:165], v[182:185], v[78:81]
	v_mfma_f32_16x16x32_bf16 v[122:125], v[134:137], v[178:181], v[122:125]
	v_mfma_f32_16x16x32_bf16 v[118:121], v[142:145], v[178:181], v[118:121]
	v_mfma_f32_16x16x32_bf16 v[106:109], v[134:137], v[174:177], v[106:109]
	v_mfma_f32_16x16x32_bf16 v[102:105], v[142:145], v[174:177], v[102:105]
	v_mfma_f32_16x16x32_bf16 v[90:93], v[134:137], v[170:173], v[90:93]
	v_mfma_f32_16x16x32_bf16 v[86:89], v[142:145], v[170:173], v[86:89]
	v_mfma_f32_16x16x32_bf16 v[74:77], v[134:137], v[166:169], v[74:77]
	v_mfma_f32_16x16x32_bf16 v[70:73], v[142:145], v[166:169], v[70:73]
	v_mfma_f32_16x16x32_bf16 v[122:125], v[138:141], v[194:197], v[122:125]
	v_mfma_f32_16x16x32_bf16 v[118:121], v[146:149], v[194:197], v[118:121]
	v_mfma_f32_16x16x32_bf16 v[106:109], v[138:141], v[190:193], v[106:109]
	v_mfma_f32_16x16x32_bf16 v[102:105], v[146:149], v[190:193], v[102:105]
	v_mfma_f32_16x16x32_bf16 v[90:93], v[138:141], v[186:189], v[90:93]
	v_mfma_f32_16x16x32_bf16 v[86:89], v[146:149], v[186:189], v[86:89]
	v_mfma_f32_16x16x32_bf16 v[74:77], v[138:141], v[182:185], v[74:77]
	v_mfma_f32_16x16x32_bf16 v[70:73], v[146:149], v[182:185], v[70:73]
	s_barrier
	s_setprio 0
	s_and_b64 vcc, exec, s[4:5]
	s_cbranch_vccnz .LBB0_1029
	ds_read_b128 v[178:181], v231 offset:49152
	ds_read_b128 v[194:197], v231 offset:50176
	ds_read_b128 v[174:177], v231 offset:51200
	ds_read_b128 v[190:193], v231 offset:52224
	ds_read_b128 v[170:173], v231 offset:53248
	ds_read_b128 v[186:189], v231 offset:54272
	ds_read_b128 v[166:169], v231 offset:55296
	ds_read_b128 v[182:185], v231 offset:56320

; #define PG8_STAGE(bufoff, gbase, voff) do { _Pragma("unroll") for (int _i = 0; _i < 2; ++_i) \
;         __builtin_amdgcn_global_load_lds((const unsigned*)((const char*)(gbase) + (voff)[_i]), (PG8_LAS unsigned*)(lds + (bufoff) + ldsw + _i * 8192), 16, 0, 0); } while (0)
; #define PG8_LDA(dst, b, h) do { _Pragma("unroll") for (int m = 0; m < 4; ++m) _Pragma("unroll") for (int k = 0; k < 2; ++k) dst[m][k] = *(const PG8_LAS bf16x8*)(lds + PG8_SA(b, h) + aoff + m * 2048 + k * 1024); } while (0)
; #define PG8_LDB(dst, b, h) do { _Pragma("unroll") for (int n = 0; n < 2; ++n) _Pragma("unroll") for (int k = 0; k < 2; ++k) dst[n][k] = *(const PG8_LAS bf16x8*)(lds + PG8_SB(b, h) + boff + n * 2048 + k * 1024); } while (0)
; #define PG8_MMA(ai, bj, At, Bt) do { __builtin_amdgcn_s_setprio(1); _Pragma("unroll") for (int m = 0; m < 4; ++m) _Pragma("unroll") for (int n = 0; n < 2; ++n) _Pragma("unroll") for (int k = 0; k < 2; ++k) \
;         acc[ai][bj][m][n] = __builtin_amdgcn_mfma_f32_16x16x32_bf16(Bt[n][k], At[m][k], acc[ai][bj][m][n], 0, 0, 0); __builtin_amdgcn_s_setprio(0); } while (0)
; #define PG8_WAIT_V(n) asm volatile("s_waitcnt vmcnt(" #n ")" ::: "memory")
; #define PG8_WAIT_L(n) asm volatile("s_waitcnt lgkmcnt(" #n ")" ::: "memory")
; #define PG8_BAR __builtin_amdgcn_s_barrier()
; #define PG8_SCHED __builtin_amdgcn_sched_barrier(0)
; template <class Epi, class Sched, bool ALIGN_EPI = false, bool SP2 = true>
; __device__ __forceinline__ void gemm_phase(PG8_LAS unsigned char* lds, const Gemm g, const Sched& S, const Epi& E) {
;     ...
;             PG8_LDB(B0, 0, 0); PG8_LDB(B1, 0, 1); PG8_SCHED; PG8_LDA(At, 0, 0); PG8_STAGE(PG8_SA(1, 1), a1 + hstep, voffA);
;             PG8_WAIT_V(8); PG8_WAIT_L(0); PG8_BAR; PG8_MMA(0, 0, At, B0); PG8_MMA(0, 1, At, B1); PG8_BAR; PG8_SCHED;
;             if (full) { PG8_LDA(At, 0, 1); } PG8_STAGE(PG8_SB(0, 0), b2, voffB); PG8_STAGE(PG8_SB(0, 1), b2 + hstep, voffB); PG8_STAGE(PG8_SA(0, 0), a2, voffA);
;             PG8_WAIT_V(8); PG8_WAIT_L(0); PG8_BAR; if (full) { PG8_MMA(1, 0, At, B0); PG8_MMA(1, 1, At, B1); } PG8_BAR; PG8_SCHED;
.LBB0_1161:
	ds_read_b128 v[150:153], v209
	ds_read_b128 v[154:157], v209 offset:1024
	ds_read_b128 v[158:161], v209 offset:2048
	ds_read_b128 v[162:165], v209 offset:3072
	ds_read_b128 v[134:137], v224
	ds_read_b128 v[138:141], v224 offset:1024
	ds_read_b128 v[142:145], v224 offset:2048
	ds_read_b128 v[146:149], v224 offset:3072
	s_add_i32 m0, s37, 0xc000
	s_waitcnt lgkmcnt(7)
	ds_read_b128 v[178:181], v225
	ds_read_b128 v[194:197], v225 offset:1024
	ds_read_b128 v[174:177], v225 offset:2048
	ds_read_b128 v[190:193], v225 offset:3072
	ds_read_b128 v[170:173], v225 offset:4096
	ds_read_b128 v[186:189], v225 offset:5120
	ds_read_b128 v[166:169], v225 offset:6144
	ds_read_b128 v[182:185], v225 offset:7168
	global_load_lds_dwordx4 v212, s[40:41]
	s_add_i32 m0, s37, 0xe000
	s_nop 0
	global_load_lds_dwordx4 v214, s[40:41]
	s_waitcnt vmcnt(8)
	s_waitcnt lgkmcnt(0)
	s_setprio 1
	s_barrier
	v_mfma_f32_16x16x32_bf16 v[130:133], v[150:153], v[178:181], v[130:133]
	v_mfma_f32_16x16x32_bf16 v[126:129], v[158:161], v[178:181], v[126:129]
	v_mfma_f32_16x16x32_bf16 v[114:117], v[150:153], v[174:177], v[114:117]
	v_mfma_f32_16x16x32_bf16 v[110:113], v[158:161], v[174:177], v[110:113]
	v_mfma_f32_16x16x32_bf16 v[98:101], v[150:153], v[170:173], v[98:101]
	v_mfma_f32_16x16x32_bf16 v[94:97], v[158:161], v[170:173], v[94:97]
	v_mfma_f32_16x16x32_bf16 v[82:85], v[150:153], v[166:169], v[82:85]
	v_mfma_f32_16x16x32_bf16 v[78:81], v[158:161], v[166:169], v[78:81]
	v_mfma_f32_16x16x32_bf16 v[130:133], v[154:157], v[194:197], v[130:133]
	v_mfma_f32_16x16x32_bf16 v[126:129], v[162:165], v[194:197], v[126:129]
	v_mfma_f32_16x16x32_bf16 v[114:117], v[154:157], v[190:193], v[114:117]
	v_mfma_f32_16x16x32_bf16 v[110:113], v[162:165], v[190:193], v[110:113]
	v_mfma_f32_16x16x32_bf16 v[98:101], v[154:157], v[186:189], v[98:101]
	v_mfma_f32_16x16x32_bf16 v[94:97], v[162:165], v[186:189], v[94:97]
	v_mfma_f32_16x16x32_bf16 v[82:85], v[154:157], v[182:185], v[82:85]
	v_mfma_f32_16x16x32_bf16 v[78:81], v[162:165], v[182:185], v[78:81]
	v_mfma_f32_16x16x32_bf16 v[122:125], v[134:137], v[178:181], v[122:125]
	v_mfma_f32_16x16x32_bf16 v[118:121], v[142:145], v[178:181], v[118:121]
	v_mfma_f32_16x16x32_bf16 v[106:109], v[134:137], v[174:177], v[106:109]
	v_mfma_f32_16x16x32_bf16 v[102:105], v[142:145], v[174:177], v[102:105]
	v_mfma_f32_16x16x32_bf16 v[90:93], v[134:137], v[170:173], v[90:93]
	v_mfma_f32_16x16x32_bf16 v[86:89], v[142:145], v[170:173], v[86:89]
	v_mfma_f32_16x16x32_bf16 v[74:77], v[134:137], v[166:169], v[74:77]
	v_mfma_f32_16x16x32_bf16 v[70:73], v[142:145], v[166:169], v[70:73]
	v_mfma_f32_16x16x32_bf16 v[122:125], v[138:141], v[194:197], v[122:125]
	v_mfma_f32_16x16x32_bf16 v[118:121], v[146:149], v[194:197], v[118:121]
	v_mfma_f32_16x16x32_bf16 v[106:109], v[138:141], v[190:193], v[106:109]
	v_mfma_f32_16x16x32_bf16 v[102:105], v[146:149], v[190:193], v[102:105]
	v_mfma_f32_16x16x32_bf16 v[90:93], v[138:141], v[186:189], v[90:93]
	v_mfma_f32_16x16x32_bf16 v[86:89], v[146:149], v[186:189], v[86:89]
	v_mfma_f32_16x16x32_bf16 v[74:77], v[138:141], v[182:185], v[74:77]
	v_mfma_f32_16x16x32_bf16 v[70:73], v[146:149], v[182:185], v[70:73]
	s_barrier
	s_setprio 0
	v_cmp_ne_u32_e64 s[8:9], 1, v226
	s_andn2_b64 vcc, exec, s[2:3]
	s_cbranch_vccnz .LBB0_1163
	ds_read_b128 v[178:181], v225 offset:16384
	ds_read_b128 v[194:197], v225 offset:17408
	ds_read_b128 v[174:177], v225 offset:18432
	ds_read_b128 v[190:193], v225 offset:19456
	ds_read_b128 v[170:173], v225 offset:20480
	ds_read_b128 v[186:189], v225 offset:21504
	ds_read_b128 v[166:169], v225 offset:22528
	ds_read_b128 v[182:185], v225 offset:23552

; #define PG8_STAGE(bufoff, gbase, voff) do { _Pragma("unroll") for (int _i = 0; _i < 2; ++_i) \
;         __builtin_amdgcn_global_load_lds((const unsigned*)((const char*)(gbase) + (voff)[_i]), (PG8_LAS unsigned*)(lds + (bufoff) + ldsw + _i * 8192), 16, 0, 0); } while (0)
; #define PG8_LDA(dst, b, h) do { _Pragma("unroll") for (int m = 0; m < 4; ++m) _Pragma("unroll") for (int k = 0; k < 2; ++k) dst[m][k] = *(const PG8_LAS bf16x8*)(lds + PG8_SA(b, h) + aoff + m * 2048 + k * 1024); } while (0)
; #define PG8_LDB(dst, b, h) do { _Pragma("unroll") for (int n = 0; n < 2; ++n) _Pragma("unroll") for (int k = 0; k < 2; ++k) dst[n][k] = *(const PG8_LAS bf16x8*)(lds + PG8_SB(b, h) + boff + n * 2048 + k * 1024); } while (0)
; #define PG8_MMA(ai, bj, At, Bt) do { __builtin_amdgcn_s_setprio(1); _Pragma("unroll") for (int m = 0; m < 4; ++m) _Pragma("unroll") for (int n = 0; n < 2; ++n) _Pragma("unroll") for (int k = 0; k < 2; ++k) \
;         acc[ai][bj][m][n] = __builtin_amdgcn_mfma_f32_16x16x32_bf16(Bt[n][k], At[m][k], acc[ai][bj][m][n], 0, 0, 0); __builtin_amdgcn_s_setprio(0); } while (0)
; #define PG8_WAIT_V(n) asm volatile("s_waitcnt vmcnt(" #n ")" ::: "memory")
; #define PG8_WAIT_L(n) asm volatile("s_waitcnt lgkmcnt(" #n ")" ::: "memory")
; #define PG8_BAR __builtin_amdgcn_s_barrier()
; #define PG8_SCHED __builtin_amdgcn_sched_barrier(0)
; template <class Epi, class Sched, bool ALIGN_EPI = false, bool SP2 = true>
; __device__ __forceinline__ void gemm_phase(PG8_LAS unsigned char* lds, const Gemm g, const Sched& S, const Epi& E) {
;     ...
;             PG8_LDB(B0, 1, 0); PG8_LDB(B1, 1, 1); PG8_SCHED; PG8_LDA(At, 1, 0); PG8_STAGE(PG8_SA(0, 1), a2 + hstep, voffA);
;             PG8_WAIT_V(8); PG8_WAIT_L(0); PG8_BAR; PG8_MMA(0, 0, At, B0); PG8_MMA(0, 1, At, B1); PG8_BAR; PG8_SCHED;
;             if (full) { PG8_LDA(At, 1, 1); } PG8_STAGE(PG8_SB(1, 0), b3, voffB); PG8_STAGE(PG8_SB(1, 1), b3 + hstep, voffB); PG8_STAGE(PG8_SA(1, 0), a3, voffA);
;             PG8_WAIT_V(8); PG8_WAIT_L(0); PG8_BAR; if (full) { PG8_MMA(1, 0, At, B0); PG8_MMA(1, 1, At, B1); } PG8_BAR; PG8_SCHED;
.LBB0_1165:
	s_barrier
	s_setprio 0
	ds_read_b128 v[150:153], v209 offset:32768
	ds_read_b128 v[154:157], v209 offset:33792
	ds_read_b128 v[158:161], v209 offset:34816
	ds_read_b128 v[162:165], v209 offset:35840
	ds_read_b128 v[134:137], v224 offset:32768
	ds_read_b128 v[138:141], v224 offset:33792
	ds_read_b128 v[142:145], v224 offset:34816
	ds_read_b128 v[146:149], v224 offset:35840
	s_add_u32 s44, s44, 0x100000
	s_addc_u32 s45, s45, 0
	s_mov_b32 m0, s55
	s_waitcnt lgkmcnt(7)
	ds_read_b128 v[178:181], v225 offset:32768
	ds_read_b128 v[194:197], v225 offset:33792
	ds_read_b128 v[174:177], v225 offset:34816
	ds_read_b128 v[190:193], v225 offset:35840
	ds_read_b128 v[170:173], v225 offset:36864
	ds_read_b128 v[186:189], v225 offset:37888
	ds_read_b128 v[166:169], v225 offset:38912
	ds_read_b128 v[182:185], v225 offset:39936
	global_load_lds_dwordx4 v200, s[44:45]
	s_mov_b32 m0, s56
	s_nop 0
	global_load_lds_dwordx4 v204, s[44:45]
	s_waitcnt vmcnt(8)
	s_waitcnt lgkmcnt(0)
	s_setprio 1
	s_barrier
	v_mfma_f32_16x16x32_bf16 v[130:133], v[150:153], v[178:181], v[130:133]
	v_mfma_f32_16x16x32_bf16 v[126:129], v[158:161], v[178:181], v[126:129]
	v_mfma_f32_16x16x32_bf16 v[114:117], v[150:153], v[174:177], v[114:117]
	v_mfma_f32_16x16x32_bf16 v[110:113], v[158:161], v[174:177], v[110:113]
	v_mfma_f32_16x16x32_bf16 v[98:101], v[150:153], v[170:173], v[98:101]
	v_mfma_f32_16x16x32_bf16 v[94:97], v[158:161], v[170:173], v[94:97]
	v_mfma_f32_16x16x32_bf16 v[82:85], v[150:153], v[166:169], v[82:85]
	v_mfma_f32_16x16x32_bf16 v[78:81], v[158:161], v[166:169], v[78:81]
	v_mfma_f32_16x16x32_bf16 v[130:133], v[154:157], v[194:197], v[130:133]
	v_mfma_f32_16x16x32_bf16 v[126:129], v[162:165], v[194:197], v[126:129]
	v_mfma_f32_16x16x32_bf16 v[114:117], v[154:157], v[190:193], v[114:117]
	v_mfma_f32_16x16x32_bf16 v[110:113], v[162:165], v[190:193], v[110:113]
	v_mfma_f32_16x16x32_bf16 v[98:101], v[154:157], v[186:189], v[98:101]
	v_mfma_f32_16x16x32_bf16 v[94:97], v[162:165], v[186:189], v[94:97]
	v_mfma_f32_16x16x32_bf16 v[82:85], v[154:157], v[182:185], v[82:85]
	v_mfma_f32_16x16x32_bf16 v[78:81], v[162:165], v[182:185], v[78:81]
	v_mfma_f32_16x16x32_bf16 v[122:125], v[134:137], v[178:181], v[122:125]
	v_mfma_f32_16x16x32_bf16 v[118:121], v[142:145], v[178:181], v[118:121]
	v_mfma_f32_16x16x32_bf16 v[106:109], v[134:137], v[174:177], v[106:109]
	v_mfma_f32_16x16x32_bf16 v[102:105], v[142:145], v[174:177], v[102:105]
	v_mfma_f32_16x16x32_bf16 v[90:93], v[134:137], v[170:173], v[90:93]
	v_mfma_f32_16x16x32_bf16 v[86:89], v[142:145], v[170:173], v[86:89]
	v_mfma_f32_16x16x32_bf16 v[74:77], v[134:137], v[166:169], v[74:77]
	v_mfma_f32_16x16x32_bf16 v[70:73], v[142:145], v[166:169], v[70:73]
	v_mfma_f32_16x16x32_bf16 v[122:125], v[138:141], v[194:197], v[122:125]
	v_mfma_f32_16x16x32_bf16 v[118:121], v[146:149], v[194:197], v[118:121]
	v_mfma_f32_16x16x32_bf16 v[106:109], v[138:141], v[190:193], v[106:109]
	v_mfma_f32_16x16x32_bf16 v[102:105], v[146:149], v[190:193], v[102:105]
	v_mfma_f32_16x16x32_bf16 v[90:93], v[138:141], v[186:189], v[90:93]
	v_mfma_f32_16x16x32_bf16 v[86:89], v[146:149], v[186:189], v[86:89]
	v_mfma_f32_16x16x32_bf16 v[74:77], v[138:141], v[182:185], v[74:77]
	v_mfma_f32_16x16x32_bf16 v[70:73], v[146:149], v[182:185], v[70:73]
	s_barrier
	s_setprio 0
	s_and_b64 vcc, exec, s[8:9]
	s_cbranch_vccnz .LBB0_1167
	ds_read_b128 v[178:181], v225 offset:49152
	ds_read_b128 v[194:197], v225 offset:50176
	ds_read_b128 v[174:177], v225 offset:51200
	ds_read_b128 v[190:193], v225 offset:52224
	ds_read_b128 v[170:173], v225 offset:53248
	ds_read_b128 v[186:189], v225 offset:54272
	ds_read_b128 v[166:169], v225 offset:55296
	ds_read_b128 v[182:185], v225 offset:56320

; #define PG8_STAGE(bufoff, gbase, voff) do { _Pragma("unroll") for (int _i = 0; _i < 2; ++_i) \
;         __builtin_amdgcn_global_load_lds((const unsigned*)((const char*)(gbase) + (voff)[_i]), (PG8_LAS unsigned*)(lds + (bufoff) + ldsw + _i * 8192), 16, 0, 0); } while (0)
; #define PG8_LDA(dst, b, h) do { _Pragma("unroll") for (int m = 0; m < 4; ++m) _Pragma("unroll") for (int k = 0; k < 2; ++k) dst[m][k] = *(const PG8_LAS bf16x8*)(lds + PG8_SA(b, h) + aoff + m * 2048 + k * 1024); } while (0)
; #define PG8_LDB(dst, b, h) do { _Pragma("unroll") for (int n = 0; n < 2; ++n) _Pragma("unroll") for (int k = 0; k < 2; ++k) dst[n][k] = *(const PG8_LAS bf16x8*)(lds + PG8_SB(b, h) + boff + n * 2048 + k * 1024); } while (0)
; #define PG8_MMA(ai, bj, At, Bt) do { __builtin_amdgcn_s_setprio(1); _Pragma("unroll") for (int m = 0; m < 4; ++m) _Pragma("unroll") for (int n = 0; n < 2; ++n) _Pragma("unroll") for (int k = 0; k < 2; ++k) \
;         acc[ai][bj][m][n] = __builtin_amdgcn_mfma_f32_16x16x32_bf16(Bt[n][k], At[m][k], acc[ai][bj][m][n], 0, 0, 0); __builtin_amdgcn_s_setprio(0); } while (0)
; #define PG8_WAIT_V(n) asm volatile("s_waitcnt vmcnt(" #n ")" ::: "memory")
; #define PG8_WAIT_L(n) asm volatile("s_waitcnt lgkmcnt(" #n ")" ::: "memory")
; #define PG8_BAR __builtin_amdgcn_s_barrier()
; #define PG8_SCHED __builtin_amdgcn_sched_barrier(0)
; template <class Epi, class Sched, bool ALIGN_EPI = false, bool SP2 = true>
; __device__ __forceinline__ void gemm_phase(PG8_LAS unsigned char* lds, const Gemm g, const Sched& S, const Epi& E) {
;     ...
;             PG8_LDB(B0, 0, 0); PG8_LDB(B1, 0, 1); PG8_SCHED; PG8_LDA(At, 0, 0); PG8_STAGE(PG8_SA(1, 1), a1 + hstep, voffA);
;             PG8_WAIT_V(8); PG8_WAIT_L(0); PG8_BAR; PG8_MMA(0, 0, At, B0); PG8_MMA(0, 1, At, B1); PG8_BAR; PG8_SCHED;
;             if (full) { PG8_LDA(At, 0, 1); } PG8_STAGE(PG8_SB(0, 0), b2, voffB); PG8_STAGE(PG8_SB(0, 1), b2 + hstep, voffB); PG8_STAGE(PG8_SA(0, 0), a2, voffA);
;             PG8_WAIT_V(8); PG8_WAIT_L(0); PG8_BAR; if (full) { PG8_MMA(1, 0, At, B0); PG8_MMA(1, 1, At, B1); } PG8_BAR; PG8_SCHED;
.LBB0_1321:
	ds_read_b128 v[150:153], v221
	ds_read_b128 v[154:157], v221 offset:1024
	ds_read_b128 v[158:161], v221 offset:2048
	ds_read_b128 v[162:165], v221 offset:3072
	ds_read_b128 v[134:137], v222
	ds_read_b128 v[138:141], v222 offset:1024
	ds_read_b128 v[142:145], v222 offset:2048
	ds_read_b128 v[146:149], v222 offset:3072
	s_add_i32 m0, s39, 0xc000
	s_waitcnt lgkmcnt(7)
	ds_read_b128 v[178:181], v223
	ds_read_b128 v[194:197], v223 offset:1024
	ds_read_b128 v[174:177], v223 offset:2048
	ds_read_b128 v[190:193], v223 offset:3072
	ds_read_b128 v[170:173], v223 offset:4096
	ds_read_b128 v[186:189], v223 offset:5120
	ds_read_b128 v[166:169], v223 offset:6144
	ds_read_b128 v[182:185], v223 offset:7168
	global_load_lds_dwordx4 v208, s[28:29]
	s_add_i32 m0, s39, 0xe000
	s_nop 0
	global_load_lds_dwordx4 v210, s[28:29]
	s_waitcnt vmcnt(8)
	s_waitcnt lgkmcnt(0)
	s_setprio 1
	s_barrier
	v_mfma_f32_16x16x32_bf16 v[130:133], v[150:153], v[178:181], v[130:133]
	v_mfma_f32_16x16x32_bf16 v[126:129], v[158:161], v[178:181], v[126:129]
	v_mfma_f32_16x16x32_bf16 v[114:117], v[150:153], v[174:177], v[114:117]
	v_mfma_f32_16x16x32_bf16 v[110:113], v[158:161], v[174:177], v[110:113]
	v_mfma_f32_16x16x32_bf16 v[98:101], v[150:153], v[170:173], v[98:101]
	v_mfma_f32_16x16x32_bf16 v[94:97], v[158:161], v[170:173], v[94:97]
	v_mfma_f32_16x16x32_bf16 v[82:85], v[150:153], v[166:169], v[82:85]
	v_mfma_f32_16x16x32_bf16 v[78:81], v[158:161], v[166:169], v[78:81]
	v_mfma_f32_16x16x32_bf16 v[130:133], v[154:157], v[194:197], v[130:133]
	v_mfma_f32_16x16x32_bf16 v[126:129], v[162:165], v[194:197], v[126:129]
	v_mfma_f32_16x16x32_bf16 v[114:117], v[154:157], v[190:193], v[114:117]
	v_mfma_f32_16x16x32_bf16 v[110:113], v[162:165], v[190:193], v[110:113]
	v_mfma_f32_16x16x32_bf16 v[98:101], v[154:157], v[186:189], v[98:101]
	v_mfma_f32_16x16x32_bf16 v[94:97], v[162:165], v[186:189], v[94:97]
	v_mfma_f32_16x16x32_bf16 v[82:85], v[154:157], v[182:185], v[82:85]
	v_mfma_f32_16x16x32_bf16 v[78:81], v[162:165], v[182:185], v[78:81]
	v_mfma_f32_16x16x32_bf16 v[122:125], v[134:137], v[178:181], v[122:125]
	v_mfma_f32_16x16x32_bf16 v[118:121], v[142:145], v[178:181], v[118:121]
	v_mfma_f32_16x16x32_bf16 v[106:109], v[134:137], v[174:177], v[106:109]
	v_mfma_f32_16x16x32_bf16 v[102:105], v[142:145], v[174:177], v[102:105]
	v_mfma_f32_16x16x32_bf16 v[90:93], v[134:137], v[170:173], v[90:93]
	v_mfma_f32_16x16x32_bf16 v[86:89], v[142:145], v[170:173], v[86:89]
	v_mfma_f32_16x16x32_bf16 v[74:77], v[134:137], v[166:169], v[74:77]
	v_mfma_f32_16x16x32_bf16 v[70:73], v[142:145], v[166:169], v[70:73]
	v_mfma_f32_16x16x32_bf16 v[122:125], v[138:141], v[194:197], v[122:125]
	v_mfma_f32_16x16x32_bf16 v[118:121], v[146:149], v[194:197], v[118:121]
	v_mfma_f32_16x16x32_bf16 v[106:109], v[138:141], v[190:193], v[106:109]
	v_mfma_f32_16x16x32_bf16 v[102:105], v[146:149], v[190:193], v[102:105]
	v_mfma_f32_16x16x32_bf16 v[90:93], v[138:141], v[186:189], v[90:93]
	v_mfma_f32_16x16x32_bf16 v[86:89], v[146:149], v[186:189], v[86:89]
	v_mfma_f32_16x16x32_bf16 v[74:77], v[138:141], v[182:185], v[74:77]
	v_mfma_f32_16x16x32_bf16 v[70:73], v[146:149], v[182:185], v[70:73]
	s_barrier
	s_setprio 0
	v_cmp_ne_u32_e64 s[4:5], 1, v224
	s_andn2_b64 vcc, exec, s[26:27]
	s_cbranch_vccnz .LBB0_1323
	ds_read_b128 v[178:181], v223 offset:16384
	ds_read_b128 v[194:197], v223 offset:17408
	ds_read_b128 v[174:177], v223 offset:18432
	ds_read_b128 v[190:193], v223 offset:19456
	ds_read_b128 v[170:173], v223 offset:20480
	ds_read_b128 v[186:189], v223 offset:21504
	ds_read_b128 v[166:169], v223 offset:22528
	ds_read_b128 v[182:185], v223 offset:23552

; #define PG8_STAGE(bufoff, gbase, voff) do { _Pragma("unroll") for (int _i = 0; _i < 2; ++_i) \
;         __builtin_amdgcn_global_load_lds((const unsigned*)((const char*)(gbase) + (voff)[_i]), (PG8_LAS unsigned*)(lds + (bufoff) + ldsw + _i * 8192), 16, 0, 0); } while (0)
; #define PG8_LDA(dst, b, h) do { _Pragma("unroll") for (int m = 0; m < 4; ++m) _Pragma("unroll") for (int k = 0; k < 2; ++k) dst[m][k] = *(const PG8_LAS bf16x8*)(lds + PG8_SA(b, h) + aoff + m * 2048 + k * 1024); } while (0)
; #define PG8_LDB(dst, b, h) do { _Pragma("unroll") for (int n = 0; n < 2; ++n) _Pragma("unroll") for (int k = 0; k < 2; ++k) dst[n][k] = *(const PG8_LAS bf16x8*)(lds + PG8_SB(b, h) + boff + n * 2048 + k * 1024); } while (0)
; #define PG8_MMA(ai, bj, At, Bt) do { __builtin_amdgcn_s_setprio(1); _Pragma("unroll") for (int m = 0; m < 4; ++m) _Pragma("unroll") for (int n = 0; n < 2; ++n) _Pragma("unroll") for (int k = 0; k < 2; ++k) \
;         acc[ai][bj][m][n] = __builtin_amdgcn_mfma_f32_16x16x32_bf16(Bt[n][k], At[m][k], acc[ai][bj][m][n], 0, 0, 0); __builtin_amdgcn_s_setprio(0); } while (0)
; #define PG8_WAIT_V(n) asm volatile("s_waitcnt vmcnt(" #n ")" ::: "memory")
; #define PG8_WAIT_L(n) asm volatile("s_waitcnt lgkmcnt(" #n ")" ::: "memory")
; #define PG8_BAR __builtin_amdgcn_s_barrier()
; #define PG8_SCHED __builtin_amdgcn_sched_barrier(0)
; template <class Epi, class Sched, bool ALIGN_EPI = false, bool SP2 = true>
; __device__ __forceinline__ void gemm_phase(PG8_LAS unsigned char* lds, const Gemm g, const Sched& S, const Epi& E) {
;     ...
;             PG8_LDB(B0, 1, 0); PG8_LDB(B1, 1, 1); PG8_SCHED; PG8_LDA(At, 1, 0); PG8_STAGE(PG8_SA(0, 1), a2 + hstep, voffA);
;             PG8_WAIT_V(8); PG8_WAIT_L(0); PG8_BAR; PG8_MMA(0, 0, At, B0); PG8_MMA(0, 1, At, B1); PG8_BAR; PG8_SCHED;
;             if (full) { PG8_LDA(At, 1, 1); } PG8_STAGE(PG8_SB(1, 0), b3, voffB); PG8_STAGE(PG8_SB(1, 1), b3 + hstep, voffB); PG8_STAGE(PG8_SA(1, 0), a3, voffA);
;             PG8_WAIT_V(8); PG8_WAIT_L(0); PG8_BAR; if (full) { PG8_MMA(1, 0, At, B0); PG8_MMA(1, 1, At, B1); } PG8_BAR; PG8_SCHED;
.LBB0_1325:
	s_barrier
	s_setprio 0
	ds_read_b128 v[150:153], v221 offset:32768
	ds_read_b128 v[154:157], v221 offset:33792
	ds_read_b128 v[158:161], v221 offset:34816
	ds_read_b128 v[162:165], v221 offset:35840
	ds_read_b128 v[134:137], v222 offset:32768
	ds_read_b128 v[138:141], v222 offset:33792
	ds_read_b128 v[142:145], v222 offset:34816
	ds_read_b128 v[146:149], v222 offset:35840
	s_add_u32 s34, s34, 0x100000
	s_addc_u32 s35, s35, 0
	s_mov_b32 m0, s45
	s_waitcnt lgkmcnt(7)
	ds_read_b128 v[178:181], v223 offset:32768
	ds_read_b128 v[194:197], v223 offset:33792
	ds_read_b128 v[174:177], v223 offset:34816
	ds_read_b128 v[190:193], v223 offset:35840
	ds_read_b128 v[170:173], v223 offset:36864
	ds_read_b128 v[186:189], v223 offset:37888
	ds_read_b128 v[166:169], v223 offset:38912
	ds_read_b128 v[182:185], v223 offset:39936
	global_load_lds_dwordx4 v200, s[34:35]
	s_mov_b32 m0, s46
	s_nop 0
	global_load_lds_dwordx4 v204, s[34:35]
	s_waitcnt vmcnt(8)
	s_waitcnt lgkmcnt(0)
	s_setprio 1
	s_barrier
	v_mfma_f32_16x16x32_bf16 v[130:133], v[150:153], v[178:181], v[130:133]
	v_mfma_f32_16x16x32_bf16 v[126:129], v[158:161], v[178:181], v[126:129]
	v_mfma_f32_16x16x32_bf16 v[114:117], v[150:153], v[174:177], v[114:117]
	v_mfma_f32_16x16x32_bf16 v[110:113], v[158:161], v[174:177], v[110:113]
	v_mfma_f32_16x16x32_bf16 v[98:101], v[150:153], v[170:173], v[98:101]
	v_mfma_f32_16x16x32_bf16 v[94:97], v[158:161], v[170:173], v[94:97]
	v_mfma_f32_16x16x32_bf16 v[82:85], v[150:153], v[166:169], v[82:85]
	v_mfma_f32_16x16x32_bf16 v[78:81], v[158:161], v[166:169], v[78:81]
	v_mfma_f32_16x16x32_bf16 v[130:133], v[154:157], v[194:197], v[130:133]
	v_mfma_f32_16x16x32_bf16 v[126:129], v[162:165], v[194:197], v[126:129]
	v_mfma_f32_16x16x32_bf16 v[114:117], v[154:157], v[190:193], v[114:117]
	v_mfma_f32_16x16x32_bf16 v[110:113], v[162:165], v[190:193], v[110:113]
	v_mfma_f32_16x16x32_bf16 v[98:101], v[154:157], v[186:189], v[98:101]
	v_mfma_f32_16x16x32_bf16 v[94:97], v[162:165], v[186:189], v[94:97]
	v_mfma_f32_16x16x32_bf16 v[82:85], v[154:157], v[182:185], v[82:85]
	v_mfma_f32_16x16x32_bf16 v[78:81], v[162:165], v[182:185], v[78:81]
	v_mfma_f32_16x16x32_bf16 v[122:125], v[134:137], v[178:181], v[122:125]
	v_mfma_f32_16x16x32_bf16 v[118:121], v[142:145], v[178:181], v[118:121]
	v_mfma_f32_16x16x32_bf16 v[106:109], v[134:137], v[174:177], v[106:109]
	v_mfma_f32_16x16x32_bf16 v[102:105], v[142:145], v[174:177], v[102:105]
	v_mfma_f32_16x16x32_bf16 v[90:93], v[134:137], v[170:173], v[90:93]
	v_mfma_f32_16x16x32_bf16 v[86:89], v[142:145], v[170:173], v[86:89]
	v_mfma_f32_16x16x32_bf16 v[74:77], v[134:137], v[166:169], v[74:77]
	v_mfma_f32_16x16x32_bf16 v[70:73], v[142:145], v[166:169], v[70:73]
	v_mfma_f32_16x16x32_bf16 v[122:125], v[138:141], v[194:197], v[122:125]
	v_mfma_f32_16x16x32_bf16 v[118:121], v[146:149], v[194:197], v[118:121]
	v_mfma_f32_16x16x32_bf16 v[106:109], v[138:141], v[190:193], v[106:109]
	v_mfma_f32_16x16x32_bf16 v[102:105], v[146:149], v[190:193], v[102:105]
	v_mfma_f32_16x16x32_bf16 v[90:93], v[138:141], v[186:189], v[90:93]
	v_mfma_f32_16x16x32_bf16 v[86:89], v[146:149], v[186:189], v[86:89]
	v_mfma_f32_16x16x32_bf16 v[74:77], v[138:141], v[182:185], v[74:77]
	v_mfma_f32_16x16x32_bf16 v[70:73], v[146:149], v[182:185], v[70:73]
	s_barrier
	s_setprio 0
	s_and_b64 vcc, exec, s[4:5]
	s_cbranch_vccnz .LBB0_1327
	ds_read_b128 v[178:181], v223 offset:49152
	ds_read_b128 v[194:197], v223 offset:50176
	ds_read_b128 v[174:177], v223 offset:51200
	ds_read_b128 v[190:193], v223 offset:52224
	ds_read_b128 v[170:173], v223 offset:53248
	ds_read_b128 v[186:189], v223 offset:54272
	ds_read_b128 v[166:169], v223 offset:55296
	ds_read_b128 v[182:185], v223 offset:56320

; #define PG8_STAGE(bufoff, gbase, voff) do { _Pragma("unroll") for (int _i = 0; _i < 2; ++_i) \
;         __builtin_amdgcn_global_load_lds((const unsigned*)((const char*)(gbase) + (voff)[_i]), (PG8_LAS unsigned*)(lds + (bufoff) + ldsw + _i * 8192), 16, 0, 0); } while (0)
; #define PG8_LDA(dst, b, h) do { _Pragma("unroll") for (int m = 0; m < 4; ++m) _Pragma("unroll") for (int k = 0; k < 2; ++k) dst[m][k] = *(const PG8_LAS bf16x8*)(lds + PG8_SA(b, h) + aoff + m * 2048 + k * 1024); } while (0)
; #define PG8_LDB(dst, b, h) do { _Pragma("unroll") for (int n = 0; n < 2; ++n) _Pragma("unroll") for (int k = 0; k < 2; ++k) dst[n][k] = *(const PG8_LAS bf16x8*)(lds + PG8_SB(b, h) + boff + n * 2048 + k * 1024); } while (0)
; #define PG8_MMA(ai, bj, At, Bt) do { __builtin_amdgcn_s_setprio(1); _Pragma("unroll") for (int m = 0; m < 4; ++m) _Pragma("unroll") for (int n = 0; n < 2; ++n) _Pragma("unroll") for (int k = 0; k < 2; ++k) \
;         acc[ai][bj][m][n] = __builtin_amdgcn_mfma_f32_16x16x32_bf16(Bt[n][k], At[m][k], acc[ai][bj][m][n], 0, 0, 0); __builtin_amdgcn_s_setprio(0); } while (0)
; #define PG8_WAIT_V(n) asm volatile("s_waitcnt vmcnt(" #n ")" ::: "memory")
; #define PG8_WAIT_L(n) asm volatile("s_waitcnt lgkmcnt(" #n ")" ::: "memory")
; #define PG8_BAR __builtin_amdgcn_s_barrier()
; #define PG8_SCHED __builtin_amdgcn_sched_barrier(0)
; template <class Epi, class Sched, bool ALIGN_EPI = false, bool SP2 = true>
; __device__ __forceinline__ void gemm_phase(PG8_LAS unsigned char* lds, const Gemm g, const Sched& S, const Epi& E) {
;     ...
;             PG8_LDB(B0, 0, 0); PG8_LDB(B1, 0, 1); PG8_SCHED; PG8_LDA(At, 0, 0); PG8_STAGE(PG8_SA(1, 1), a1 + hstep, voffA);
;             PG8_WAIT_V(8); PG8_WAIT_L(0); PG8_BAR; PG8_MMA(0, 0, At, B0); PG8_MMA(0, 1, At, B1); PG8_BAR; PG8_SCHED;
;             if (full) { PG8_LDA(At, 0, 1); } PG8_STAGE(PG8_SB(0, 0), b2, voffB); PG8_STAGE(PG8_SB(0, 1), b2 + hstep, voffB); PG8_STAGE(PG8_SA(0, 0), a2, voffA);
;             PG8_WAIT_V(8); PG8_WAIT_L(0); PG8_BAR; if (full) { PG8_MMA(1, 0, At, B0); PG8_MMA(1, 1, At, B1); } PG8_BAR; PG8_SCHED;
.LBB0_1427:
	ds_read_b128 v[150:153], v224
	ds_read_b128 v[154:157], v224 offset:1024
	ds_read_b128 v[158:161], v224 offset:2048
	ds_read_b128 v[162:165], v224 offset:3072
	ds_read_b128 v[134:137], v225
	ds_read_b128 v[138:141], v225 offset:1024
	ds_read_b128 v[142:145], v225 offset:2048
	ds_read_b128 v[146:149], v225 offset:3072
	s_add_i32 m0, s41, 0xc000
	s_waitcnt lgkmcnt(7)
	ds_read_b128 v[178:181], v226
	ds_read_b128 v[194:197], v226 offset:1024
	ds_read_b128 v[174:177], v226 offset:2048
	ds_read_b128 v[190:193], v226 offset:3072
	ds_read_b128 v[170:173], v226 offset:4096
	ds_read_b128 v[186:189], v226 offset:5120
	ds_read_b128 v[166:169], v226 offset:6144
	ds_read_b128 v[182:185], v226 offset:7168
	global_load_lds_dwordx4 v210, s[28:29]
	s_add_i32 m0, s41, 0xe000
	s_nop 0
	global_load_lds_dwordx4 v212, s[28:29]
	s_waitcnt vmcnt(8)
	s_waitcnt lgkmcnt(0)
	s_setprio 1
	s_barrier
	v_mfma_f32_16x16x32_bf16 v[66:69], v[150:153], v[178:181], v[66:69]
	v_mfma_f32_16x16x32_bf16 v[62:65], v[158:161], v[178:181], v[62:65]
	v_mfma_f32_16x16x32_bf16 v[50:53], v[150:153], v[174:177], v[50:53]
	v_mfma_f32_16x16x32_bf16 v[46:49], v[158:161], v[174:177], v[46:49]
	v_mfma_f32_16x16x32_bf16 v[34:37], v[150:153], v[170:173], v[34:37]
	v_mfma_f32_16x16x32_bf16 v[30:33], v[158:161], v[170:173], v[30:33]
	v_mfma_f32_16x16x32_bf16 v[18:21], v[150:153], v[166:169], v[18:21]
	v_mfma_f32_16x16x32_bf16 v[14:17], v[158:161], v[166:169], v[14:17]
	v_mfma_f32_16x16x32_bf16 v[66:69], v[154:157], v[194:197], v[66:69]
	v_mfma_f32_16x16x32_bf16 v[62:65], v[162:165], v[194:197], v[62:65]
	v_mfma_f32_16x16x32_bf16 v[50:53], v[154:157], v[190:193], v[50:53]
	v_mfma_f32_16x16x32_bf16 v[46:49], v[162:165], v[190:193], v[46:49]
	v_mfma_f32_16x16x32_bf16 v[34:37], v[154:157], v[186:189], v[34:37]
	v_mfma_f32_16x16x32_bf16 v[30:33], v[162:165], v[186:189], v[30:33]
	v_mfma_f32_16x16x32_bf16 v[18:21], v[154:157], v[182:185], v[18:21]
	v_mfma_f32_16x16x32_bf16 v[14:17], v[162:165], v[182:185], v[14:17]
	v_mfma_f32_16x16x32_bf16 v[58:61], v[134:137], v[178:181], v[58:61]
	v_mfma_f32_16x16x32_bf16 v[54:57], v[142:145], v[178:181], v[54:57]
	v_mfma_f32_16x16x32_bf16 v[42:45], v[134:137], v[174:177], v[42:45]
	v_mfma_f32_16x16x32_bf16 v[38:41], v[142:145], v[174:177], v[38:41]
	v_mfma_f32_16x16x32_bf16 v[26:29], v[134:137], v[170:173], v[26:29]
	v_mfma_f32_16x16x32_bf16 v[22:25], v[142:145], v[170:173], v[22:25]
	v_mfma_f32_16x16x32_bf16 v[10:13], v[134:137], v[166:169], v[10:13]
	v_mfma_f32_16x16x32_bf16 v[4:7], v[142:145], v[166:169], v[6:9]
	v_mfma_f32_16x16x32_bf16 v[58:61], v[138:141], v[194:197], v[58:61]
	v_mfma_f32_16x16x32_bf16 v[54:57], v[146:149], v[194:197], v[54:57]
	v_mfma_f32_16x16x32_bf16 v[42:45], v[138:141], v[190:193], v[42:45]
	v_mfma_f32_16x16x32_bf16 v[38:41], v[146:149], v[190:193], v[38:41]
	v_mfma_f32_16x16x32_bf16 v[26:29], v[138:141], v[186:189], v[26:29]
	v_mfma_f32_16x16x32_bf16 v[22:25], v[146:149], v[186:189], v[22:25]
	v_mfma_f32_16x16x32_bf16 v[10:13], v[138:141], v[182:185], v[10:13]
	v_mfma_f32_16x16x32_bf16 v[4:7], v[146:149], v[182:185], v[4:7]
	s_barrier
	s_setprio 0
	v_cmp_ne_u32_e64 s[8:9], 1, v227
	s_andn2_b64 vcc, exec, s[2:3]
	s_cbranch_vccnz .LBB0_1429
	ds_read_b128 v[178:181], v226 offset:16384
	ds_read_b128 v[194:197], v226 offset:17408
	ds_read_b128 v[174:177], v226 offset:18432
	ds_read_b128 v[190:193], v226 offset:19456
	ds_read_b128 v[170:173], v226 offset:20480
	ds_read_b128 v[186:189], v226 offset:21504
	ds_read_b128 v[166:169], v226 offset:22528
	ds_read_b128 v[182:185], v226 offset:23552

; #define PG8_STAGE(bufoff, gbase, voff) do { _Pragma("unroll") for (int _i = 0; _i < 2; ++_i) \
;         __builtin_amdgcn_global_load_lds((const unsigned*)((const char*)(gbase) + (voff)[_i]), (PG8_LAS unsigned*)(lds + (bufoff) + ldsw + _i * 8192), 16, 0, 0); } while (0)
; #define PG8_LDA(dst, b, h) do { _Pragma("unroll") for (int m = 0; m < 4; ++m) _Pragma("unroll") for (int k = 0; k < 2; ++k) dst[m][k] = *(const PG8_LAS bf16x8*)(lds + PG8_SA(b, h) + aoff + m * 2048 + k * 1024); } while (0)
; #define PG8_LDB(dst, b, h) do { _Pragma("unroll") for (int n = 0; n < 2; ++n) _Pragma("unroll") for (int k = 0; k < 2; ++k) dst[n][k] = *(const PG8_LAS bf16x8*)(lds + PG8_SB(b, h) + boff + n * 2048 + k * 1024); } while (0)
; #define PG8_MMA(ai, bj, At, Bt) do { __builtin_amdgcn_s_setprio(1); _Pragma("unroll") for (int m = 0; m < 4; ++m) _Pragma("unroll") for (int n = 0; n < 2; ++n) _Pragma("unroll") for (int k = 0; k < 2; ++k) \
;         acc[ai][bj][m][n] = __builtin_amdgcn_mfma_f32_16x16x32_bf16(Bt[n][k], At[m][k], acc[ai][bj][m][n], 0, 0, 0); __builtin_amdgcn_s_setprio(0); } while (0)
; #define PG8_WAIT_V(n) asm volatile("s_waitcnt vmcnt(" #n ")" ::: "memory")
; #define PG8_WAIT_L(n) asm volatile("s_waitcnt lgkmcnt(" #n ")" ::: "memory")
; #define PG8_BAR __builtin_amdgcn_s_barrier()
; #define PG8_SCHED __builtin_amdgcn_sched_barrier(0)
; template <class Epi, class Sched, bool ALIGN_EPI = false, bool SP2 = true>
; __device__ __forceinline__ void gemm_phase(PG8_LAS unsigned char* lds, const Gemm g, const Sched& S, const Epi& E) {
;     ...
;             PG8_LDB(B0, 1, 0); PG8_LDB(B1, 1, 1); PG8_SCHED; PG8_LDA(At, 1, 0); PG8_STAGE(PG8_SA(0, 1), a2 + hstep, voffA);
;             PG8_WAIT_V(8); PG8_WAIT_L(0); PG8_BAR; PG8_MMA(0, 0, At, B0); PG8_MMA(0, 1, At, B1); PG8_BAR; PG8_SCHED;
;             if (full) { PG8_LDA(At, 1, 1); } PG8_STAGE(PG8_SB(1, 0), b3, voffB); PG8_STAGE(PG8_SB(1, 1), b3 + hstep, voffB); PG8_STAGE(PG8_SA(1, 0), a3, voffA);
;             PG8_WAIT_V(8); PG8_WAIT_L(0); PG8_BAR; if (full) { PG8_MMA(1, 0, At, B0); PG8_MMA(1, 1, At, B1); } PG8_BAR; PG8_SCHED;
.LBB0_1431:
	s_barrier
	s_setprio 0
	ds_read_b128 v[150:153], v224 offset:32768
	ds_read_b128 v[154:157], v224 offset:33792
	ds_read_b128 v[158:161], v224 offset:34816
	ds_read_b128 v[162:165], v224 offset:35840
	ds_read_b128 v[134:137], v225 offset:32768
	ds_read_b128 v[138:141], v225 offset:33792
	ds_read_b128 v[142:145], v225 offset:34816
	ds_read_b128 v[146:149], v225 offset:35840
	s_add_u32 s34, s34, 0x2b0000
	s_addc_u32 s35, s35, 0
	s_mov_b32 m0, s47
	s_waitcnt lgkmcnt(7)
	ds_read_b128 v[178:181], v226 offset:32768
	ds_read_b128 v[194:197], v226 offset:33792
	ds_read_b128 v[174:177], v226 offset:34816
	ds_read_b128 v[190:193], v226 offset:35840
	ds_read_b128 v[170:173], v226 offset:36864
	ds_read_b128 v[186:189], v226 offset:37888
	ds_read_b128 v[166:169], v226 offset:38912
	ds_read_b128 v[182:185], v226 offset:39936
	global_load_lds_dwordx4 v200, s[34:35]
	s_mov_b32 m0, s48
	s_nop 0
	global_load_lds_dwordx4 v204, s[34:35]
	s_waitcnt vmcnt(8)
	s_waitcnt lgkmcnt(0)
	s_setprio 1
	s_barrier
	v_mfma_f32_16x16x32_bf16 v[66:69], v[150:153], v[178:181], v[66:69]
	v_mfma_f32_16x16x32_bf16 v[62:65], v[158:161], v[178:181], v[62:65]
	v_mfma_f32_16x16x32_bf16 v[50:53], v[150:153], v[174:177], v[50:53]
	v_mfma_f32_16x16x32_bf16 v[46:49], v[158:161], v[174:177], v[46:49]
	v_mfma_f32_16x16x32_bf16 v[34:37], v[150:153], v[170:173], v[34:37]
	v_mfma_f32_16x16x32_bf16 v[30:33], v[158:161], v[170:173], v[30:33]
	v_mfma_f32_16x16x32_bf16 v[18:21], v[150:153], v[166:169], v[18:21]
	v_mfma_f32_16x16x32_bf16 v[14:17], v[158:161], v[166:169], v[14:17]
	v_mfma_f32_16x16x32_bf16 v[66:69], v[154:157], v[194:197], v[66:69]
	v_mfma_f32_16x16x32_bf16 v[62:65], v[162:165], v[194:197], v[62:65]
	v_mfma_f32_16x16x32_bf16 v[50:53], v[154:157], v[190:193], v[50:53]
	v_mfma_f32_16x16x32_bf16 v[46:49], v[162:165], v[190:193], v[46:49]
	v_mfma_f32_16x16x32_bf16 v[34:37], v[154:157], v[186:189], v[34:37]
	v_mfma_f32_16x16x32_bf16 v[30:33], v[162:165], v[186:189], v[30:33]
	v_mfma_f32_16x16x32_bf16 v[18:21], v[154:157], v[182:185], v[18:21]
	v_mfma_f32_16x16x32_bf16 v[14:17], v[162:165], v[182:185], v[14:17]
	v_mfma_f32_16x16x32_bf16 v[58:61], v[134:137], v[178:181], v[58:61]
	v_mfma_f32_16x16x32_bf16 v[54:57], v[142:145], v[178:181], v[54:57]
	v_mfma_f32_16x16x32_bf16 v[42:45], v[134:137], v[174:177], v[42:45]
	v_mfma_f32_16x16x32_bf16 v[38:41], v[142:145], v[174:177], v[38:41]
	v_mfma_f32_16x16x32_bf16 v[26:29], v[134:137], v[170:173], v[26:29]
	v_mfma_f32_16x16x32_bf16 v[22:25], v[142:145], v[170:173], v[22:25]
	v_mfma_f32_16x16x32_bf16 v[8:11], v[134:137], v[166:169], v[10:13]
	v_mfma_f32_16x16x32_bf16 v[4:7], v[142:145], v[166:169], v[4:7]
	v_mfma_f32_16x16x32_bf16 v[58:61], v[138:141], v[194:197], v[58:61]
	v_mfma_f32_16x16x32_bf16 v[54:57], v[146:149], v[194:197], v[54:57]
	v_mfma_f32_16x16x32_bf16 v[42:45], v[138:141], v[190:193], v[42:45]
	v_mfma_f32_16x16x32_bf16 v[38:41], v[146:149], v[190:193], v[38:41]
	v_mfma_f32_16x16x32_bf16 v[26:29], v[138:141], v[186:189], v[26:29]
	v_mfma_f32_16x16x32_bf16 v[22:25], v[146:149], v[186:189], v[22:25]
	v_mfma_f32_16x16x32_bf16 v[10:13], v[138:141], v[182:185], v[8:11]
	v_mfma_f32_16x16x32_bf16 v[6:9], v[146:149], v[182:185], v[4:7]
	s_barrier
	s_setprio 0
	s_and_b64 vcc, exec, s[8:9]
	s_cbranch_vccnz .LBB0_1433
	ds_read_b128 v[178:181], v226 offset:49152
	ds_read_b128 v[194:197], v226 offset:50176
	ds_read_b128 v[174:177], v226 offset:51200
	ds_read_b128 v[190:193], v226 offset:52224
	ds_read_b128 v[170:173], v226 offset:53248
	ds_read_b128 v[186:189], v226 offset:54272
	ds_read_b128 v[166:169], v226 offset:55296
	ds_read_b128 v[182:185], v226 offset:56320

; __global__ void __launch_bounds__(NWAVES * 64, 2) mk_fwd(Args args) {
;     extern __shared__ __attribute__((aligned(16))) unsigned char lds[];
	.amdhsa_kernel _Z6mk_fwd4Args
		.amdhsa_group_segment_fixed_size 0
		.amdhsa_private_segment_fixed_size 0
		.amdhsa_kernarg_size 512
		.amdhsa_user_sgpr_count 2
		.amdhsa_user_sgpr_dispatch_ptr 0
		.amdhsa_user_sgpr_queue_ptr 0
		.amdhsa_user_sgpr_kernarg_segment_ptr 1
		.amdhsa_user_sgpr_dispatch_id 0
		.amdhsa_user_sgpr_kernarg_preload_length 0
		.amdhsa_user_sgpr_kernarg_preload_offset 0
		.amdhsa_user_sgpr_private_segment_size 0
		.amdhsa_uses_dynamic_stack 0
		.amdhsa_enable_private_segment 0
		.amdhsa_system_sgpr_workgroup_id_x 1
		.amdhsa_system_sgpr_workgroup_id_y 0
		.amdhsa_system_sgpr_workgroup_id_z 0
		.amdhsa_system_sgpr_workgroup_info 0
		.amdhsa_system_vgpr_workitem_id 0
		.amdhsa_next_free_vgpr 239
		.amdhsa_next_free_sgpr 102
		.amdhsa_accum_offset 240
		.amdhsa_reserve_vcc 1
		.amdhsa_float_round_mode_32 0
		.amdhsa_float_round_mode_16_64 0
		.amdhsa_float_denorm_mode_32 3
		.amdhsa_float_denorm_mode_16_64 3
		.amdhsa_dx10_clamp 1
		.amdhsa_ieee_mode 1
		.amdhsa_fp16_overflow 0
		.amdhsa_tg_split 0
		.amdhsa_exception_fp_ieee_invalid_op 0
		.amdhsa_exception_fp_denorm_src 0
		.amdhsa_exception_fp_ieee_div_zero 0
		.amdhsa_exception_fp_ieee_overflow 0
		.amdhsa_exception_fp_ieee_underflow 0
		.amdhsa_exception_fp_ieee_inexact 0
		.amdhsa_exception_int_div_zero 0
	.end_amdhsa_kernel

; __global__ void __launch_bounds__(NWAVES * 64, 2) mk_fwd(Args args) {
;     extern __shared__ __attribute__((aligned(16))) unsigned char lds[];
amdhsa.kernels:
  - .agpr_count:     0
    .args:
      - .offset:         0
        .size:           256
        .value_kind:     by_value
      - .offset:         256
        .size:           4
        .value_kind:     hidden_block_count_x
      - .offset:         260
        .size:           4
        .value_kind:     hidden_block_count_y
      - .offset:         264
        .size:           4
        .value_kind:     hidden_block_count_z
      - .offset:         268
        .size:           2
        .value_kind:     hidden_group_size_x
      - .offset:         270
        .size:           2
        .value_kind:     hidden_group_size_y
      - .offset:         272
        .size:           2
        .value_kind:     hidden_group_size_z
      - .offset:         274
        .size:           2
        .value_kind:     hidden_remainder_x
      - .offset:         276
        .size:           2
        .value_kind:     hidden_remainder_y
      - .offset:         278
        .size:           2
        .value_kind:     hidden_remainder_z
      - .offset:         296
        .size:           8
        .value_kind:     hidden_global_offset_x
      - .offset:         304
        .size:           8
        .value_kind:     hidden_global_offset_y
      - .offset:         312
        .size:           8
        .value_kind:     hidden_global_offset_z
      - .offset:         320
        .size:           2
        .value_kind:     hidden_grid_dims
      - .offset:         376
        .size:           4
        .value_kind:     hidden_dynamic_lds_size
    .group_segment_fixed_size: 0
    .kernarg_segment_align: 8
    .kernarg_segment_size: 512
    .language:       OpenCL C
    .language_version:
      - 2
      - 0
    .max_flat_workgroup_size: 512
    .name:           _Z6mk_fwd4Args
    .private_segment_fixed_size: 0
    .sgpr_count:     104
    .sgpr_spill_count: 86
    .symbol:         _Z6mk_fwd4Args.kd
    .uniform_work_group_size: 1
    .uses_dynamic_stack: false
    .vgpr_count:     239
    .vgpr_spill_count: 0
    .wavefront_size: 64
